# GEMM second-half LDS read rebalance: 4 fragment ds_reads moved ph5 to ph4 with vmcnt(10) at ph3, all 6 GEMM copies
# speedup vs baseline: 1.0023x; 1.0023x over previous
.LBB0_121:
	s_add_u32 s2, s10, 0x100
	s_addc_u32 s3, s11, 0
	s_add_i32 s34, 0, 0x10000
	s_cmp_eq_u32 s67, 40
	s_cselect_b32 s15, s5, s3
	s_cselect_b32 s14, s4, s2
	s_cselect_b32 s13, s53, s63
	s_cselect_b32 s12, s31, s55
	v_lshl_add_u64 v[190:191], s[10:11], 0, v[132:133]
	s_add_i32 m0, s22, 0xc000
	ds_read_b128 v[156:159], v138
	ds_read_b128 v[160:163], v138 offset:1024
	ds_read_b128 v[164:167], v138 offset:2048
	ds_read_b128 v[168:171], v138 offset:3072
	ds_read_b128 v[172:175], v138 offset:4096
	ds_read_b128 v[182:185], v138 offset:5120
	ds_read_b128 v[186:189], v138 offset:6144
	ds_read_b128 v[214:217], v138 offset:7168
	global_load_lds_dwordx4 v[190:191], off
	v_lshl_add_u64 v[190:191], s[10:11], 0, v[134:135]
	s_add_i32 m0, s22, 0xe000
	s_nop 0
	global_load_lds_dwordx4 v[190:191], off
	s_waitcnt lgkmcnt(8)
	s_barrier
	s_waitcnt lgkmcnt(0)
	s_waitcnt lgkmcnt(0)
	v_mfma_f32_16x16x32_bf16 v[20:23], v[140:143], v[156:159], v[20:23]
	v_mfma_f32_16x16x32_bf16 v[28:31], v[148:151], v[156:159], v[28:31]
	v_mfma_f32_16x16x32_bf16 v[12:15], v[140:143], v[164:167], v[12:15]
	v_mfma_f32_16x16x32_bf16 v[24:27], v[148:151], v[164:167], v[24:27]
	v_mfma_f32_16x16x32_bf16 v[4:7], v[140:143], v[172:175], v[4:7]
	v_mfma_f32_16x16x32_bf16 v[16:19], v[148:151], v[172:175], v[16:19]
	v_mfma_f32_16x16x32_bf16 v[0:3], v[140:143], v[186:189], v[0:3]
	v_mfma_f32_16x16x32_bf16 v[8:11], v[148:151], v[186:189], v[8:11]
	v_mfma_f32_16x16x32_bf16 v[20:23], v[144:147], v[160:163], v[20:23]
	v_mfma_f32_16x16x32_bf16 v[28:31], v[152:155], v[160:163], v[28:31]
	v_mfma_f32_16x16x32_bf16 v[12:15], v[144:147], v[168:171], v[12:15]
	v_mfma_f32_16x16x32_bf16 v[24:27], v[152:155], v[168:171], v[24:27]
	v_mfma_f32_16x16x32_bf16 v[4:7], v[144:147], v[182:185], v[4:7]
	v_mfma_f32_16x16x32_bf16 v[16:19], v[152:155], v[182:185], v[16:19]
	v_mfma_f32_16x16x32_bf16 v[0:3], v[144:147], v[214:217], v[0:3]
	v_mfma_f32_16x16x32_bf16 v[8:11], v[152:155], v[214:217], v[8:11]
	s_barrier
	s_add_i32 s35, 0, 0x14000
	s_add_i32 s10, s34, s58
	v_add_u32_e32 v139, s35, v137
	v_lshl_add_u64 v[190:191], s[12:13], 0, v[176:177]
	s_mov_b32 m0, s10
	ds_read_b128 v[218:221], v139
	ds_read_b128 v[222:225], v139 offset:1024
	ds_read_b128 v[226:229], v139 offset:2048
	ds_read_b128 v[230:233], v139 offset:3072
	global_load_lds_dwordx4 v[190:191], off
	v_lshl_add_u64 v[234:235], s[12:13], 0, v[128:129]
	s_add_i32 m0, s10, 0x2000
	s_nop 0
	global_load_lds_dwordx4 v[234:235], off
	s_barrier
	s_waitcnt lgkmcnt(0)
	s_waitcnt lgkmcnt(0)
	v_mfma_f32_16x16x32_bf16 v[80:83], v[218:221], v[156:159], v[80:83]
	v_mfma_f32_16x16x32_bf16 v[92:95], v[226:229], v[156:159], v[92:95]
	v_mfma_f32_16x16x32_bf16 v[64:67], v[218:221], v[164:167], v[64:67]
	v_mfma_f32_16x16x32_bf16 v[84:87], v[226:229], v[164:167], v[84:87]
	v_mfma_f32_16x16x32_bf16 v[52:55], v[218:221], v[172:175], v[52:55]
	v_mfma_f32_16x16x32_bf16 v[76:79], v[226:229], v[172:175], v[76:79]
	v_mfma_f32_16x16x32_bf16 v[40:43], v[218:221], v[186:189], v[40:43]
	v_mfma_f32_16x16x32_bf16 v[60:63], v[226:229], v[186:189], v[60:63]
	v_mfma_f32_16x16x32_bf16 v[80:83], v[222:225], v[160:163], v[80:83]
	v_mfma_f32_16x16x32_bf16 v[92:95], v[230:233], v[160:163], v[92:95]
	v_mfma_f32_16x16x32_bf16 v[64:67], v[222:225], v[168:171], v[64:67]
	v_mfma_f32_16x16x32_bf16 v[84:87], v[230:233], v[168:171], v[84:87]
	v_mfma_f32_16x16x32_bf16 v[52:55], v[222:225], v[182:185], v[52:55]
	v_mfma_f32_16x16x32_bf16 v[76:79], v[230:233], v[182:185], v[76:79]
	v_mfma_f32_16x16x32_bf16 v[40:43], v[222:225], v[214:217], v[40:43]
	v_mfma_f32_16x16x32_bf16 v[60:63], v[230:233], v[214:217], v[60:63]
	s_mov_b32 m0, s22
	v_lshl_add_u64 v[236:237], s[14:15], 0, v[176:177]
	s_barrier
	ds_read_b128 v[156:159], v138 offset:16384
	ds_read_b128 v[160:163], v138 offset:17408
	ds_read_b128 v[164:167], v138 offset:18432
	ds_read_b128 v[168:171], v138 offset:19456
	ds_read_b128 v[172:175], v138 offset:20480
	ds_read_b128 v[182:185], v138 offset:21504
	ds_read_b128 v[186:189], v138 offset:22528
	ds_read_b128 v[214:217], v138 offset:23552
	global_load_lds_dwordx4 v[236:237], off
	v_lshl_add_u64 v[238:239], s[14:15], 0, v[128:129]
	s_mov_b32 m0, s23
	s_nop 0
	global_load_lds_dwordx4 v[238:239], off
	s_waitcnt vmcnt(10)
	s_barrier
	s_waitcnt lgkmcnt(0)
	s_waitcnt lgkmcnt(0)
	v_mfma_f32_16x16x32_bf16 v[68:71], v[140:143], v[156:159], v[68:71]
	v_mfma_f32_16x16x32_bf16 v[88:91], v[148:151], v[156:159], v[88:91]
	v_mfma_f32_16x16x32_bf16 v[48:51], v[140:143], v[164:167], v[48:51]
	v_mfma_f32_16x16x32_bf16 v[72:75], v[148:151], v[164:167], v[72:75]
	v_mfma_f32_16x16x32_bf16 v[36:39], v[140:143], v[172:175], v[36:39]
	v_mfma_f32_16x16x32_bf16 v[56:59], v[148:151], v[172:175], v[56:59]
	v_mfma_f32_16x16x32_bf16 v[32:35], v[140:143], v[186:189], v[32:35]
	v_mfma_f32_16x16x32_bf16 v[44:47], v[148:151], v[186:189], v[44:47]
	v_mfma_f32_16x16x32_bf16 v[68:71], v[144:147], v[160:163], v[68:71]
	v_mfma_f32_16x16x32_bf16 v[88:91], v[152:155], v[160:163], v[88:91]
	v_mfma_f32_16x16x32_bf16 v[48:51], v[144:147], v[168:171], v[48:51]
	v_mfma_f32_16x16x32_bf16 v[72:75], v[152:155], v[168:171], v[72:75]
	v_mfma_f32_16x16x32_bf16 v[36:39], v[144:147], v[182:185], v[36:39]
	v_mfma_f32_16x16x32_bf16 v[56:59], v[152:155], v[182:185], v[56:59]
	v_mfma_f32_16x16x32_bf16 v[32:35], v[144:147], v[214:217], v[32:35]
	v_mfma_f32_16x16x32_bf16 v[44:47], v[152:155], v[214:217], v[44:47]
	s_barrier
	s_add_u32 s10, s12, 0xb0000
	s_addc_u32 s11, s13, 0
	s_add_i32 s34, s35, s58
	v_lshl_add_u64 v[140:141], s[10:11], 0, v[176:177]
	s_mov_b32 m0, s34
	s_nop 0
	global_load_lds_dwordx4 v[140:141], off
	v_lshl_add_u64 v[140:141], s[10:11], 0, v[128:129]
	s_add_i32 m0, s34, 0x2000
	s_nop 0
	global_load_lds_dwordx4 v[140:141], off
	v_add_u32_e32 v139, 0x18000, v137
	ds_read_b128 v[140:143], v139
	ds_read_b128 v[144:147], v139 offset:1024
	ds_read_b128 v[148:151], v139 offset:2048
	ds_read_b128 v[152:155], v139 offset:3072
	s_waitcnt vmcnt(6)
	s_barrier
	v_mfma_f32_16x16x32_bf16 v[120:123], v[218:221], v[156:159], v[120:123]
	v_mfma_f32_16x16x32_bf16 v[124:127], v[226:229], v[156:159], v[124:127]
	v_mfma_f32_16x16x32_bf16 v[112:115], v[218:221], v[164:167], v[112:115]
	v_mfma_f32_16x16x32_bf16 v[116:119], v[226:229], v[164:167], v[116:119]
	v_mfma_f32_16x16x32_bf16 v[104:107], v[218:221], v[172:175], v[104:107]
	v_mfma_f32_16x16x32_bf16 v[108:111], v[226:229], v[172:175], v[108:111]
	v_mfma_f32_16x16x32_bf16 v[96:99], v[218:221], v[186:189], v[96:99]
	v_mfma_f32_16x16x32_bf16 v[100:103], v[226:229], v[186:189], v[100:103]
	v_mfma_f32_16x16x32_bf16 v[120:123], v[222:225], v[160:163], v[120:123]
	v_mfma_f32_16x16x32_bf16 v[124:127], v[230:233], v[160:163], v[124:127]
	v_mfma_f32_16x16x32_bf16 v[112:115], v[222:225], v[168:171], v[112:115]
	v_mfma_f32_16x16x32_bf16 v[116:119], v[230:233], v[168:171], v[116:119]
	v_mfma_f32_16x16x32_bf16 v[104:107], v[222:225], v[182:185], v[104:107]
	v_mfma_f32_16x16x32_bf16 v[108:111], v[230:233], v[182:185], v[108:111]
	v_mfma_f32_16x16x32_bf16 v[96:99], v[222:225], v[214:217], v[96:99]
	v_mfma_f32_16x16x32_bf16 v[100:103], v[230:233], v[214:217], v[100:103]
	s_add_i32 s34, 0, 0x18000
	s_barrier
	s_add_u32 s10, s14, 0xb0000
	s_addc_u32 s11, s15, 0
	s_mov_b32 m0, s24
	v_lshl_add_u64 v[218:219], s[10:11], 0, v[176:177]
	ds_read_b128 v[156:159], v138 offset:32768
	ds_read_b128 v[160:163], v138 offset:33792
	ds_read_b128 v[164:167], v138 offset:34816
	ds_read_b128 v[168:171], v138 offset:35840
	ds_read_b128 v[172:175], v138 offset:36864
	ds_read_b128 v[182:185], v138 offset:37888
	ds_read_b128 v[186:189], v138 offset:38912
	ds_read_b128 v[214:217], v138 offset:39936
	global_load_lds_dwordx4 v[218:219], off
	v_lshl_add_u64 v[218:219], s[10:11], 0, v[128:129]
	s_mov_b32 m0, s25
	s_nop 0
	global_load_lds_dwordx4 v[218:219], off
	s_waitcnt lgkmcnt(8)
	s_barrier
	s_waitcnt lgkmcnt(0)
	s_waitcnt lgkmcnt(0)
	v_mfma_f32_16x16x32_bf16 v[20:23], v[140:143], v[156:159], v[20:23]
	v_mfma_f32_16x16x32_bf16 v[28:31], v[148:151], v[156:159], v[28:31]
	v_mfma_f32_16x16x32_bf16 v[12:15], v[140:143], v[164:167], v[12:15]
	v_mfma_f32_16x16x32_bf16 v[24:27], v[148:151], v[164:167], v[24:27]
	v_mfma_f32_16x16x32_bf16 v[4:7], v[140:143], v[172:175], v[4:7]
	v_mfma_f32_16x16x32_bf16 v[16:19], v[148:151], v[172:175], v[16:19]
	v_mfma_f32_16x16x32_bf16 v[0:3], v[140:143], v[186:189], v[0:3]
	v_mfma_f32_16x16x32_bf16 v[8:11], v[148:151], v[186:189], v[8:11]
	v_mfma_f32_16x16x32_bf16 v[20:23], v[144:147], v[160:163], v[20:23]
	v_mfma_f32_16x16x32_bf16 v[28:31], v[152:155], v[160:163], v[28:31]
	v_mfma_f32_16x16x32_bf16 v[12:15], v[144:147], v[168:171], v[12:15]
	v_mfma_f32_16x16x32_bf16 v[24:27], v[152:155], v[168:171], v[24:27]
	v_mfma_f32_16x16x32_bf16 v[4:7], v[144:147], v[182:185], v[4:7]
	v_mfma_f32_16x16x32_bf16 v[16:19], v[152:155], v[182:185], v[16:19]
	v_mfma_f32_16x16x32_bf16 v[0:3], v[144:147], v[214:217], v[0:3]
	v_mfma_f32_16x16x32_bf16 v[8:11], v[152:155], v[214:217], v[8:11]
	s_barrier
	s_add_i32 s14, 0, 0x1c000
	s_add_i32 s10, s34, s58
	v_add_u32_e32 v139, s14, v137
	v_lshl_add_u64 v[190:191], v[190:191], 0, s[64:65]
	s_mov_b32 m0, s10
	ds_read_b128 v[218:221], v139
	ds_read_b128 v[222:225], v139 offset:1024
	ds_read_b128 v[226:229], v139 offset:2048
	ds_read_b128 v[230:233], v139 offset:3072
	global_load_lds_dwordx4 v[190:191], off
	v_lshl_add_u64 v[190:191], v[234:235], 0, s[64:65]
	s_add_i32 m0, s10, 0x2000
	s_nop 0
	global_load_lds_dwordx4 v[190:191], off
	s_barrier
	s_waitcnt lgkmcnt(0)
	s_waitcnt lgkmcnt(0)
	v_mfma_f32_16x16x32_bf16 v[80:83], v[218:221], v[156:159], v[80:83]
	v_mfma_f32_16x16x32_bf16 v[92:95], v[226:229], v[156:159], v[92:95]
	v_mfma_f32_16x16x32_bf16 v[64:67], v[218:221], v[164:167], v[64:67]
	v_mfma_f32_16x16x32_bf16 v[84:87], v[226:229], v[164:167], v[84:87]
	v_mfma_f32_16x16x32_bf16 v[52:55], v[218:221], v[172:175], v[52:55]
	v_mfma_f32_16x16x32_bf16 v[76:79], v[226:229], v[172:175], v[76:79]
	v_mfma_f32_16x16x32_bf16 v[40:43], v[218:221], v[186:189], v[40:43]
	v_mfma_f32_16x16x32_bf16 v[60:63], v[226:229], v[186:189], v[60:63]
	v_mfma_f32_16x16x32_bf16 v[80:83], v[222:225], v[160:163], v[80:83]
	v_mfma_f32_16x16x32_bf16 v[92:95], v[230:233], v[160:163], v[92:95]
	v_mfma_f32_16x16x32_bf16 v[64:67], v[222:225], v[168:171], v[64:67]
	v_mfma_f32_16x16x32_bf16 v[84:87], v[230:233], v[168:171], v[84:87]
	v_mfma_f32_16x16x32_bf16 v[52:55], v[222:225], v[182:185], v[52:55]
	v_mfma_f32_16x16x32_bf16 v[76:79], v[230:233], v[182:185], v[76:79]
	v_mfma_f32_16x16x32_bf16 v[40:43], v[222:225], v[214:217], v[40:43]
	v_mfma_f32_16x16x32_bf16 v[60:63], v[230:233], v[214:217], v[60:63]
	s_mov_b32 m0, s0
	v_lshl_add_u64 v[190:191], v[236:237], 0, s[64:65]
	s_barrier
	ds_read_b128 v[156:159], v138 offset:49152
	ds_read_b128 v[160:163], v138 offset:50176
	ds_read_b128 v[164:167], v138 offset:51200
	ds_read_b128 v[168:171], v138 offset:52224
	ds_read_b128 v[172:175], v138 offset:53248
	ds_read_b128 v[182:185], v138 offset:54272
	ds_read_b128 v[186:189], v138 offset:55296
	ds_read_b128 v[214:217], v138 offset:56320
	global_load_lds_dwordx4 v[190:191], off
	v_lshl_add_u64 v[190:191], v[238:239], 0, s[64:65]
	s_mov_b32 m0, s1
	s_nop 0
	global_load_lds_dwordx4 v[190:191], off
	s_waitcnt vmcnt(10)
	s_barrier
	s_waitcnt lgkmcnt(0)
	s_waitcnt lgkmcnt(0)
	v_mfma_f32_16x16x32_bf16 v[68:71], v[140:143], v[156:159], v[68:71]
	v_mfma_f32_16x16x32_bf16 v[88:91], v[148:151], v[156:159], v[88:91]
	v_mfma_f32_16x16x32_bf16 v[48:51], v[140:143], v[164:167], v[48:51]
	v_mfma_f32_16x16x32_bf16 v[72:75], v[148:151], v[164:167], v[72:75]
	v_mfma_f32_16x16x32_bf16 v[36:39], v[140:143], v[172:175], v[36:39]
	v_mfma_f32_16x16x32_bf16 v[56:59], v[148:151], v[172:175], v[56:59]
	v_mfma_f32_16x16x32_bf16 v[32:35], v[140:143], v[186:189], v[32:35]
	v_mfma_f32_16x16x32_bf16 v[44:47], v[148:151], v[186:189], v[44:47]
	v_mfma_f32_16x16x32_bf16 v[68:71], v[144:147], v[160:163], v[68:71]
	v_mfma_f32_16x16x32_bf16 v[88:91], v[152:155], v[160:163], v[88:91]
	v_mfma_f32_16x16x32_bf16 v[48:51], v[144:147], v[168:171], v[48:51]
	v_mfma_f32_16x16x32_bf16 v[72:75], v[152:155], v[168:171], v[72:75]
	v_mfma_f32_16x16x32_bf16 v[36:39], v[144:147], v[182:185], v[36:39]
	v_mfma_f32_16x16x32_bf16 v[56:59], v[152:155], v[182:185], v[56:59]
	v_mfma_f32_16x16x32_bf16 v[32:35], v[144:147], v[214:217], v[32:35]
	v_mfma_f32_16x16x32_bf16 v[44:47], v[152:155], v[214:217], v[44:47]
	s_barrier
	s_add_u32 s10, s12, 0xb0080
	s_addc_u32 s11, s13, 0
	s_add_i32 s12, s14, s58
	v_lshl_add_u64 v[140:141], s[10:11], 0, v[176:177]
	s_mov_b32 m0, s12
	s_nop 0
	global_load_lds_dwordx4 v[140:141], off
	v_lshl_add_u64 v[140:141], s[10:11], 0, v[128:129]
	s_add_i32 m0, s12, 0x2000
	s_nop 0
	global_load_lds_dwordx4 v[140:141], off
	v_add_u32_e32 v139, 0x10000, v137
	ds_read_b128 v[140:143], v139
	ds_read_b128 v[144:147], v139 offset:1024
	ds_read_b128 v[148:151], v139 offset:2048
	ds_read_b128 v[152:155], v139 offset:3072
	s_waitcnt vmcnt(6)
	s_barrier
	v_mfma_f32_16x16x32_bf16 v[120:123], v[218:221], v[156:159], v[120:123]
	v_mfma_f32_16x16x32_bf16 v[124:127], v[226:229], v[156:159], v[124:127]
	v_mfma_f32_16x16x32_bf16 v[112:115], v[218:221], v[164:167], v[112:115]
	v_mfma_f32_16x16x32_bf16 v[116:119], v[226:229], v[164:167], v[116:119]
	v_mfma_f32_16x16x32_bf16 v[104:107], v[218:221], v[172:175], v[104:107]
	v_mfma_f32_16x16x32_bf16 v[108:111], v[226:229], v[172:175], v[108:111]
	v_mfma_f32_16x16x32_bf16 v[96:99], v[218:221], v[186:189], v[96:99]
	v_mfma_f32_16x16x32_bf16 v[100:103], v[226:229], v[186:189], v[100:103]
	v_mfma_f32_16x16x32_bf16 v[120:123], v[222:225], v[160:163], v[120:123]
	v_mfma_f32_16x16x32_bf16 v[124:127], v[230:233], v[160:163], v[124:127]
	v_mfma_f32_16x16x32_bf16 v[112:115], v[222:225], v[168:171], v[112:115]
	v_mfma_f32_16x16x32_bf16 v[116:119], v[230:233], v[168:171], v[116:119]
	v_mfma_f32_16x16x32_bf16 v[104:107], v[222:225], v[182:185], v[104:107]
	v_mfma_f32_16x16x32_bf16 v[108:111], v[230:233], v[182:185], v[108:111]
	v_mfma_f32_16x16x32_bf16 v[96:99], v[222:225], v[214:217], v[96:99]
	v_mfma_f32_16x16x32_bf16 v[100:103], v[230:233], v[214:217], v[100:103]
	s_add_i32 s67, s67, 2
	s_add_u32 s55, s55, 0x100
	s_addc_u32 s63, s63, 0
	s_cmp_gt_u32 s67, 41
	s_mov_b64 s[10:11], s[2:3]
	s_barrier
	s_cbranch_scc0 .LBB0_121
	s_lshl_b32 s2, s30, 8
	v_lshl_add_u32 v250, s29, 8, v136
	s_ashr_i32 s3, s2, 31
	v_ashrrev_i32_e32 v251, 31, v250
	v_lshl_add_u64 v[252:253], s[2:3], 1, v[130:131]
	v_lshlrev_b64 v[254:255], 11, v[250:251]
	v_lshl_add_u64 v[254:255], v[252:253], 0, v[254:255]
	v_cvt_pk_bf16_f32 v20, v20, v21
	v_cvt_pk_bf16_f32 v21, v22, v23
	v_cvt_pk_bf16_f32 v22, v28, v29
	v_cvt_pk_bf16_f32 v23, v30, v31
	global_store_dwordx4 v[254:255], v[20:23], off
	v_cvt_pk_bf16_f32 v12, v12, v13
	v_cvt_pk_bf16_f32 v13, v14, v15
	v_cvt_pk_bf16_f32 v20, v80, v81
	v_cvt_pk_bf16_f32 v21, v82, v83
	v_cvt_pk_bf16_f32 v22, v92, v93
	v_cvt_pk_bf16_f32 v23, v94, v95
	global_store_dwordx4 v[254:255], v[20:23], off offset:256
	v_cvt_pk_bf16_f32 v14, v24, v25
	v_cvt_pk_bf16_f32 v15, v26, v27
	v_or_b32_e32 v20, 16, v250
	v_ashrrev_i32_e32 v21, 31, v20
	v_lshlrev_b64 v[20:21], 11, v[20:21]
	v_lshl_add_u64 v[20:21], v[252:253], 0, v[20:21]
	global_store_dwordx4 v[20:21], v[12:15], off
	v_cvt_pk_bf16_f32 v4, v4, v5
	v_cvt_pk_bf16_f32 v5, v6, v7
	v_cvt_pk_bf16_f32 v12, v64, v65
	v_cvt_pk_bf16_f32 v13, v66, v67
	v_cvt_pk_bf16_f32 v14, v84, v85
	v_cvt_pk_bf16_f32 v15, v86, v87
	global_store_dwordx4 v[20:21], v[12:15], off offset:256
	v_cvt_pk_bf16_f32 v6, v16, v17
	v_cvt_pk_bf16_f32 v7, v18, v19
	v_or_b32_e32 v12, 32, v250
	v_ashrrev_i32_e32 v13, 31, v12
	v_lshlrev_b64 v[12:13], 11, v[12:13]
	v_lshl_add_u64 v[12:13], v[252:253], 0, v[12:13]
	global_store_dwordx4 v[12:13], v[4:7], off
	v_cvt_pk_bf16_f32 v0, v0, v1
	v_cvt_pk_bf16_f32 v1, v2, v3
	v_cvt_pk_bf16_f32 v4, v52, v53
	v_cvt_pk_bf16_f32 v5, v54, v55
	v_cvt_pk_bf16_f32 v6, v76, v77
	v_cvt_pk_bf16_f32 v7, v78, v79
	global_store_dwordx4 v[12:13], v[4:7], off offset:256
	v_cvt_pk_bf16_f32 v2, v8, v9
	v_cvt_pk_bf16_f32 v3, v10, v11
	v_or_b32_e32 v4, 48, v250
	v_ashrrev_i32_e32 v5, 31, v4
	v_lshlrev_b64 v[4:5], 11, v[4:5]
	v_lshl_add_u64 v[4:5], v[252:253], 0, v[4:5]
	global_store_dwordx4 v[4:5], v[0:3], off
	s_mov_b64 s[2:3], 0x40000
	v_readlane_b32 s63, v244, 19
	v_cvt_pk_bf16_f32 v0, v40, v41
	v_cvt_pk_bf16_f32 v1, v42, v43
	v_cvt_pk_bf16_f32 v2, v60, v61
	v_cvt_pk_bf16_f32 v3, v62, v63
	global_store_dwordx4 v[4:5], v[0:3], off offset:256
	v_lshl_add_u64 v[4:5], v[254:255], 0, s[2:3]
	s_mov_b32 s2, 0x40000
	v_add_co_u32_e32 v6, vcc, s2, v254
	v_cvt_pk_bf16_f32 v0, v68, v69
	v_cvt_pk_bf16_f32 v1, v70, v71
	v_cvt_pk_bf16_f32 v2, v88, v89
	v_cvt_pk_bf16_f32 v3, v90, v91
	v_addc_co_u32_e32 v7, vcc, 0, v255, vcc
	global_store_dwordx4 v[6:7], v[0:3], off
	s_mov_b64 s[2:3], 0x48000
	v_readlane_b32 s67, v244, 20
	v_cvt_pk_bf16_f32 v0, v120, v121
	v_cvt_pk_bf16_f32 v1, v122, v123
	v_cvt_pk_bf16_f32 v2, v124, v125
	v_cvt_pk_bf16_f32 v3, v126, v127
	global_store_dwordx4 v[4:5], v[0:3], off offset:256
	v_lshl_add_u64 v[4:5], v[254:255], 0, s[2:3]
	s_mov_b32 s2, 0x48000
	v_add_co_u32_e32 v6, vcc, s2, v254
	v_cvt_pk_bf16_f32 v0, v48, v49
	v_cvt_pk_bf16_f32 v1, v50, v51
	v_cvt_pk_bf16_f32 v2, v72, v73
	v_cvt_pk_bf16_f32 v3, v74, v75
	v_addc_co_u32_e32 v7, vcc, 0, v255, vcc
	global_store_dwordx4 v[6:7], v[0:3], off
	s_mov_b64 s[2:3], 0x50000
	s_movk_i32 s53, 0x440
	v_cvt_pk_bf16_f32 v0, v112, v113
	v_cvt_pk_bf16_f32 v1, v114, v115
	v_cvt_pk_bf16_f32 v2, v116, v117
	v_cvt_pk_bf16_f32 v3, v118, v119
	global_store_dwordx4 v[4:5], v[0:3], off offset:256
	v_lshl_add_u64 v[4:5], v[254:255], 0, s[2:3]
	s_mov_b32 s2, 0x50000
	v_add_co_u32_e32 v6, vcc, s2, v254
	v_cvt_pk_bf16_f32 v0, v36, v37
	v_cvt_pk_bf16_f32 v1, v38, v39
	v_cvt_pk_bf16_f32 v2, v56, v57
	v_cvt_pk_bf16_f32 v3, v58, v59
	v_addc_co_u32_e32 v7, vcc, 0, v255, vcc
	global_store_dwordx4 v[6:7], v[0:3], off
	s_mov_b64 s[2:3], 0x58000
	v_readlane_b32 s55, v244, 31
	v_cvt_pk_bf16_f32 v0, v104, v105
	v_cvt_pk_bf16_f32 v1, v106, v107
	v_cvt_pk_bf16_f32 v2, v108, v109
	v_cvt_pk_bf16_f32 v3, v110, v111
	global_store_dwordx4 v[4:5], v[0:3], off offset:256
	v_lshl_add_u64 v[4:5], v[254:255], 0, s[2:3]
	s_mov_b32 s2, 0x58000
	v_add_co_u32_e32 v6, vcc, s2, v254
	v_cvt_pk_bf16_f32 v0, v32, v33
	v_cvt_pk_bf16_f32 v1, v34, v35
	v_cvt_pk_bf16_f32 v2, v44, v45
	v_cvt_pk_bf16_f32 v3, v46, v47
	v_addc_co_u32_e32 v7, vcc, 0, v255, vcc
	global_store_dwordx4 v[6:7], v[0:3], off
	s_mov_b64 s[2:3], -1
	s_and_b64 vcc, exec, s[8:9]
	v_cvt_pk_bf16_f32 v0, v96, v97
	v_cvt_pk_bf16_f32 v1, v98, v99
	v_cvt_pk_bf16_f32 v2, v100, v101
	v_cvt_pk_bf16_f32 v3, v102, v103
	global_store_dwordx4 v[4:5], v[0:3], off offset:256
	s_cbranch_vccz .LBB0_117
	v_mov_b32_e32 v20, v177
	v_mov_b32_e32 v28, v177
	v_mov_b32_e32 v12, v177
	v_mov_b32_e32 v24, v177
	v_mov_b32_e32 v4, v177
	v_mov_b32_e32 v16, v177
	v_mov_b32_e32 v0, v177
	v_mov_b32_e32 v8, v177
	v_mov_b32_e32 v80, v177
	v_mov_b32_e32 v92, v177
	v_mov_b32_e32 v64, v177
	v_mov_b32_e32 v84, v177
	v_mov_b32_e32 v52, v177
	v_mov_b32_e32 v76, v177
	v_mov_b32_e32 v40, v177
	v_mov_b32_e32 v60, v177
	v_mov_b32_e32 v68, v177
	v_mov_b32_e32 v88, v177
	v_mov_b32_e32 v48, v177
	v_mov_b32_e32 v72, v177
	v_mov_b32_e32 v36, v177
	v_mov_b32_e32 v56, v177
	v_mov_b32_e32 v32, v177
	v_mov_b32_e32 v44, v177
	v_mov_b32_e32 v120, v177
	v_mov_b32_e32 v124, v177
	v_mov_b32_e32 v112, v177
	v_mov_b32_e32 v116, v177
	v_mov_b32_e32 v104, v177
	v_mov_b32_e32 v108, v177
	v_mov_b32_e32 v96, v177
	v_mov_b32_e32 v100, v177
	s_nop 0
	v_mov_b32_e32 v21, v20
	v_mov_b32_e32 v22, v20
	v_mov_b32_e32 v23, v20
	v_mov_b32_e32 v29, v28
	v_mov_b32_e32 v30, v28
	v_mov_b32_e32 v31, v28
	v_mov_b32_e32 v13, v12
	v_mov_b32_e32 v14, v12
	v_mov_b32_e32 v15, v12
	v_mov_b32_e32 v25, v24
	v_mov_b32_e32 v26, v24
	v_mov_b32_e32 v27, v24
	v_mov_b32_e32 v5, v4
	v_mov_b32_e32 v6, v4
	v_mov_b32_e32 v7, v4
	v_mov_b32_e32 v17, v16
	v_mov_b32_e32 v18, v16
	v_mov_b32_e32 v19, v16
	s_nop 0
	v_mov_b32_e32 v1, v0
	v_mov_b32_e32 v2, v0
	v_mov_b32_e32 v3, v0
	v_mov_b32_e32 v9, v8
	v_mov_b32_e32 v10, v8
	v_mov_b32_e32 v11, v8
	v_mov_b32_e32 v81, v80
	v_mov_b32_e32 v82, v80
	v_mov_b32_e32 v83, v80
	v_mov_b32_e32 v93, v92
	v_mov_b32_e32 v94, v92
	v_mov_b32_e32 v95, v92
	v_mov_b32_e32 v65, v64
	v_mov_b32_e32 v66, v64
	v_mov_b32_e32 v67, v64
	v_mov_b32_e32 v85, v84
	v_mov_b32_e32 v86, v84
	v_mov_b32_e32 v87, v84
	s_nop 0
	v_mov_b32_e32 v53, v52
	v_mov_b32_e32 v54, v52
	v_mov_b32_e32 v55, v52
	v_mov_b32_e32 v77, v76
	v_mov_b32_e32 v78, v76
	v_mov_b32_e32 v79, v76
	v_mov_b32_e32 v41, v40
	v_mov_b32_e32 v42, v40
	v_mov_b32_e32 v43, v40
	v_mov_b32_e32 v61, v60
	v_mov_b32_e32 v62, v60
	v_mov_b32_e32 v63, v60
	v_mov_b32_e32 v69, v68
	v_mov_b32_e32 v70, v68
	v_mov_b32_e32 v71, v68
	v_mov_b32_e32 v89, v88
	v_mov_b32_e32 v90, v88
	v_mov_b32_e32 v91, v88
	s_nop 0
	v_mov_b32_e32 v49, v48
	v_mov_b32_e32 v50, v48
	v_mov_b32_e32 v51, v48
	v_mov_b32_e32 v73, v72
	v_mov_b32_e32 v74, v72
	v_mov_b32_e32 v75, v72
	v_mov_b32_e32 v37, v36
	v_mov_b32_e32 v38, v36
	v_mov_b32_e32 v39, v36
	v_mov_b32_e32 v57, v56
	v_mov_b32_e32 v58, v56
	v_mov_b32_e32 v59, v56
	v_mov_b32_e32 v33, v32
	v_mov_b32_e32 v34, v32
	v_mov_b32_e32 v35, v32
	v_mov_b32_e32 v45, v44
	v_mov_b32_e32 v46, v44
	v_mov_b32_e32 v47, v44
	s_nop 0
	v_mov_b32_e32 v121, v120
	v_mov_b32_e32 v122, v120
	v_mov_b32_e32 v123, v120
	v_mov_b32_e32 v125, v124
	v_mov_b32_e32 v126, v124
	v_mov_b32_e32 v127, v124
	v_mov_b32_e32 v113, v112
	v_mov_b32_e32 v114, v112
	v_mov_b32_e32 v115, v112
	v_mov_b32_e32 v117, v116
	v_mov_b32_e32 v118, v116
	v_mov_b32_e32 v119, v116
	v_mov_b32_e32 v105, v104
	v_mov_b32_e32 v106, v104
	v_mov_b32_e32 v107, v104
	v_mov_b32_e32 v109, v108
	v_mov_b32_e32 v110, v108
	v_mov_b32_e32 v111, v108
	s_mov_b64 s[2:3], 0
	v_mov_b32_e32 v97, v96
	v_mov_b32_e32 v98, v96
	v_mov_b32_e32 v99, v96
	v_mov_b32_e32 v101, v100
	v_mov_b32_e32 v102, v100
	v_mov_b32_e32 v103, v100
	s_branch .LBB0_117

.LBB0_320:
	s_add_u32 s2, s10, 0x100
	s_addc_u32 s3, s11, 0
	s_add_i32 s23, 0, 0x10000
	s_cmp_eq_u32 s22, 12
	s_cselect_b32 s29, s9, s3
	s_cselect_b32 s28, s8, s2
	s_cselect_b32 s93, s5, s21
	s_cselect_b32 s92, s1, s7
	v_lshl_add_u64 v[136:137], s[10:11], 0, v[132:133]
	s_add_i32 m0, s17, 0xc000
	ds_read_b128 v[158:161], v140
	ds_read_b128 v[162:165], v140 offset:1024
	ds_read_b128 v[166:169], v140 offset:2048
	ds_read_b128 v[170:173], v140 offset:3072
	ds_read_b128 v[182:185], v140 offset:4096
	ds_read_b128 v[186:189], v140 offset:5120
	ds_read_b128 v[214:217], v140 offset:6144
	ds_read_b128 v[218:221], v140 offset:7168
	global_load_lds_dwordx4 v[136:137], off
	v_lshl_add_u64 v[136:137], s[10:11], 0, v[134:135]
	s_add_i32 m0, s17, 0xe000
	s_nop 0
	global_load_lds_dwordx4 v[136:137], off
	s_waitcnt lgkmcnt(8)
	s_barrier
	s_waitcnt lgkmcnt(0)
	s_waitcnt lgkmcnt(0)
	v_mfma_f32_16x16x32_bf16 v[120:123], v[142:145], v[158:161], v[120:123]
	v_mfma_f32_16x16x32_bf16 v[124:127], v[150:153], v[158:161], v[124:127]
	v_mfma_f32_16x16x32_bf16 v[104:107], v[142:145], v[166:169], v[104:107]
	v_mfma_f32_16x16x32_bf16 v[108:111], v[150:153], v[166:169], v[108:111]
	v_mfma_f32_16x16x32_bf16 v[88:91], v[142:145], v[182:185], v[88:91]
	v_mfma_f32_16x16x32_bf16 v[92:95], v[150:153], v[182:185], v[92:95]
	v_mfma_f32_16x16x32_bf16 v[72:75], v[142:145], v[214:217], v[72:75]
	v_mfma_f32_16x16x32_bf16 v[76:79], v[150:153], v[214:217], v[76:79]
	v_mfma_f32_16x16x32_bf16 v[120:123], v[146:149], v[162:165], v[120:123]
	v_mfma_f32_16x16x32_bf16 v[124:127], v[154:157], v[162:165], v[124:127]
	v_mfma_f32_16x16x32_bf16 v[104:107], v[146:149], v[170:173], v[104:107]
	v_mfma_f32_16x16x32_bf16 v[108:111], v[154:157], v[170:173], v[108:111]
	v_mfma_f32_16x16x32_bf16 v[88:91], v[146:149], v[186:189], v[88:91]
	v_mfma_f32_16x16x32_bf16 v[92:95], v[154:157], v[186:189], v[92:95]
	v_mfma_f32_16x16x32_bf16 v[72:75], v[146:149], v[218:221], v[72:75]
	v_mfma_f32_16x16x32_bf16 v[76:79], v[154:157], v[218:221], v[76:79]
	s_barrier
	s_add_i32 s24, 0, 0x14000
	v_add_u32_e32 v136, s24, v139
	s_add_i32 s10, s23, s58
	ds_read_b128 v[222:225], v136
	ds_read_b128 v[226:229], v136 offset:1024
	ds_read_b128 v[230:233], v136 offset:2048
	ds_read_b128 v[234:237], v136 offset:3072
	v_lshl_add_u64 v[136:137], s[92:93], 0, v[176:177]
	s_mov_b32 m0, s10
	v_lshl_add_u64 v[174:175], s[92:93], 0, v[128:129]
	global_load_lds_dwordx4 v[136:137], off
	s_add_i32 m0, s10, 0x2000
	s_nop 0
	global_load_lds_dwordx4 v[174:175], off
	s_barrier
	s_waitcnt lgkmcnt(0)
	s_waitcnt lgkmcnt(0)
	v_mfma_f32_16x16x32_bf16 v[112:115], v[222:225], v[158:161], v[112:115]
	v_mfma_f32_16x16x32_bf16 v[116:119], v[230:233], v[158:161], v[116:119]
	v_mfma_f32_16x16x32_bf16 v[96:99], v[222:225], v[166:169], v[96:99]
	v_mfma_f32_16x16x32_bf16 v[100:103], v[230:233], v[166:169], v[100:103]
	v_mfma_f32_16x16x32_bf16 v[80:83], v[222:225], v[182:185], v[80:83]
	v_mfma_f32_16x16x32_bf16 v[84:87], v[230:233], v[182:185], v[84:87]
	v_mfma_f32_16x16x32_bf16 v[64:67], v[222:225], v[214:217], v[64:67]
	v_mfma_f32_16x16x32_bf16 v[68:71], v[230:233], v[214:217], v[68:71]
	v_mfma_f32_16x16x32_bf16 v[112:115], v[226:229], v[162:165], v[112:115]
	v_mfma_f32_16x16x32_bf16 v[116:119], v[234:237], v[162:165], v[116:119]
	v_mfma_f32_16x16x32_bf16 v[96:99], v[226:229], v[170:173], v[96:99]
	v_mfma_f32_16x16x32_bf16 v[100:103], v[234:237], v[170:173], v[100:103]
	v_mfma_f32_16x16x32_bf16 v[80:83], v[226:229], v[186:189], v[80:83]
	v_mfma_f32_16x16x32_bf16 v[84:87], v[234:237], v[186:189], v[84:87]
	v_mfma_f32_16x16x32_bf16 v[64:67], v[226:229], v[218:221], v[64:67]
	v_mfma_f32_16x16x32_bf16 v[68:71], v[234:237], v[218:221], v[68:71]
	s_mov_b32 m0, s17
	v_lshl_add_u64 v[190:191], s[28:29], 0, v[176:177]
	s_barrier
	ds_read_b128 v[158:161], v140 offset:16384
	ds_read_b128 v[162:165], v140 offset:17408
	ds_read_b128 v[166:169], v140 offset:18432
	ds_read_b128 v[170:173], v140 offset:19456
	ds_read_b128 v[182:185], v140 offset:20480
	ds_read_b128 v[186:189], v140 offset:21504
	ds_read_b128 v[214:217], v140 offset:22528
	ds_read_b128 v[218:221], v140 offset:23552
	global_load_lds_dwordx4 v[190:191], off
	v_lshl_add_u64 v[238:239], s[28:29], 0, v[128:129]
	s_mov_b32 m0, s89
	s_nop 0
	global_load_lds_dwordx4 v[238:239], off
	s_waitcnt vmcnt(10)
	s_barrier
	s_waitcnt lgkmcnt(0)
	s_waitcnt lgkmcnt(0)
	v_mfma_f32_16x16x32_bf16 v[56:59], v[142:145], v[158:161], v[56:59]
	v_mfma_f32_16x16x32_bf16 v[60:63], v[150:153], v[158:161], v[60:63]
	v_mfma_f32_16x16x32_bf16 v[40:43], v[142:145], v[166:169], v[40:43]
	v_mfma_f32_16x16x32_bf16 v[44:47], v[150:153], v[166:169], v[44:47]
	v_mfma_f32_16x16x32_bf16 v[24:27], v[142:145], v[182:185], v[24:27]
	v_mfma_f32_16x16x32_bf16 v[28:31], v[150:153], v[182:185], v[28:31]
	v_mfma_f32_16x16x32_bf16 v[8:11], v[142:145], v[214:217], v[8:11]
	v_mfma_f32_16x16x32_bf16 v[12:15], v[150:153], v[214:217], v[12:15]
	v_mfma_f32_16x16x32_bf16 v[56:59], v[146:149], v[162:165], v[56:59]
	v_mfma_f32_16x16x32_bf16 v[60:63], v[154:157], v[162:165], v[60:63]
	v_mfma_f32_16x16x32_bf16 v[40:43], v[146:149], v[170:173], v[40:43]
	v_mfma_f32_16x16x32_bf16 v[44:47], v[154:157], v[170:173], v[44:47]
	v_mfma_f32_16x16x32_bf16 v[24:27], v[146:149], v[186:189], v[24:27]
	v_mfma_f32_16x16x32_bf16 v[28:31], v[154:157], v[186:189], v[28:31]
	v_mfma_f32_16x16x32_bf16 v[8:11], v[146:149], v[218:221], v[8:11]
	v_mfma_f32_16x16x32_bf16 v[12:15], v[154:157], v[218:221], v[12:15]
	s_barrier
	s_add_u32 s10, s92, 0x40000
	s_addc_u32 s11, s93, 0
	s_add_i32 s23, s24, s58
	v_lshl_add_u64 v[142:143], s[10:11], 0, v[176:177]
	s_mov_b32 m0, s23
	s_nop 0
	global_load_lds_dwordx4 v[142:143], off
	v_lshl_add_u64 v[142:143], s[10:11], 0, v[128:129]
	s_add_i32 m0, s23, 0x2000
	s_nop 0
	global_load_lds_dwordx4 v[142:143], off
	v_add_u32_e32 v141, 0x18000, v139
	ds_read_b128 v[142:145], v141
	ds_read_b128 v[146:149], v141 offset:1024
	ds_read_b128 v[150:153], v141 offset:2048
	ds_read_b128 v[154:157], v141 offset:3072
	s_waitcnt vmcnt(6)
	s_barrier
	v_mfma_f32_16x16x32_bf16 v[48:51], v[222:225], v[158:161], v[48:51]
	v_mfma_f32_16x16x32_bf16 v[52:55], v[230:233], v[158:161], v[52:55]
	v_mfma_f32_16x16x32_bf16 v[32:35], v[222:225], v[166:169], v[32:35]
	v_mfma_f32_16x16x32_bf16 v[36:39], v[230:233], v[166:169], v[36:39]
	v_mfma_f32_16x16x32_bf16 v[16:19], v[222:225], v[182:185], v[16:19]
	v_mfma_f32_16x16x32_bf16 v[20:23], v[230:233], v[182:185], v[20:23]
	v_mfma_f32_16x16x32_bf16 v[0:3], v[222:225], v[214:217], v[0:3]
	v_mfma_f32_16x16x32_bf16 v[4:7], v[230:233], v[214:217], v[4:7]
	v_mfma_f32_16x16x32_bf16 v[48:51], v[226:229], v[162:165], v[48:51]
	v_mfma_f32_16x16x32_bf16 v[52:55], v[234:237], v[162:165], v[52:55]
	v_mfma_f32_16x16x32_bf16 v[32:35], v[226:229], v[170:173], v[32:35]
	v_mfma_f32_16x16x32_bf16 v[36:39], v[234:237], v[170:173], v[36:39]
	v_mfma_f32_16x16x32_bf16 v[16:19], v[226:229], v[186:189], v[16:19]
	v_mfma_f32_16x16x32_bf16 v[20:23], v[234:237], v[186:189], v[20:23]
	v_mfma_f32_16x16x32_bf16 v[0:3], v[226:229], v[218:221], v[0:3]
	v_mfma_f32_16x16x32_bf16 v[4:7], v[234:237], v[218:221], v[4:7]
	s_add_i32 s23, 0, 0x18000
	s_barrier
	s_add_u32 s10, s28, 0x40000
	s_addc_u32 s11, s29, 0
	s_mov_b32 m0, s88
	v_lshl_add_u64 v[222:223], s[10:11], 0, v[176:177]
	ds_read_b128 v[158:161], v140 offset:32768
	ds_read_b128 v[162:165], v140 offset:33792
	ds_read_b128 v[166:169], v140 offset:34816
	ds_read_b128 v[170:173], v140 offset:35840
	ds_read_b128 v[182:185], v140 offset:36864
	ds_read_b128 v[186:189], v140 offset:37888
	ds_read_b128 v[214:217], v140 offset:38912
	ds_read_b128 v[218:221], v140 offset:39936
	global_load_lds_dwordx4 v[222:223], off
	v_lshl_add_u64 v[222:223], s[10:11], 0, v[128:129]
	s_mov_b32 m0, s55
	s_nop 0
	global_load_lds_dwordx4 v[222:223], off
	s_waitcnt lgkmcnt(8)
	s_barrier
	s_waitcnt lgkmcnt(0)
	s_waitcnt lgkmcnt(0)
	v_mfma_f32_16x16x32_bf16 v[120:123], v[142:145], v[158:161], v[120:123]
	v_mfma_f32_16x16x32_bf16 v[124:127], v[150:153], v[158:161], v[124:127]
	v_mfma_f32_16x16x32_bf16 v[104:107], v[142:145], v[166:169], v[104:107]
	v_mfma_f32_16x16x32_bf16 v[108:111], v[150:153], v[166:169], v[108:111]
	v_mfma_f32_16x16x32_bf16 v[88:91], v[142:145], v[182:185], v[88:91]
	v_mfma_f32_16x16x32_bf16 v[92:95], v[150:153], v[182:185], v[92:95]
	v_mfma_f32_16x16x32_bf16 v[72:75], v[142:145], v[214:217], v[72:75]
	v_mfma_f32_16x16x32_bf16 v[76:79], v[150:153], v[214:217], v[76:79]
	v_mfma_f32_16x16x32_bf16 v[120:123], v[146:149], v[162:165], v[120:123]
	v_mfma_f32_16x16x32_bf16 v[124:127], v[154:157], v[162:165], v[124:127]
	v_mfma_f32_16x16x32_bf16 v[104:107], v[146:149], v[170:173], v[104:107]
	v_mfma_f32_16x16x32_bf16 v[108:111], v[154:157], v[170:173], v[108:111]
	v_mfma_f32_16x16x32_bf16 v[88:91], v[146:149], v[186:189], v[88:91]
	v_mfma_f32_16x16x32_bf16 v[92:95], v[154:157], v[186:189], v[92:95]
	v_mfma_f32_16x16x32_bf16 v[72:75], v[146:149], v[218:221], v[72:75]
	v_mfma_f32_16x16x32_bf16 v[76:79], v[154:157], v[218:221], v[76:79]
	s_barrier
	s_add_i32 s24, 0, 0x1c000
	s_add_i32 s10, s23, s58
	v_add_u32_e32 v141, s24, v139
	v_lshl_add_u64 v[136:137], v[136:137], 0, s[64:65]
	s_mov_b32 m0, s10
	ds_read_b128 v[222:225], v141
	ds_read_b128 v[226:229], v141 offset:1024
	ds_read_b128 v[230:233], v141 offset:2048
	ds_read_b128 v[234:237], v141 offset:3072
	global_load_lds_dwordx4 v[136:137], off
	v_lshl_add_u64 v[136:137], v[174:175], 0, s[64:65]
	s_add_i32 m0, s10, 0x2000
	s_nop 0
	global_load_lds_dwordx4 v[136:137], off
	s_barrier
	s_waitcnt lgkmcnt(0)
	s_waitcnt lgkmcnt(0)
	v_mfma_f32_16x16x32_bf16 v[112:115], v[222:225], v[158:161], v[112:115]
	v_mfma_f32_16x16x32_bf16 v[116:119], v[230:233], v[158:161], v[116:119]
	v_mfma_f32_16x16x32_bf16 v[96:99], v[222:225], v[166:169], v[96:99]
	v_mfma_f32_16x16x32_bf16 v[100:103], v[230:233], v[166:169], v[100:103]
	v_mfma_f32_16x16x32_bf16 v[80:83], v[222:225], v[182:185], v[80:83]
	v_mfma_f32_16x16x32_bf16 v[84:87], v[230:233], v[182:185], v[84:87]
	v_mfma_f32_16x16x32_bf16 v[64:67], v[222:225], v[214:217], v[64:67]
	v_mfma_f32_16x16x32_bf16 v[68:71], v[230:233], v[214:217], v[68:71]
	v_mfma_f32_16x16x32_bf16 v[112:115], v[226:229], v[162:165], v[112:115]
	v_mfma_f32_16x16x32_bf16 v[116:119], v[234:237], v[162:165], v[116:119]
	v_mfma_f32_16x16x32_bf16 v[96:99], v[226:229], v[170:173], v[96:99]
	v_mfma_f32_16x16x32_bf16 v[100:103], v[234:237], v[170:173], v[100:103]
	v_mfma_f32_16x16x32_bf16 v[80:83], v[226:229], v[186:189], v[80:83]
	v_mfma_f32_16x16x32_bf16 v[84:87], v[234:237], v[186:189], v[84:87]
	v_mfma_f32_16x16x32_bf16 v[64:67], v[226:229], v[218:221], v[64:67]
	v_mfma_f32_16x16x32_bf16 v[68:71], v[234:237], v[218:221], v[68:71]
	s_mov_b32 m0, s30
	v_lshl_add_u64 v[136:137], v[190:191], 0, s[64:65]
	s_barrier
	ds_read_b128 v[158:161], v140 offset:49152
	ds_read_b128 v[162:165], v140 offset:50176
	ds_read_b128 v[166:169], v140 offset:51200
	ds_read_b128 v[170:173], v140 offset:52224
	ds_read_b128 v[182:185], v140 offset:53248
	ds_read_b128 v[186:189], v140 offset:54272
	ds_read_b128 v[214:217], v140 offset:55296
	ds_read_b128 v[218:221], v140 offset:56320
	global_load_lds_dwordx4 v[136:137], off
	v_lshl_add_u64 v[136:137], v[238:239], 0, s[64:65]
	s_mov_b32 m0, s31
	s_nop 0
	global_load_lds_dwordx4 v[136:137], off
	s_waitcnt vmcnt(10)
	s_barrier
	s_waitcnt lgkmcnt(0)
	s_waitcnt lgkmcnt(0)
	v_mfma_f32_16x16x32_bf16 v[56:59], v[142:145], v[158:161], v[56:59]
	v_mfma_f32_16x16x32_bf16 v[60:63], v[150:153], v[158:161], v[60:63]
	v_mfma_f32_16x16x32_bf16 v[40:43], v[142:145], v[166:169], v[40:43]
	v_mfma_f32_16x16x32_bf16 v[44:47], v[150:153], v[166:169], v[44:47]
	v_mfma_f32_16x16x32_bf16 v[24:27], v[142:145], v[182:185], v[24:27]
	v_mfma_f32_16x16x32_bf16 v[28:31], v[150:153], v[182:185], v[28:31]
	v_mfma_f32_16x16x32_bf16 v[8:11], v[142:145], v[214:217], v[8:11]
	v_mfma_f32_16x16x32_bf16 v[12:15], v[150:153], v[214:217], v[12:15]
	v_mfma_f32_16x16x32_bf16 v[56:59], v[146:149], v[162:165], v[56:59]
	v_mfma_f32_16x16x32_bf16 v[60:63], v[154:157], v[162:165], v[60:63]
	v_mfma_f32_16x16x32_bf16 v[40:43], v[146:149], v[170:173], v[40:43]
	v_mfma_f32_16x16x32_bf16 v[44:47], v[154:157], v[170:173], v[44:47]
	v_mfma_f32_16x16x32_bf16 v[24:27], v[146:149], v[186:189], v[24:27]
	v_mfma_f32_16x16x32_bf16 v[28:31], v[154:157], v[186:189], v[28:31]
	v_mfma_f32_16x16x32_bf16 v[8:11], v[146:149], v[218:221], v[8:11]
	v_mfma_f32_16x16x32_bf16 v[12:15], v[154:157], v[218:221], v[12:15]
	s_barrier
	s_add_u32 s10, s92, 0x40080
	s_addc_u32 s11, s93, 0
	s_add_i32 s23, s24, s58
	v_lshl_add_u64 v[136:137], s[10:11], 0, v[176:177]
	s_mov_b32 m0, s23
	s_nop 0
	global_load_lds_dwordx4 v[136:137], off
	v_lshl_add_u64 v[136:137], s[10:11], 0, v[128:129]
	s_add_i32 m0, s23, 0x2000
	s_nop 0
	global_load_lds_dwordx4 v[136:137], off
	v_add_u32_e32 v136, 0x10000, v139
	ds_read_b128 v[142:145], v136
	ds_read_b128 v[146:149], v136 offset:1024
	ds_read_b128 v[150:153], v136 offset:2048
	ds_read_b128 v[154:157], v136 offset:3072
	s_waitcnt vmcnt(6)
	s_barrier
	v_mfma_f32_16x16x32_bf16 v[48:51], v[222:225], v[158:161], v[48:51]
	v_mfma_f32_16x16x32_bf16 v[52:55], v[230:233], v[158:161], v[52:55]
	v_mfma_f32_16x16x32_bf16 v[32:35], v[222:225], v[166:169], v[32:35]
	v_mfma_f32_16x16x32_bf16 v[36:39], v[230:233], v[166:169], v[36:39]
	v_mfma_f32_16x16x32_bf16 v[16:19], v[222:225], v[182:185], v[16:19]
	v_mfma_f32_16x16x32_bf16 v[20:23], v[230:233], v[182:185], v[20:23]
	v_mfma_f32_16x16x32_bf16 v[0:3], v[222:225], v[214:217], v[0:3]
	v_mfma_f32_16x16x32_bf16 v[4:7], v[230:233], v[214:217], v[4:7]
	v_mfma_f32_16x16x32_bf16 v[48:51], v[226:229], v[162:165], v[48:51]
	v_mfma_f32_16x16x32_bf16 v[52:55], v[234:237], v[162:165], v[52:55]
	v_mfma_f32_16x16x32_bf16 v[32:35], v[226:229], v[170:173], v[32:35]
	v_mfma_f32_16x16x32_bf16 v[36:39], v[234:237], v[170:173], v[36:39]
	v_mfma_f32_16x16x32_bf16 v[16:19], v[226:229], v[186:189], v[16:19]
	v_mfma_f32_16x16x32_bf16 v[20:23], v[234:237], v[186:189], v[20:23]
	v_mfma_f32_16x16x32_bf16 v[0:3], v[226:229], v[218:221], v[0:3]
	v_mfma_f32_16x16x32_bf16 v[4:7], v[234:237], v[218:221], v[4:7]
	s_add_i32 s22, s22, 2
	s_add_u32 s7, s7, 0x100
	s_addc_u32 s21, s21, 0
	s_cmp_gt_u32 s22, 13
	s_mov_b64 s[10:11], s[2:3]
	s_barrier
	s_cbranch_scc0 .LBB0_320
	v_mul_f32_e32 v252, 0xbfb8aa3b, v120
	v_mul_f32_e32 v253, 0xbfb8aa3b, v121
	v_exp_f32_e32 v252, v252
	v_exp_f32_e32 v253, v253
	s_lshl_b32 s0, s0, 7
	s_ashr_i32 s1, s0, 31
	v_add_f32_e32 v252, 1.0, v252
	v_add_f32_e32 v253, 1.0, v253
	v_rcp_f32_e32 v252, v252
	v_rcp_f32_e32 v253, v253
	v_lshl_add_u32 v141, s16, 8, v138
	v_lshl_add_u64 v[136:137], s[0:1], 1, v[130:131]
	s_movk_i32 s2, 0x1600
	v_pk_mul_f32 v[120:121], v[120:121], v[252:253]
	s_and_b64 vcc, exec, s[14:15]
	v_pk_mul_f32 v[120:121], v[124:125], v[120:121]
	v_mul_f32_e32 v124, 0xbfb8aa3b, v122
	v_mul_f32_e32 v125, 0xbfb8aa3b, v123
	v_exp_f32_e32 v124, v124
	v_exp_f32_e32 v125, v125
	v_cvt_pk_bf16_f32 v120, v120, v121
	v_add_f32_e32 v124, 1.0, v124
	v_add_f32_e32 v125, 1.0, v125
	v_rcp_f32_e32 v124, v124
	v_rcp_f32_e32 v125, v125
	s_nop 0
	v_pk_mul_f32 v[122:123], v[122:123], v[124:125]
	s_nop 0
	v_pk_mul_f32 v[122:123], v[126:127], v[122:123]
	s_nop 0
	v_cvt_pk_bf16_f32 v121, v122, v123
	v_mul_f32_e32 v122, 0xbfb8aa3b, v112
	v_mul_f32_e32 v123, 0xbfb8aa3b, v113
	v_exp_f32_e32 v122, v122
	v_exp_f32_e32 v123, v123
	v_add_f32_e32 v122, 1.0, v122
	v_add_f32_e32 v123, 1.0, v123
	v_rcp_f32_e32 v122, v122
	v_rcp_f32_e32 v123, v123
	s_nop 0
	v_pk_mul_f32 v[112:113], v[112:113], v[122:123]
	s_nop 0
	v_pk_mul_f32 v[112:113], v[116:117], v[112:113]
	v_mul_f32_e32 v116, 0xbfb8aa3b, v114
	v_mul_f32_e32 v117, 0xbfb8aa3b, v115
	v_exp_f32_e32 v116, v116
	v_exp_f32_e32 v117, v117
	v_cvt_pk_bf16_f32 v122, v112, v113
	v_mad_i64_i32 v[112:113], s[0:1], v141, s2, v[136:137]
	v_add_f32_e32 v116, 1.0, v116
	v_add_f32_e32 v117, 1.0, v117
	v_rcp_f32_e32 v116, v116
	v_rcp_f32_e32 v117, v117
	s_nop 0
	v_pk_mul_f32 v[114:115], v[114:115], v[116:117]
	s_nop 0
	v_pk_mul_f32 v[114:115], v[118:119], v[114:115]
	s_nop 0
	v_cvt_pk_bf16_f32 v123, v114, v115
	global_store_dwordx4 v[112:113], v[120:123], off
	v_mul_f32_e32 v112, 0xbfb8aa3b, v104
	v_mul_f32_e32 v113, 0xbfb8aa3b, v105
	v_exp_f32_e32 v112, v112
	v_exp_f32_e32 v113, v113
	v_or_b32_e32 v114, 16, v141
	v_add_f32_e32 v112, 1.0, v112
	v_add_f32_e32 v113, 1.0, v113
	v_rcp_f32_e32 v112, v112
	v_rcp_f32_e32 v113, v113
	s_nop 0
	v_pk_mul_f32 v[104:105], v[104:105], v[112:113]
	s_nop 0
	v_pk_mul_f32 v[104:105], v[108:109], v[104:105]
	v_mul_f32_e32 v108, 0xbfb8aa3b, v106
	v_mul_f32_e32 v109, 0xbfb8aa3b, v107
	v_exp_f32_e32 v108, v108
	v_exp_f32_e32 v109, v109
	v_cvt_pk_bf16_f32 v104, v104, v105
	v_add_f32_e32 v108, 1.0, v108
	v_add_f32_e32 v109, 1.0, v109
	v_rcp_f32_e32 v108, v108
	v_rcp_f32_e32 v109, v109
	s_nop 0
	v_pk_mul_f32 v[106:107], v[106:107], v[108:109]
	s_nop 0
	v_pk_mul_f32 v[106:107], v[110:111], v[106:107]
	s_nop 0
	v_cvt_pk_bf16_f32 v105, v106, v107
	v_mul_f32_e32 v106, 0xbfb8aa3b, v96
	v_mul_f32_e32 v107, 0xbfb8aa3b, v97
	v_exp_f32_e32 v106, v106
	v_exp_f32_e32 v107, v107
	v_add_f32_e32 v106, 1.0, v106
	v_add_f32_e32 v107, 1.0, v107
	v_rcp_f32_e32 v106, v106
	v_rcp_f32_e32 v107, v107
	s_nop 0
	v_pk_mul_f32 v[96:97], v[96:97], v[106:107]
	s_nop 0
	v_pk_mul_f32 v[96:97], v[100:101], v[96:97]
	v_mul_f32_e32 v100, 0xbfb8aa3b, v98
	v_mul_f32_e32 v101, 0xbfb8aa3b, v99
	v_exp_f32_e32 v100, v100
	v_exp_f32_e32 v101, v101
	v_cvt_pk_bf16_f32 v106, v96, v97
	v_mad_i64_i32 v[96:97], s[0:1], v114, s2, v[136:137]
	v_add_f32_e32 v100, 1.0, v100
	v_add_f32_e32 v101, 1.0, v101
	v_rcp_f32_e32 v100, v100
	v_rcp_f32_e32 v101, v101
	s_nop 0
	v_pk_mul_f32 v[98:99], v[98:99], v[100:101]
	s_nop 0
	v_pk_mul_f32 v[98:99], v[102:103], v[98:99]
	s_nop 0
	v_cvt_pk_bf16_f32 v107, v98, v99
	global_store_dwordx4 v[96:97], v[104:107], off
	v_mul_f32_e32 v96, 0xbfb8aa3b, v88
	v_mul_f32_e32 v97, 0xbfb8aa3b, v89
	v_exp_f32_e32 v96, v96
	v_exp_f32_e32 v97, v97
	v_or_b32_e32 v98, 32, v141
	v_add_f32_e32 v96, 1.0, v96
	v_add_f32_e32 v97, 1.0, v97
	v_rcp_f32_e32 v96, v96
	v_rcp_f32_e32 v97, v97
	s_nop 0
	v_pk_mul_f32 v[88:89], v[88:89], v[96:97]
	s_nop 0
	v_pk_mul_f32 v[88:89], v[92:93], v[88:89]
	v_mul_f32_e32 v92, 0xbfb8aa3b, v90
	v_mul_f32_e32 v93, 0xbfb8aa3b, v91
	v_exp_f32_e32 v92, v92
	v_exp_f32_e32 v93, v93
	v_cvt_pk_bf16_f32 v88, v88, v89
	v_add_f32_e32 v92, 1.0, v92
	v_add_f32_e32 v93, 1.0, v93
	v_rcp_f32_e32 v92, v92
	v_rcp_f32_e32 v93, v93
	s_nop 0
	v_pk_mul_f32 v[90:91], v[90:91], v[92:93]
	s_nop 0
	v_pk_mul_f32 v[90:91], v[94:95], v[90:91]
	s_nop 0
	v_cvt_pk_bf16_f32 v89, v90, v91
	v_mul_f32_e32 v90, 0xbfb8aa3b, v80
	v_mul_f32_e32 v91, 0xbfb8aa3b, v81
	v_exp_f32_e32 v90, v90
	v_exp_f32_e32 v91, v91
	v_add_f32_e32 v90, 1.0, v90
	v_add_f32_e32 v91, 1.0, v91
	v_rcp_f32_e32 v90, v90
	v_rcp_f32_e32 v91, v91
	s_nop 0
	v_pk_mul_f32 v[80:81], v[80:81], v[90:91]
	s_nop 0
	v_pk_mul_f32 v[80:81], v[84:85], v[80:81]
	v_mul_f32_e32 v84, 0xbfb8aa3b, v82
	v_mul_f32_e32 v85, 0xbfb8aa3b, v83
	v_exp_f32_e32 v84, v84
	v_exp_f32_e32 v85, v85
	v_cvt_pk_bf16_f32 v90, v80, v81
	v_mad_i64_i32 v[80:81], s[0:1], v98, s2, v[136:137]
	v_add_f32_e32 v84, 1.0, v84
	v_add_f32_e32 v85, 1.0, v85
	v_rcp_f32_e32 v84, v84
	v_rcp_f32_e32 v85, v85
	s_nop 0
	v_pk_mul_f32 v[82:83], v[82:83], v[84:85]
	s_nop 0
	v_pk_mul_f32 v[82:83], v[86:87], v[82:83]
	s_nop 0
	v_cvt_pk_bf16_f32 v91, v82, v83
	global_store_dwordx4 v[80:81], v[88:91], off
	v_mul_f32_e32 v80, 0xbfb8aa3b, v72
	v_mul_f32_e32 v81, 0xbfb8aa3b, v73
	v_exp_f32_e32 v80, v80
	v_exp_f32_e32 v81, v81
	v_or_b32_e32 v82, 48, v141
	v_add_f32_e32 v80, 1.0, v80
	v_add_f32_e32 v81, 1.0, v81
	v_rcp_f32_e32 v80, v80
	v_rcp_f32_e32 v81, v81
	s_nop 0
	v_pk_mul_f32 v[72:73], v[72:73], v[80:81]
	s_nop 0
	v_pk_mul_f32 v[72:73], v[76:77], v[72:73]
	v_mul_f32_e32 v76, 0xbfb8aa3b, v74
	v_mul_f32_e32 v77, 0xbfb8aa3b, v75
	v_exp_f32_e32 v76, v76
	v_exp_f32_e32 v77, v77
	v_cvt_pk_bf16_f32 v72, v72, v73
	v_add_f32_e32 v76, 1.0, v76
	v_add_f32_e32 v77, 1.0, v77
	v_rcp_f32_e32 v76, v76
	v_rcp_f32_e32 v77, v77
	s_nop 0
	v_pk_mul_f32 v[74:75], v[74:75], v[76:77]
	s_nop 0
	v_pk_mul_f32 v[74:75], v[78:79], v[74:75]
	s_nop 0
	v_cvt_pk_bf16_f32 v73, v74, v75
	v_mul_f32_e32 v74, 0xbfb8aa3b, v64
	v_mul_f32_e32 v75, 0xbfb8aa3b, v65
	v_exp_f32_e32 v74, v74
	v_exp_f32_e32 v75, v75
	v_add_f32_e32 v74, 1.0, v74
	v_add_f32_e32 v75, 1.0, v75
	v_rcp_f32_e32 v74, v74
	v_rcp_f32_e32 v75, v75
	s_nop 0
	v_pk_mul_f32 v[64:65], v[64:65], v[74:75]
	s_nop 0
	v_pk_mul_f32 v[64:65], v[68:69], v[64:65]
	v_mul_f32_e32 v68, 0xbfb8aa3b, v66
	v_mul_f32_e32 v69, 0xbfb8aa3b, v67
	v_exp_f32_e32 v68, v68
	v_exp_f32_e32 v69, v69
	v_cvt_pk_bf16_f32 v74, v64, v65
	v_mad_i64_i32 v[64:65], s[0:1], v82, s2, v[136:137]
	v_add_f32_e32 v68, 1.0, v68
	v_add_f32_e32 v69, 1.0, v69
	v_rcp_f32_e32 v68, v68
	v_rcp_f32_e32 v69, v69
	s_nop 0
	v_pk_mul_f32 v[66:67], v[66:67], v[68:69]
	s_nop 0
	v_pk_mul_f32 v[66:67], v[70:71], v[66:67]
	s_nop 0
	v_cvt_pk_bf16_f32 v75, v66, v67
	global_store_dwordx4 v[64:65], v[72:75], off
	v_mul_f32_e32 v64, 0xbfb8aa3b, v56
	v_mul_f32_e32 v65, 0xbfb8aa3b, v57
	v_exp_f32_e32 v64, v64
	v_exp_f32_e32 v65, v65
	v_add_u32_e32 v66, 0x80, v141
	v_add_f32_e32 v64, 1.0, v64
	v_add_f32_e32 v65, 1.0, v65
	v_rcp_f32_e32 v64, v64
	v_rcp_f32_e32 v65, v65
	s_nop 0
	v_pk_mul_f32 v[56:57], v[56:57], v[64:65]
	s_nop 0
	v_pk_mul_f32 v[56:57], v[60:61], v[56:57]
	v_mul_f32_e32 v60, 0xbfb8aa3b, v58
	v_mul_f32_e32 v61, 0xbfb8aa3b, v59
	v_exp_f32_e32 v60, v60
	v_exp_f32_e32 v61, v61
	v_cvt_pk_bf16_f32 v56, v56, v57
	v_add_f32_e32 v60, 1.0, v60
	v_add_f32_e32 v61, 1.0, v61
	v_rcp_f32_e32 v60, v60
	v_rcp_f32_e32 v61, v61
	s_nop 0
	v_pk_mul_f32 v[58:59], v[58:59], v[60:61]
	s_nop 0
	v_pk_mul_f32 v[58:59], v[62:63], v[58:59]
	s_nop 0
	v_cvt_pk_bf16_f32 v57, v58, v59
	v_mul_f32_e32 v58, 0xbfb8aa3b, v48
	v_mul_f32_e32 v59, 0xbfb8aa3b, v49
	v_exp_f32_e32 v58, v58
	v_exp_f32_e32 v59, v59
	v_add_f32_e32 v58, 1.0, v58
	v_add_f32_e32 v59, 1.0, v59
	v_rcp_f32_e32 v58, v58
	v_rcp_f32_e32 v59, v59
	s_nop 0
	v_pk_mul_f32 v[48:49], v[48:49], v[58:59]
	s_nop 0
	v_pk_mul_f32 v[48:49], v[52:53], v[48:49]
	v_mul_f32_e32 v52, 0xbfb8aa3b, v50
	v_mul_f32_e32 v53, 0xbfb8aa3b, v51
	v_exp_f32_e32 v52, v52
	v_exp_f32_e32 v53, v53
	v_cvt_pk_bf16_f32 v58, v48, v49
	v_mad_i64_i32 v[48:49], s[0:1], v66, s2, v[136:137]
	v_add_f32_e32 v52, 1.0, v52
	v_add_f32_e32 v53, 1.0, v53
	v_rcp_f32_e32 v52, v52
	v_rcp_f32_e32 v53, v53
	s_nop 0
	v_pk_mul_f32 v[50:51], v[50:51], v[52:53]
	s_nop 0
	v_pk_mul_f32 v[50:51], v[54:55], v[50:51]
	s_nop 0
	v_cvt_pk_bf16_f32 v59, v50, v51
	global_store_dwordx4 v[48:49], v[56:59], off
	v_mul_f32_e32 v48, 0xbfb8aa3b, v40
	v_mul_f32_e32 v49, 0xbfb8aa3b, v41
	v_exp_f32_e32 v48, v48
	v_exp_f32_e32 v49, v49
	v_add_u32_e32 v50, 0x90, v141
	v_add_f32_e32 v48, 1.0, v48
	v_add_f32_e32 v49, 1.0, v49
	v_rcp_f32_e32 v48, v48
	v_rcp_f32_e32 v49, v49
	s_nop 0
	v_pk_mul_f32 v[40:41], v[40:41], v[48:49]
	s_nop 0
	v_pk_mul_f32 v[40:41], v[44:45], v[40:41]
	v_mul_f32_e32 v44, 0xbfb8aa3b, v42
	v_mul_f32_e32 v45, 0xbfb8aa3b, v43
	v_exp_f32_e32 v44, v44
	v_exp_f32_e32 v45, v45
	v_cvt_pk_bf16_f32 v40, v40, v41
	v_add_f32_e32 v44, 1.0, v44
	v_add_f32_e32 v45, 1.0, v45
	v_rcp_f32_e32 v44, v44
	v_rcp_f32_e32 v45, v45
	s_nop 0
	v_pk_mul_f32 v[42:43], v[42:43], v[44:45]
	s_nop 0
	v_pk_mul_f32 v[42:43], v[46:47], v[42:43]
	s_nop 0
	v_cvt_pk_bf16_f32 v41, v42, v43
	v_mul_f32_e32 v42, 0xbfb8aa3b, v32
	v_mul_f32_e32 v43, 0xbfb8aa3b, v33
	v_exp_f32_e32 v42, v42
	v_exp_f32_e32 v43, v43
	v_add_f32_e32 v42, 1.0, v42
	v_add_f32_e32 v43, 1.0, v43
	v_rcp_f32_e32 v42, v42
	v_rcp_f32_e32 v43, v43
	s_nop 0
	v_pk_mul_f32 v[32:33], v[32:33], v[42:43]
	s_nop 0
	v_pk_mul_f32 v[32:33], v[36:37], v[32:33]
	v_mul_f32_e32 v36, 0xbfb8aa3b, v34
	v_mul_f32_e32 v37, 0xbfb8aa3b, v35
	v_exp_f32_e32 v36, v36
	v_exp_f32_e32 v37, v37
	v_cvt_pk_bf16_f32 v42, v32, v33
	v_mad_i64_i32 v[32:33], s[0:1], v50, s2, v[136:137]
	v_add_f32_e32 v36, 1.0, v36
	v_add_f32_e32 v37, 1.0, v37
	v_rcp_f32_e32 v36, v36
	v_rcp_f32_e32 v37, v37
	s_nop 0
	v_pk_mul_f32 v[34:35], v[34:35], v[36:37]
	s_nop 0
	v_pk_mul_f32 v[34:35], v[38:39], v[34:35]
	s_nop 0
	v_cvt_pk_bf16_f32 v43, v34, v35
	global_store_dwordx4 v[32:33], v[40:43], off
	v_mul_f32_e32 v32, 0xbfb8aa3b, v24
	v_mul_f32_e32 v33, 0xbfb8aa3b, v25
	v_exp_f32_e32 v32, v32
	v_exp_f32_e32 v33, v33
	v_add_u32_e32 v34, 0xa0, v141
	v_add_f32_e32 v32, 1.0, v32
	v_add_f32_e32 v33, 1.0, v33
	v_rcp_f32_e32 v32, v32
	v_rcp_f32_e32 v33, v33
	s_nop 0
	v_pk_mul_f32 v[24:25], v[24:25], v[32:33]
	s_nop 0
	v_pk_mul_f32 v[24:25], v[28:29], v[24:25]
	v_mul_f32_e32 v28, 0xbfb8aa3b, v26
	v_mul_f32_e32 v29, 0xbfb8aa3b, v27
	v_exp_f32_e32 v28, v28
	v_exp_f32_e32 v29, v29
	v_cvt_pk_bf16_f32 v24, v24, v25
	v_add_f32_e32 v28, 1.0, v28
	v_add_f32_e32 v29, 1.0, v29
	v_rcp_f32_e32 v28, v28
	v_rcp_f32_e32 v29, v29
	s_nop 0
	v_pk_mul_f32 v[26:27], v[26:27], v[28:29]
	s_nop 0
	v_pk_mul_f32 v[26:27], v[30:31], v[26:27]
	s_nop 0
	v_cvt_pk_bf16_f32 v25, v26, v27
	v_mul_f32_e32 v26, 0xbfb8aa3b, v16
	v_mul_f32_e32 v27, 0xbfb8aa3b, v17
	v_exp_f32_e32 v26, v26
	v_exp_f32_e32 v27, v27
	v_add_f32_e32 v26, 1.0, v26
	v_add_f32_e32 v27, 1.0, v27
	v_rcp_f32_e32 v26, v26
	v_rcp_f32_e32 v27, v27
	s_nop 0
	v_pk_mul_f32 v[16:17], v[16:17], v[26:27]
	s_nop 0
	v_pk_mul_f32 v[16:17], v[20:21], v[16:17]
	v_mul_f32_e32 v20, 0xbfb8aa3b, v18
	v_mul_f32_e32 v21, 0xbfb8aa3b, v19
	v_exp_f32_e32 v20, v20
	v_exp_f32_e32 v21, v21
	v_cvt_pk_bf16_f32 v26, v16, v17
	v_mad_i64_i32 v[16:17], s[0:1], v34, s2, v[136:137]
	v_add_f32_e32 v20, 1.0, v20
	v_add_f32_e32 v21, 1.0, v21
	v_rcp_f32_e32 v20, v20
	v_rcp_f32_e32 v21, v21
	s_nop 0
	v_pk_mul_f32 v[18:19], v[18:19], v[20:21]
	s_nop 0
	v_pk_mul_f32 v[18:19], v[22:23], v[18:19]
	s_nop 0
	v_cvt_pk_bf16_f32 v27, v18, v19
	global_store_dwordx4 v[16:17], v[24:27], off
	v_mul_f32_e32 v16, 0xbfb8aa3b, v8
	v_mul_f32_e32 v17, 0xbfb8aa3b, v9
	v_exp_f32_e32 v16, v16
	v_exp_f32_e32 v17, v17
	v_add_u32_e32 v18, 0xb0, v141
	v_add_f32_e32 v16, 1.0, v16
	v_add_f32_e32 v17, 1.0, v17
	v_rcp_f32_e32 v16, v16
	v_rcp_f32_e32 v17, v17
	s_nop 0
	v_pk_mul_f32 v[8:9], v[8:9], v[16:17]
	s_nop 0
	v_pk_mul_f32 v[8:9], v[12:13], v[8:9]
	v_mul_f32_e32 v12, 0xbfb8aa3b, v10
	v_mul_f32_e32 v13, 0xbfb8aa3b, v11
	v_exp_f32_e32 v12, v12
	v_exp_f32_e32 v13, v13
	v_cvt_pk_bf16_f32 v8, v8, v9
	v_add_f32_e32 v12, 1.0, v12
	v_add_f32_e32 v13, 1.0, v13
	v_rcp_f32_e32 v12, v12
	v_rcp_f32_e32 v13, v13
	s_nop 0
	v_pk_mul_f32 v[10:11], v[10:11], v[12:13]
	s_nop 0
	v_pk_mul_f32 v[10:11], v[14:15], v[10:11]
	s_nop 0
	v_cvt_pk_bf16_f32 v9, v10, v11
	v_mul_f32_e32 v10, 0xbfb8aa3b, v0
	v_mul_f32_e32 v11, 0xbfb8aa3b, v1
	v_exp_f32_e32 v10, v10
	v_exp_f32_e32 v11, v11
	v_add_f32_e32 v10, 1.0, v10
	v_add_f32_e32 v11, 1.0, v11
	v_rcp_f32_e32 v10, v10
	v_rcp_f32_e32 v11, v11
	s_nop 0
	v_pk_mul_f32 v[0:1], v[0:1], v[10:11]
	s_nop 0
	v_pk_mul_f32 v[0:1], v[4:5], v[0:1]
	v_mul_f32_e32 v4, 0xbfb8aa3b, v2
	v_mul_f32_e32 v5, 0xbfb8aa3b, v3
	v_exp_f32_e32 v4, v4
	v_exp_f32_e32 v5, v5
	v_cvt_pk_bf16_f32 v10, v0, v1
	v_mad_i64_i32 v[0:1], s[0:1], v18, s2, v[136:137]
	v_add_f32_e32 v4, 1.0, v4
	v_add_f32_e32 v5, 1.0, v5
	v_rcp_f32_e32 v4, v4
	v_rcp_f32_e32 v5, v5
	s_mov_b64 s[2:3], -1
	v_pk_mul_f32 v[2:3], v[2:3], v[4:5]
	s_nop 0
	v_pk_mul_f32 v[2:3], v[6:7], v[2:3]
	s_nop 0
	v_cvt_pk_bf16_f32 v11, v2, v3
	global_store_dwordx4 v[0:1], v[8:11], off
	s_cbranch_vccz .LBB0_316
; __device__ __forceinline__ f32x4 zero4() { float z = 0.f; asm volatile("" : "+v"(z)); return (f32x4){z, z, z, z}; }
; __device__ __forceinline__ void gemm_phase(const Params& p, int l, const bf16_t* __restrict__ A, const bf16_t* __restrict__ Bt, int M, int N, int K,
;                            int epi, bf16_t* __restrict__ outp, char* smem, int wvi) {
;     ...
;       if (!has_next) break;
; #pragma unroll
;       for (int a = 0; a < 2; ++a)
; #pragma unroll
;         for (int b = 0; b < 2; ++b)
; #pragma unroll
;           for (int m = 0; m < 4; ++m)
; #pragma unroll
;             for (int n = 0; n < 2; ++n) acc[a][b][m][n] = zero4();
;       Lw = Ln; pm = npm; pn = npn; cA = nA; cB = nB;
	v_mov_b32_e32 v120, v177
	v_mov_b32_e32 v124, v177
	v_mov_b32_e32 v104, v177
	v_mov_b32_e32 v108, v177
	v_mov_b32_e32 v88, v177
	v_mov_b32_e32 v92, v177
	v_mov_b32_e32 v72, v177
	v_mov_b32_e32 v76, v177
	v_mov_b32_e32 v112, v177
	v_mov_b32_e32 v116, v177
	v_mov_b32_e32 v96, v177
	v_mov_b32_e32 v100, v177
	v_mov_b32_e32 v80, v177
	v_mov_b32_e32 v84, v177
	v_mov_b32_e32 v64, v177
	v_mov_b32_e32 v68, v177
	v_mov_b32_e32 v56, v177
	v_mov_b32_e32 v60, v177
	v_mov_b32_e32 v40, v177
	v_mov_b32_e32 v44, v177
	v_mov_b32_e32 v24, v177
	v_mov_b32_e32 v28, v177
	v_mov_b32_e32 v8, v177
	v_mov_b32_e32 v12, v177
	v_mov_b32_e32 v48, v177
	v_mov_b32_e32 v52, v177
	v_mov_b32_e32 v32, v177
	v_mov_b32_e32 v36, v177
	v_mov_b32_e32 v16, v177
	v_mov_b32_e32 v20, v177
	v_mov_b32_e32 v0, v177
	v_mov_b32_e32 v4, v177
	s_nop 0
	v_mov_b32_e32 v121, v120
	v_mov_b32_e32 v122, v120
	v_mov_b32_e32 v123, v120
	v_mov_b32_e32 v125, v124
	v_mov_b32_e32 v126, v124
	v_mov_b32_e32 v127, v124
	v_mov_b32_e32 v105, v104
	v_mov_b32_e32 v106, v104
	v_mov_b32_e32 v107, v104
	v_mov_b32_e32 v109, v108
	v_mov_b32_e32 v110, v108
	v_mov_b32_e32 v111, v108
	v_mov_b32_e32 v89, v88
	v_mov_b32_e32 v90, v88
	v_mov_b32_e32 v91, v88
	v_mov_b32_e32 v93, v92
	v_mov_b32_e32 v94, v92
	v_mov_b32_e32 v95, v92
	s_nop 0
	v_mov_b32_e32 v73, v72
	v_mov_b32_e32 v74, v72
	v_mov_b32_e32 v75, v72
	v_mov_b32_e32 v77, v76
	v_mov_b32_e32 v78, v76
	v_mov_b32_e32 v79, v76
	v_mov_b32_e32 v113, v112
	v_mov_b32_e32 v114, v112
	v_mov_b32_e32 v115, v112
	v_mov_b32_e32 v117, v116
	v_mov_b32_e32 v118, v116
	v_mov_b32_e32 v119, v116
	v_mov_b32_e32 v97, v96
	v_mov_b32_e32 v98, v96
	v_mov_b32_e32 v99, v96
	v_mov_b32_e32 v101, v100
	v_mov_b32_e32 v102, v100
	v_mov_b32_e32 v103, v100
	s_nop 0
	v_mov_b32_e32 v81, v80
	v_mov_b32_e32 v82, v80
	v_mov_b32_e32 v83, v80
	v_mov_b32_e32 v85, v84
	v_mov_b32_e32 v86, v84
	v_mov_b32_e32 v87, v84
	v_mov_b32_e32 v65, v64
	v_mov_b32_e32 v66, v64
	v_mov_b32_e32 v67, v64
	v_mov_b32_e32 v69, v68
	v_mov_b32_e32 v70, v68
	v_mov_b32_e32 v71, v68
	v_mov_b32_e32 v57, v56
	v_mov_b32_e32 v58, v56
	v_mov_b32_e32 v59, v56
	v_mov_b32_e32 v61, v60
	v_mov_b32_e32 v62, v60
	v_mov_b32_e32 v63, v60
	s_nop 0
	v_mov_b32_e32 v41, v40
	v_mov_b32_e32 v42, v40
	v_mov_b32_e32 v43, v40
	v_mov_b32_e32 v45, v44
	v_mov_b32_e32 v46, v44
	v_mov_b32_e32 v47, v44
	v_mov_b32_e32 v25, v24
	v_mov_b32_e32 v26, v24
	v_mov_b32_e32 v27, v24
	v_mov_b32_e32 v29, v28
	v_mov_b32_e32 v30, v28
	v_mov_b32_e32 v31, v28
	v_mov_b32_e32 v9, v8
	v_mov_b32_e32 v10, v8
	v_mov_b32_e32 v11, v8
	v_mov_b32_e32 v13, v12
	v_mov_b32_e32 v14, v12
	v_mov_b32_e32 v15, v12
	s_nop 0
	v_mov_b32_e32 v49, v48
	v_mov_b32_e32 v50, v48
	v_mov_b32_e32 v51, v48
	v_mov_b32_e32 v53, v52
	v_mov_b32_e32 v54, v52
	v_mov_b32_e32 v55, v52
	v_mov_b32_e32 v33, v32
	v_mov_b32_e32 v34, v32
	v_mov_b32_e32 v35, v32
	v_mov_b32_e32 v37, v36
	v_mov_b32_e32 v38, v36
	v_mov_b32_e32 v39, v36
	v_mov_b32_e32 v17, v16
	v_mov_b32_e32 v18, v16
	v_mov_b32_e32 v19, v16
	v_mov_b32_e32 v21, v20
	v_mov_b32_e32 v22, v20
	v_mov_b32_e32 v23, v20
	s_mov_b64 s[2:3], 0
	v_mov_b32_e32 v1, v0
	v_mov_b32_e32 v2, v0
	v_mov_b32_e32 v3, v0
	v_mov_b32_e32 v5, v4
	v_mov_b32_e32 v6, v4
	v_mov_b32_e32 v7, v4
	s_branch .LBB0_316

; #define G_STAGE(bufoff, gbase) do { _Pragma("unroll") for (int _i = 0; _i < 2; ++_i) \
;     __builtin_amdgcn_global_load_lds((const unsigned*)((const char*)(gbase) + voff[_i]), (GLAS unsigned*)(lds + (bufoff) + ldsw + _i * 8192), 16, 0, 0); } while (0)
; #define G_LDA(dst, b, h) do { _Pragma("unroll") for (int m = 0; m < 4; ++m) _Pragma("unroll") for (int k = 0; k < 2; ++k) \
;     dst[m][k] = *(const GLAS bf16x8*)(lds + G_SA(b, h) + aoff + m * 2048 + k * 1024); } while (0)
; #define G_LDB(dst, b, h) do { _Pragma("unroll") for (int n = 0; n < 2; ++n) _Pragma("unroll") for (int k = 0; k < 2; ++k) \
;     dst[n][k] = *(const GLAS bf16x8*)(lds + G_SB(b, h) + boff + n * 2048 + k * 1024); } while (0)
; #define G_MMA(ai, bj, At_, Bt_) do { __builtin_amdgcn_s_setprio(1); \
;     _Pragma("unroll") for (int m = 0; m < 4; ++m) _Pragma("unroll") for (int n = 0; n < 2; ++n) _Pragma("unroll") for (int k = 0; k < 2; ++k) \
;       acc[ai][bj][m][n] = __builtin_amdgcn_mfma_f32_16x16x32_bf16(Bt_[n][k], At_[m][k], acc[ai][bj][m][n], 0, 0, 0); \
;     __builtin_amdgcn_s_setprio(0); } while (0)
; #define G_WAIT_L(n) asm volatile("s_waitcnt lgkmcnt(" #n ")" ::: "memory")
; #define G_BAR __builtin_amdgcn_s_barrier()
; #define G_SCHED __builtin_amdgcn_sched_barrier(0)
; __device__ __forceinline__ void gemm_phase(const Params& p, int l, const bf16_t* __restrict__ A, const bf16_t* __restrict__ Bt, int M, int N, int K,
;                            int epi, bf16_t* __restrict__ outp, char* smem, int wvi) {
;     ...
;       for (int t = 0; t < nt; t += 2) {
;         const bool lastt = (t == nt - 2);
;         const char* a1 = cA + (size_t)(t + 1) * kstep;
;         const char* a2 = lastt ? nA : cA + (size_t)(t + 2) * kstep; const char* b2 = lastt ? nB : cB + (size_t)(t + 2) * kstep;
;         const char* a3 = a2 + kstep; const char* b3 = b2 + kstep;
;         G_LDB(B0, 0, 0); G_SCHED; G_LDA(At, 0, 0); G_STAGE(G_SA(1, 1), a1 + hstep);
;         G_WAIT_L(8); G_BAR; G_WAIT_L(0); G_MMA(0, 0, At, B0); G_BAR; G_SCHED;
;         G_LDB(B1, 0, 1); G_STAGE(G_SB(0, 0), b2);
;         G_BAR; G_WAIT_L(0); G_MMA(0, 1, At, B1); G_BAR;
;         G_LDA(At, 0, 1); G_STAGE(G_SA(0, 0), a2);
;         G_BAR; G_WAIT_L(0); G_MMA(1, 0, At, B0); G_BAR; G_SCHED;
.LBB0_373:
	s_add_u32 s2, s16, 0x100
	s_addc_u32 s3, s17, 0
	s_add_i32 s34, 0, 0x10000
	s_cmp_eq_u32 s55, 12
	s_cselect_b32 s29, s11, s3
	s_cselect_b32 s28, s10, s2
	s_cselect_b32 s13, s7, s53
	s_cselect_b32 s12, s5, s31
	v_lshl_add_u64 v[190:191], s[16:17], 0, v[132:133]
	s_add_i32 m0, s9, 0xc000
	ds_read_b128 v[156:159], v138
	ds_read_b128 v[160:163], v138 offset:1024
	ds_read_b128 v[164:167], v138 offset:2048
	ds_read_b128 v[168:171], v138 offset:3072
	ds_read_b128 v[172:175], v138 offset:4096
	ds_read_b128 v[182:185], v138 offset:5120
	ds_read_b128 v[186:189], v138 offset:6144
	ds_read_b128 v[214:217], v138 offset:7168
	global_load_lds_dwordx4 v[190:191], off
	v_lshl_add_u64 v[190:191], s[16:17], 0, v[134:135]
	s_add_i32 m0, s9, 0xe000
	s_nop 0
	global_load_lds_dwordx4 v[190:191], off
	s_waitcnt lgkmcnt(8)
	s_barrier
	s_waitcnt lgkmcnt(0)
	s_waitcnt lgkmcnt(0)
	v_mfma_f32_16x16x32_bf16 v[20:23], v[140:143], v[156:159], v[20:23]
	v_mfma_f32_16x16x32_bf16 v[28:31], v[148:151], v[156:159], v[28:31]
	v_mfma_f32_16x16x32_bf16 v[12:15], v[140:143], v[164:167], v[12:15]
	v_mfma_f32_16x16x32_bf16 v[24:27], v[148:151], v[164:167], v[24:27]
	v_mfma_f32_16x16x32_bf16 v[4:7], v[140:143], v[172:175], v[4:7]
	v_mfma_f32_16x16x32_bf16 v[16:19], v[148:151], v[172:175], v[16:19]
	v_mfma_f32_16x16x32_bf16 v[0:3], v[140:143], v[186:189], v[0:3]
	v_mfma_f32_16x16x32_bf16 v[8:11], v[148:151], v[186:189], v[8:11]
	v_mfma_f32_16x16x32_bf16 v[20:23], v[144:147], v[160:163], v[20:23]
	v_mfma_f32_16x16x32_bf16 v[28:31], v[152:155], v[160:163], v[28:31]
	v_mfma_f32_16x16x32_bf16 v[12:15], v[144:147], v[168:171], v[12:15]
	v_mfma_f32_16x16x32_bf16 v[24:27], v[152:155], v[168:171], v[24:27]
	v_mfma_f32_16x16x32_bf16 v[4:7], v[144:147], v[182:185], v[4:7]
	v_mfma_f32_16x16x32_bf16 v[16:19], v[152:155], v[182:185], v[16:19]
	v_mfma_f32_16x16x32_bf16 v[0:3], v[144:147], v[214:217], v[0:3]
	v_mfma_f32_16x16x32_bf16 v[8:11], v[152:155], v[214:217], v[8:11]
	s_barrier
	s_add_i32 s35, 0, 0x14000
	s_add_i32 s16, s34, s58
	v_add_u32_e32 v139, s35, v137
	v_lshl_add_u64 v[190:191], s[12:13], 0, v[176:177]
	s_mov_b32 m0, s16
	ds_read_b128 v[218:221], v139
	ds_read_b128 v[222:225], v139 offset:1024
	ds_read_b128 v[226:229], v139 offset:2048
	ds_read_b128 v[230:233], v139 offset:3072
	global_load_lds_dwordx4 v[190:191], off
	v_lshl_add_u64 v[234:235], s[12:13], 0, v[128:129]
	s_add_i32 m0, s16, 0x2000
	s_nop 0
	global_load_lds_dwordx4 v[234:235], off
	s_barrier
	s_waitcnt lgkmcnt(0)
	s_waitcnt lgkmcnt(0)
	v_mfma_f32_16x16x32_bf16 v[80:83], v[218:221], v[156:159], v[80:83]
	v_mfma_f32_16x16x32_bf16 v[92:95], v[226:229], v[156:159], v[92:95]
	v_mfma_f32_16x16x32_bf16 v[64:67], v[218:221], v[164:167], v[64:67]
	v_mfma_f32_16x16x32_bf16 v[84:87], v[226:229], v[164:167], v[84:87]
	v_mfma_f32_16x16x32_bf16 v[52:55], v[218:221], v[172:175], v[52:55]
	v_mfma_f32_16x16x32_bf16 v[76:79], v[226:229], v[172:175], v[76:79]
	v_mfma_f32_16x16x32_bf16 v[40:43], v[218:221], v[186:189], v[40:43]
	v_mfma_f32_16x16x32_bf16 v[60:63], v[226:229], v[186:189], v[60:63]
	v_mfma_f32_16x16x32_bf16 v[80:83], v[222:225], v[160:163], v[80:83]
	v_mfma_f32_16x16x32_bf16 v[92:95], v[230:233], v[160:163], v[92:95]
	v_mfma_f32_16x16x32_bf16 v[64:67], v[222:225], v[168:171], v[64:67]
	v_mfma_f32_16x16x32_bf16 v[84:87], v[230:233], v[168:171], v[84:87]
	v_mfma_f32_16x16x32_bf16 v[52:55], v[222:225], v[182:185], v[52:55]
	v_mfma_f32_16x16x32_bf16 v[76:79], v[230:233], v[182:185], v[76:79]
	v_mfma_f32_16x16x32_bf16 v[40:43], v[222:225], v[214:217], v[40:43]
	v_mfma_f32_16x16x32_bf16 v[60:63], v[230:233], v[214:217], v[60:63]
	s_mov_b32 m0, s9
	v_lshl_add_u64 v[236:237], s[28:29], 0, v[176:177]
	s_barrier
	ds_read_b128 v[156:159], v138 offset:16384
	ds_read_b128 v[160:163], v138 offset:17408
	ds_read_b128 v[164:167], v138 offset:18432
	ds_read_b128 v[168:171], v138 offset:19456
	ds_read_b128 v[172:175], v138 offset:20480
	ds_read_b128 v[182:185], v138 offset:21504
	ds_read_b128 v[186:189], v138 offset:22528
	ds_read_b128 v[214:217], v138 offset:23552
	global_load_lds_dwordx4 v[236:237], off
	v_lshl_add_u64 v[238:239], s[28:29], 0, v[128:129]
	s_mov_b32 m0, s24
	s_nop 0
	global_load_lds_dwordx4 v[238:239], off
	s_waitcnt vmcnt(10)
	s_barrier
	s_waitcnt lgkmcnt(0)
	s_waitcnt lgkmcnt(0)
	v_mfma_f32_16x16x32_bf16 v[68:71], v[140:143], v[156:159], v[68:71]
	v_mfma_f32_16x16x32_bf16 v[88:91], v[148:151], v[156:159], v[88:91]
	v_mfma_f32_16x16x32_bf16 v[48:51], v[140:143], v[164:167], v[48:51]
	v_mfma_f32_16x16x32_bf16 v[72:75], v[148:151], v[164:167], v[72:75]
	v_mfma_f32_16x16x32_bf16 v[36:39], v[140:143], v[172:175], v[36:39]
	v_mfma_f32_16x16x32_bf16 v[56:59], v[148:151], v[172:175], v[56:59]
	v_mfma_f32_16x16x32_bf16 v[32:35], v[140:143], v[186:189], v[32:35]
	v_mfma_f32_16x16x32_bf16 v[44:47], v[148:151], v[186:189], v[44:47]
	v_mfma_f32_16x16x32_bf16 v[68:71], v[144:147], v[160:163], v[68:71]
	v_mfma_f32_16x16x32_bf16 v[88:91], v[152:155], v[160:163], v[88:91]
	v_mfma_f32_16x16x32_bf16 v[48:51], v[144:147], v[168:171], v[48:51]
	v_mfma_f32_16x16x32_bf16 v[72:75], v[152:155], v[168:171], v[72:75]
	v_mfma_f32_16x16x32_bf16 v[36:39], v[144:147], v[182:185], v[36:39]
	v_mfma_f32_16x16x32_bf16 v[56:59], v[152:155], v[182:185], v[56:59]
	v_mfma_f32_16x16x32_bf16 v[32:35], v[144:147], v[214:217], v[32:35]
	v_mfma_f32_16x16x32_bf16 v[44:47], v[152:155], v[214:217], v[44:47]
	s_barrier
; #define G_STAGE(bufoff, gbase) do { _Pragma("unroll") for (int _i = 0; _i < 2; ++_i) \
;     __builtin_amdgcn_global_load_lds((const unsigned*)((const char*)(gbase) + voff[_i]), (GLAS unsigned*)(lds + (bufoff) + ldsw + _i * 8192), 16, 0, 0); } while (0)
; #define G_LDA(dst, b, h) do { _Pragma("unroll") for (int m = 0; m < 4; ++m) _Pragma("unroll") for (int k = 0; k < 2; ++k) \
;     dst[m][k] = *(const GLAS bf16x8*)(lds + G_SA(b, h) + aoff + m * 2048 + k * 1024); } while (0)
; #define G_LDB(dst, b, h) do { _Pragma("unroll") for (int n = 0; n < 2; ++n) _Pragma("unroll") for (int k = 0; k < 2; ++k) \
;     dst[n][k] = *(const GLAS bf16x8*)(lds + G_SB(b, h) + boff + n * 2048 + k * 1024); } while (0)
; #define G_MMA(ai, bj, At_, Bt_) do { __builtin_amdgcn_s_setprio(1); \
;     _Pragma("unroll") for (int m = 0; m < 4; ++m) _Pragma("unroll") for (int n = 0; n < 2; ++n) _Pragma("unroll") for (int k = 0; k < 2; ++k) \
;       acc[ai][bj][m][n] = __builtin_amdgcn_mfma_f32_16x16x32_bf16(Bt_[n][k], At_[m][k], acc[ai][bj][m][n], 0, 0, 0); \
;     __builtin_amdgcn_s_setprio(0); } while (0)
; #define G_WAIT_V(n) asm volatile("s_waitcnt vmcnt(" #n ")" ::: "memory")
; #define G_WAIT_L(n) asm volatile("s_waitcnt lgkmcnt(" #n ")" ::: "memory")
; #define G_BAR __builtin_amdgcn_s_barrier()
; #define G_SCHED __builtin_amdgcn_sched_barrier(0)
; __device__ __forceinline__ void gemm_phase(const Params& p, int l, const bf16_t* __restrict__ A, const bf16_t* __restrict__ Bt, int M, int N, int K,
;                            int epi, bf16_t* __restrict__ outp, char* smem, int wvi) {
;     ...
;         G_STAGE(G_SB(0, 1), b2 + hstep);
;         G_WAIT_V(6); G_BAR; G_MMA(1, 1, At, B1); G_BAR;
;         G_LDB(B0, 1, 0); G_SCHED; G_LDA(At, 1, 0); G_STAGE(G_SA(0, 1), a2 + hstep);
;         G_WAIT_L(8); G_BAR; G_WAIT_L(0); G_MMA(0, 0, At, B0); G_BAR; G_SCHED;
;         G_LDB(B1, 1, 1); G_STAGE(G_SB(1, 0), b3);
;         G_BAR; G_WAIT_L(0); G_MMA(0, 1, At, B1); G_BAR;
;         G_LDA(At, 1, 1); G_STAGE(G_SA(1, 0), a3);
;         G_BAR; G_WAIT_L(0); G_MMA(1, 0, At, B0); G_BAR; G_SCHED;
	s_add_u32 s16, s12, 0x40000
	s_addc_u32 s17, s13, 0
	s_add_i32 s34, s35, s58
	v_lshl_add_u64 v[140:141], s[16:17], 0, v[176:177]
	s_mov_b32 m0, s34
	s_nop 0
	global_load_lds_dwordx4 v[140:141], off
	v_lshl_add_u64 v[140:141], s[16:17], 0, v[128:129]
	s_add_i32 m0, s34, 0x2000
	s_nop 0
	global_load_lds_dwordx4 v[140:141], off
	v_add_u32_e32 v139, 0x18000, v137
	ds_read_b128 v[140:143], v139
	ds_read_b128 v[144:147], v139 offset:1024
	ds_read_b128 v[148:151], v139 offset:2048
	ds_read_b128 v[152:155], v139 offset:3072
	s_waitcnt vmcnt(6)
	s_barrier
	v_mfma_f32_16x16x32_bf16 v[120:123], v[218:221], v[156:159], v[120:123]
	v_mfma_f32_16x16x32_bf16 v[124:127], v[226:229], v[156:159], v[124:127]
	v_mfma_f32_16x16x32_bf16 v[112:115], v[218:221], v[164:167], v[112:115]
	v_mfma_f32_16x16x32_bf16 v[116:119], v[226:229], v[164:167], v[116:119]
	v_mfma_f32_16x16x32_bf16 v[104:107], v[218:221], v[172:175], v[104:107]
	v_mfma_f32_16x16x32_bf16 v[108:111], v[226:229], v[172:175], v[108:111]
	v_mfma_f32_16x16x32_bf16 v[96:99], v[218:221], v[186:189], v[96:99]
	v_mfma_f32_16x16x32_bf16 v[100:103], v[226:229], v[186:189], v[100:103]
	v_mfma_f32_16x16x32_bf16 v[120:123], v[222:225], v[160:163], v[120:123]
	v_mfma_f32_16x16x32_bf16 v[124:127], v[230:233], v[160:163], v[124:127]
	v_mfma_f32_16x16x32_bf16 v[112:115], v[222:225], v[168:171], v[112:115]
	v_mfma_f32_16x16x32_bf16 v[116:119], v[230:233], v[168:171], v[116:119]
	v_mfma_f32_16x16x32_bf16 v[104:107], v[222:225], v[182:185], v[104:107]
	v_mfma_f32_16x16x32_bf16 v[108:111], v[230:233], v[182:185], v[108:111]
	v_mfma_f32_16x16x32_bf16 v[96:99], v[222:225], v[214:217], v[96:99]
	v_mfma_f32_16x16x32_bf16 v[100:103], v[230:233], v[214:217], v[100:103]
	s_add_i32 s34, 0, 0x18000
	s_barrier
	s_add_u32 s16, s28, 0x40000
	s_addc_u32 s17, s29, 0
	s_mov_b32 m0, s25
	v_lshl_add_u64 v[218:219], s[16:17], 0, v[176:177]
	ds_read_b128 v[156:159], v138 offset:32768
	ds_read_b128 v[160:163], v138 offset:33792
	ds_read_b128 v[164:167], v138 offset:34816
	ds_read_b128 v[168:171], v138 offset:35840
	ds_read_b128 v[172:175], v138 offset:36864
	ds_read_b128 v[182:185], v138 offset:37888
	ds_read_b128 v[186:189], v138 offset:38912
	ds_read_b128 v[214:217], v138 offset:39936
	global_load_lds_dwordx4 v[218:219], off
	v_lshl_add_u64 v[218:219], s[16:17], 0, v[128:129]
	s_mov_b32 m0, s26
	s_nop 0
	global_load_lds_dwordx4 v[218:219], off
	s_waitcnt lgkmcnt(8)
	s_barrier
	s_waitcnt lgkmcnt(0)
	s_waitcnt lgkmcnt(0)
	v_mfma_f32_16x16x32_bf16 v[20:23], v[140:143], v[156:159], v[20:23]
	v_mfma_f32_16x16x32_bf16 v[28:31], v[148:151], v[156:159], v[28:31]
	v_mfma_f32_16x16x32_bf16 v[12:15], v[140:143], v[164:167], v[12:15]
	v_mfma_f32_16x16x32_bf16 v[24:27], v[148:151], v[164:167], v[24:27]
	v_mfma_f32_16x16x32_bf16 v[4:7], v[140:143], v[172:175], v[4:7]
	v_mfma_f32_16x16x32_bf16 v[16:19], v[148:151], v[172:175], v[16:19]
	v_mfma_f32_16x16x32_bf16 v[0:3], v[140:143], v[186:189], v[0:3]
	v_mfma_f32_16x16x32_bf16 v[8:11], v[148:151], v[186:189], v[8:11]
	v_mfma_f32_16x16x32_bf16 v[20:23], v[144:147], v[160:163], v[20:23]
	v_mfma_f32_16x16x32_bf16 v[28:31], v[152:155], v[160:163], v[28:31]
	v_mfma_f32_16x16x32_bf16 v[12:15], v[144:147], v[168:171], v[12:15]
	v_mfma_f32_16x16x32_bf16 v[24:27], v[152:155], v[168:171], v[24:27]
	v_mfma_f32_16x16x32_bf16 v[4:7], v[144:147], v[182:185], v[4:7]
	v_mfma_f32_16x16x32_bf16 v[16:19], v[152:155], v[182:185], v[16:19]
	v_mfma_f32_16x16x32_bf16 v[0:3], v[144:147], v[214:217], v[0:3]
	v_mfma_f32_16x16x32_bf16 v[8:11], v[152:155], v[214:217], v[8:11]
	s_barrier
	s_add_i32 s16, 0, 0x1c000
	s_add_i32 s17, s34, s58
	v_add_u32_e32 v139, s16, v137
	v_lshl_add_u64 v[190:191], v[190:191], 0, s[64:65]
	s_mov_b32 m0, s17
	ds_read_b128 v[218:221], v139
	ds_read_b128 v[222:225], v139 offset:1024
	ds_read_b128 v[226:229], v139 offset:2048
	ds_read_b128 v[230:233], v139 offset:3072
	global_load_lds_dwordx4 v[190:191], off
	v_lshl_add_u64 v[190:191], v[234:235], 0, s[64:65]
	s_add_i32 m0, s17, 0x2000
	s_nop 0
	global_load_lds_dwordx4 v[190:191], off
	s_barrier
	s_waitcnt lgkmcnt(0)
	s_waitcnt lgkmcnt(0)
	v_mfma_f32_16x16x32_bf16 v[80:83], v[218:221], v[156:159], v[80:83]
	v_mfma_f32_16x16x32_bf16 v[92:95], v[226:229], v[156:159], v[92:95]
	v_mfma_f32_16x16x32_bf16 v[64:67], v[218:221], v[164:167], v[64:67]
	v_mfma_f32_16x16x32_bf16 v[84:87], v[226:229], v[164:167], v[84:87]
	v_mfma_f32_16x16x32_bf16 v[52:55], v[218:221], v[172:175], v[52:55]
	v_mfma_f32_16x16x32_bf16 v[76:79], v[226:229], v[172:175], v[76:79]
	v_mfma_f32_16x16x32_bf16 v[40:43], v[218:221], v[186:189], v[40:43]
	v_mfma_f32_16x16x32_bf16 v[60:63], v[226:229], v[186:189], v[60:63]
	v_mfma_f32_16x16x32_bf16 v[80:83], v[222:225], v[160:163], v[80:83]
	v_mfma_f32_16x16x32_bf16 v[92:95], v[230:233], v[160:163], v[92:95]
	v_mfma_f32_16x16x32_bf16 v[64:67], v[222:225], v[168:171], v[64:67]
	v_mfma_f32_16x16x32_bf16 v[84:87], v[230:233], v[168:171], v[84:87]
	v_mfma_f32_16x16x32_bf16 v[52:55], v[222:225], v[182:185], v[52:55]
	v_mfma_f32_16x16x32_bf16 v[76:79], v[230:233], v[182:185], v[76:79]
	v_mfma_f32_16x16x32_bf16 v[40:43], v[222:225], v[214:217], v[40:43]
	v_mfma_f32_16x16x32_bf16 v[60:63], v[230:233], v[214:217], v[60:63]
	s_mov_b32 m0, s0
	v_lshl_add_u64 v[190:191], v[236:237], 0, s[64:65]
	s_barrier
	ds_read_b128 v[156:159], v138 offset:49152
	ds_read_b128 v[160:163], v138 offset:50176
	ds_read_b128 v[164:167], v138 offset:51200
	ds_read_b128 v[168:171], v138 offset:52224
	ds_read_b128 v[172:175], v138 offset:53248
	ds_read_b128 v[182:185], v138 offset:54272
	ds_read_b128 v[186:189], v138 offset:55296
	ds_read_b128 v[214:217], v138 offset:56320
	global_load_lds_dwordx4 v[190:191], off
	v_lshl_add_u64 v[190:191], v[238:239], 0, s[64:65]
	s_mov_b32 m0, s1
	s_nop 0
	global_load_lds_dwordx4 v[190:191], off
	s_waitcnt vmcnt(10)
	s_barrier
; __device__ __forceinline__ u32x4 mk4(unsigned a, unsigned b, unsigned c, unsigned d) { return (u32x4){a, b, c, d}; }
; #define G_STAGE(bufoff, gbase) do { _Pragma("unroll") for (int _i = 0; _i < 2; ++_i) \
;     __builtin_amdgcn_global_load_lds((const unsigned*)((const char*)(gbase) + voff[_i]), (GLAS unsigned*)(lds + (bufoff) + ldsw + _i * 8192), 16, 0, 0); } while (0)
; #define G_MMA(ai, bj, At_, Bt_) do { __builtin_amdgcn_s_setprio(1); \
;     _Pragma("unroll") for (int m = 0; m < 4; ++m) _Pragma("unroll") for (int n = 0; n < 2; ++n) _Pragma("unroll") for (int k = 0; k < 2; ++k) \
;       acc[ai][bj][m][n] = __builtin_amdgcn_mfma_f32_16x16x32_bf16(Bt_[n][k], At_[m][k], acc[ai][bj][m][n], 0, 0, 0); \
;     __builtin_amdgcn_s_setprio(0); } while (0)
; #define G_WAIT_V(n) asm volatile("s_waitcnt vmcnt(" #n ")" ::: "memory")
; #define G_BAR __builtin_amdgcn_s_barrier()
; __device__ __forceinline__ void gemm_phase(const Params& p, int l, const bf16_t* __restrict__ A, const bf16_t* __restrict__ Bt, int M, int N, int K,
;                            int epi, bf16_t* __restrict__ outp, char* smem, int wvi) {
;     ...
;         G_STAGE(G_SB(1, 1), b3 + hstep);
;         G_WAIT_V(6); G_BAR; G_MMA(1, 1, At, B1); G_BAR;
;       }
;       const int brow = pm * GBM, bcol = pn * GBM;
;     const int r0 = brow + wr * 64 + fr;
;     if (epi == EPI_PLAIN) {
; #pragma unroll
;       for (int ai = 0; ai < 2; ++ai)
; #pragma unroll
;         for (int m = 0; m < 4; ++m) {
;           bf16_t* rp = outp + (size_t)(r0 + ai * GHALF + m * 16) * N + bcol + wc * 32 + fq * 8;
; #pragma unroll
;           for (int bj = 0; bj < 2; ++bj) {
;             const f32x4 v0 = acc[ai][bj][m][0], v1 = acc[ai][bj][m][1];
;             *reinterpret_cast<u32x4*>(rp + bj * GHALF) = mk4(pk2(v0[0], v0[1]), pk2(v0[2], v0[3]), pk2(v1[0], v1[1]), pk2(v1[2], v1[3]));
;           }
	s_waitcnt lgkmcnt(0)
	s_waitcnt lgkmcnt(0)
	v_mfma_f32_16x16x32_bf16 v[68:71], v[140:143], v[156:159], v[68:71]
	v_mfma_f32_16x16x32_bf16 v[88:91], v[148:151], v[156:159], v[88:91]
	v_mfma_f32_16x16x32_bf16 v[48:51], v[140:143], v[164:167], v[48:51]
	v_mfma_f32_16x16x32_bf16 v[72:75], v[148:151], v[164:167], v[72:75]
	v_mfma_f32_16x16x32_bf16 v[36:39], v[140:143], v[172:175], v[36:39]
	v_mfma_f32_16x16x32_bf16 v[56:59], v[148:151], v[172:175], v[56:59]
	v_mfma_f32_16x16x32_bf16 v[32:35], v[140:143], v[186:189], v[32:35]
	v_mfma_f32_16x16x32_bf16 v[44:47], v[148:151], v[186:189], v[44:47]
	v_mfma_f32_16x16x32_bf16 v[68:71], v[144:147], v[160:163], v[68:71]
	v_mfma_f32_16x16x32_bf16 v[88:91], v[152:155], v[160:163], v[88:91]
	v_mfma_f32_16x16x32_bf16 v[48:51], v[144:147], v[168:171], v[48:51]
	v_mfma_f32_16x16x32_bf16 v[72:75], v[152:155], v[168:171], v[72:75]
	v_mfma_f32_16x16x32_bf16 v[36:39], v[144:147], v[182:185], v[36:39]
	v_mfma_f32_16x16x32_bf16 v[56:59], v[152:155], v[182:185], v[56:59]
	v_mfma_f32_16x16x32_bf16 v[32:35], v[144:147], v[214:217], v[32:35]
	v_mfma_f32_16x16x32_bf16 v[44:47], v[152:155], v[214:217], v[44:47]
	s_barrier
	s_add_u32 s12, s12, 0x40080
	s_addc_u32 s13, s13, 0
	s_add_i32 s16, s16, s58
	v_lshl_add_u64 v[140:141], s[12:13], 0, v[176:177]
	s_mov_b32 m0, s16
	s_nop 0
	global_load_lds_dwordx4 v[140:141], off
	v_lshl_add_u64 v[140:141], s[12:13], 0, v[128:129]
	s_add_i32 m0, s16, 0x2000
	s_nop 0
	global_load_lds_dwordx4 v[140:141], off
	v_add_u32_e32 v139, 0x10000, v137
	ds_read_b128 v[140:143], v139
	ds_read_b128 v[144:147], v139 offset:1024
	ds_read_b128 v[148:151], v139 offset:2048
	ds_read_b128 v[152:155], v139 offset:3072
	s_waitcnt vmcnt(6)
	s_barrier
	v_mfma_f32_16x16x32_bf16 v[120:123], v[218:221], v[156:159], v[120:123]
	v_mfma_f32_16x16x32_bf16 v[124:127], v[226:229], v[156:159], v[124:127]
	v_mfma_f32_16x16x32_bf16 v[112:115], v[218:221], v[164:167], v[112:115]
	v_mfma_f32_16x16x32_bf16 v[116:119], v[226:229], v[164:167], v[116:119]
	v_mfma_f32_16x16x32_bf16 v[104:107], v[218:221], v[172:175], v[104:107]
	v_mfma_f32_16x16x32_bf16 v[108:111], v[226:229], v[172:175], v[108:111]
	v_mfma_f32_16x16x32_bf16 v[96:99], v[218:221], v[186:189], v[96:99]
	v_mfma_f32_16x16x32_bf16 v[100:103], v[226:229], v[186:189], v[100:103]
	v_mfma_f32_16x16x32_bf16 v[120:123], v[222:225], v[160:163], v[120:123]
	v_mfma_f32_16x16x32_bf16 v[124:127], v[230:233], v[160:163], v[124:127]
	v_mfma_f32_16x16x32_bf16 v[112:115], v[222:225], v[168:171], v[112:115]
	v_mfma_f32_16x16x32_bf16 v[116:119], v[230:233], v[168:171], v[116:119]
	v_mfma_f32_16x16x32_bf16 v[104:107], v[222:225], v[182:185], v[104:107]
	v_mfma_f32_16x16x32_bf16 v[108:111], v[230:233], v[182:185], v[108:111]
	v_mfma_f32_16x16x32_bf16 v[96:99], v[222:225], v[214:217], v[96:99]
	v_mfma_f32_16x16x32_bf16 v[100:103], v[230:233], v[214:217], v[100:103]
	s_add_i32 s55, s55, 2
	s_add_u32 s31, s31, 0x100
	s_addc_u32 s53, s53, 0
	s_cmp_gt_u32 s55, 13
	s_mov_b64 s[16:17], s[2:3]
	s_barrier
	s_cbranch_scc0 .LBB0_373
	s_lshl_b32 s2, s30, 8
	v_lshl_add_u32 v250, s8, 8, v136
	s_ashr_i32 s3, s2, 31
	v_ashrrev_i32_e32 v251, 31, v250
	v_lshl_add_u64 v[252:253], s[2:3], 1, v[130:131]
	v_lshlrev_b64 v[254:255], 11, v[250:251]
	v_lshl_add_u64 v[254:255], v[252:253], 0, v[254:255]
	v_cvt_pk_bf16_f32 v20, v20, v21
	v_cvt_pk_bf16_f32 v21, v22, v23
	v_cvt_pk_bf16_f32 v22, v28, v29
	v_cvt_pk_bf16_f32 v23, v30, v31
	global_store_dwordx4 v[254:255], v[20:23], off
	v_cvt_pk_bf16_f32 v12, v12, v13
	v_cvt_pk_bf16_f32 v13, v14, v15
	v_cvt_pk_bf16_f32 v20, v80, v81
	v_cvt_pk_bf16_f32 v21, v82, v83
	v_cvt_pk_bf16_f32 v22, v92, v93
	v_cvt_pk_bf16_f32 v23, v94, v95
	global_store_dwordx4 v[254:255], v[20:23], off offset:256
	v_cvt_pk_bf16_f32 v14, v24, v25
	v_cvt_pk_bf16_f32 v15, v26, v27
	v_or_b32_e32 v20, 16, v250
	v_ashrrev_i32_e32 v21, 31, v20
	v_lshlrev_b64 v[20:21], 11, v[20:21]
	v_lshl_add_u64 v[20:21], v[252:253], 0, v[20:21]
	global_store_dwordx4 v[20:21], v[12:15], off
	v_cvt_pk_bf16_f32 v4, v4, v5
	v_cvt_pk_bf16_f32 v5, v6, v7
	v_cvt_pk_bf16_f32 v12, v64, v65
	v_cvt_pk_bf16_f32 v13, v66, v67
	v_cvt_pk_bf16_f32 v14, v84, v85
	v_cvt_pk_bf16_f32 v15, v86, v87
	global_store_dwordx4 v[20:21], v[12:15], off offset:256
	v_cvt_pk_bf16_f32 v6, v16, v17
	v_cvt_pk_bf16_f32 v7, v18, v19
	v_or_b32_e32 v12, 32, v250
	v_ashrrev_i32_e32 v13, 31, v12
	v_lshlrev_b64 v[12:13], 11, v[12:13]
	v_lshl_add_u64 v[12:13], v[252:253], 0, v[12:13]
	global_store_dwordx4 v[12:13], v[4:7], off
	v_cvt_pk_bf16_f32 v0, v0, v1
	v_cvt_pk_bf16_f32 v1, v2, v3
	v_cvt_pk_bf16_f32 v4, v52, v53
	v_cvt_pk_bf16_f32 v5, v54, v55
	v_cvt_pk_bf16_f32 v6, v76, v77
	v_cvt_pk_bf16_f32 v7, v78, v79
	global_store_dwordx4 v[12:13], v[4:7], off offset:256
	v_cvt_pk_bf16_f32 v2, v8, v9
	v_cvt_pk_bf16_f32 v3, v10, v11
	v_or_b32_e32 v4, 48, v250
	v_ashrrev_i32_e32 v5, 31, v4
	v_lshlrev_b64 v[4:5], 11, v[4:5]
	v_lshl_add_u64 v[4:5], v[252:253], 0, v[4:5]
	global_store_dwordx4 v[4:5], v[0:3], off
	s_mov_b64 s[2:3], 0x40000
	s_movk_i32 s53, 0x440
	v_cvt_pk_bf16_f32 v0, v40, v41
	v_cvt_pk_bf16_f32 v1, v42, v43
	v_cvt_pk_bf16_f32 v2, v60, v61
	v_cvt_pk_bf16_f32 v3, v62, v63
	global_store_dwordx4 v[4:5], v[0:3], off offset:256
	v_lshl_add_u64 v[4:5], v[254:255], 0, s[2:3]
	s_mov_b32 s2, 0x40000
	v_add_co_u32_e32 v6, vcc, s2, v254
; __device__ __forceinline__ u32x4 mk4(unsigned a, unsigned b, unsigned c, unsigned d) { return (u32x4){a, b, c, d}; }
; __device__ __forceinline__ f32x4 zero4() { float z = 0.f; asm volatile("" : "+v"(z)); return (f32x4){z, z, z, z}; }
; __device__ __forceinline__ void gemm_phase(const Params& p, int l, const bf16_t* __restrict__ A, const bf16_t* __restrict__ Bt, int M, int N, int K,
;                            int epi, bf16_t* __restrict__ outp, char* smem, int wvi) {
;     ...
;           bf16_t* rp = outp + (size_t)(r0 + ai * GHALF + m * 16) * N + bcol + wc * 32 + fq * 8;
; #pragma unroll
;           for (int bj = 0; bj < 2; ++bj) {
;             const f32x4 v0 = acc[ai][bj][m][0], v1 = acc[ai][bj][m][1];
;             *reinterpret_cast<u32x4*>(rp + bj * GHALF) = mk4(pk2(v0[0], v0[1]), pk2(v0[2], v0[3]), pk2(v1[0], v1[1]), pk2(v1[2], v1[3]));
;           }
;         }
;     ...
;       if (!has_next) break;
; #pragma unroll
;       for (int a = 0; a < 2; ++a)
; #pragma unroll
;         for (int b = 0; b < 2; ++b)
; #pragma unroll
;           for (int m = 0; m < 4; ++m)
; #pragma unroll
;             for (int n = 0; n < 2; ++n) acc[a][b][m][n] = zero4();
;       Lw = Ln; pm = npm; pn = npn; cA = nA; cB = nB;
	v_cvt_pk_bf16_f32 v0, v68, v69
	v_cvt_pk_bf16_f32 v1, v70, v71
	v_cvt_pk_bf16_f32 v2, v88, v89
	v_cvt_pk_bf16_f32 v3, v90, v91
	v_addc_co_u32_e32 v7, vcc, 0, v255, vcc
	global_store_dwordx4 v[6:7], v[0:3], off
	s_mov_b64 s[2:3], 0x48000
	v_readlane_b32 s55, v244, 31
	v_cvt_pk_bf16_f32 v0, v120, v121
	v_cvt_pk_bf16_f32 v1, v122, v123
	v_cvt_pk_bf16_f32 v2, v124, v125
	v_cvt_pk_bf16_f32 v3, v126, v127
	global_store_dwordx4 v[4:5], v[0:3], off offset:256
	v_lshl_add_u64 v[4:5], v[254:255], 0, s[2:3]
	s_mov_b32 s2, 0x48000
	v_add_co_u32_e32 v6, vcc, s2, v254
	v_cvt_pk_bf16_f32 v0, v48, v49
	v_cvt_pk_bf16_f32 v1, v50, v51
	v_cvt_pk_bf16_f32 v2, v72, v73
	v_cvt_pk_bf16_f32 v3, v74, v75
	v_addc_co_u32_e32 v7, vcc, 0, v255, vcc
	global_store_dwordx4 v[6:7], v[0:3], off
	s_mov_b64 s[2:3], 0x50000
	s_nop 0
	v_cvt_pk_bf16_f32 v0, v112, v113
	v_cvt_pk_bf16_f32 v1, v114, v115
	v_cvt_pk_bf16_f32 v2, v116, v117
	v_cvt_pk_bf16_f32 v3, v118, v119
	global_store_dwordx4 v[4:5], v[0:3], off offset:256
	v_lshl_add_u64 v[4:5], v[254:255], 0, s[2:3]
	s_mov_b32 s2, 0x50000
	v_add_co_u32_e32 v6, vcc, s2, v254
	v_cvt_pk_bf16_f32 v0, v36, v37
	v_cvt_pk_bf16_f32 v1, v38, v39
	v_cvt_pk_bf16_f32 v2, v56, v57
	v_cvt_pk_bf16_f32 v3, v58, v59
	v_addc_co_u32_e32 v7, vcc, 0, v255, vcc
	global_store_dwordx4 v[6:7], v[0:3], off
	s_mov_b64 s[2:3], 0x58000
	s_nop 0
	v_cvt_pk_bf16_f32 v0, v104, v105
	v_cvt_pk_bf16_f32 v1, v106, v107
	v_cvt_pk_bf16_f32 v2, v108, v109
	v_cvt_pk_bf16_f32 v3, v110, v111
	global_store_dwordx4 v[4:5], v[0:3], off offset:256
	v_lshl_add_u64 v[4:5], v[254:255], 0, s[2:3]
	s_mov_b32 s2, 0x58000
	v_add_co_u32_e32 v6, vcc, s2, v254
	v_cvt_pk_bf16_f32 v0, v32, v33
	v_cvt_pk_bf16_f32 v1, v34, v35
	v_cvt_pk_bf16_f32 v2, v44, v45
	v_cvt_pk_bf16_f32 v3, v46, v47
	v_addc_co_u32_e32 v7, vcc, 0, v255, vcc
	global_store_dwordx4 v[6:7], v[0:3], off
	s_mov_b64 s[2:3], -1
	s_and_b64 vcc, exec, s[14:15]
	v_cvt_pk_bf16_f32 v0, v96, v97
	v_cvt_pk_bf16_f32 v1, v98, v99
	v_cvt_pk_bf16_f32 v2, v100, v101
	v_cvt_pk_bf16_f32 v3, v102, v103
	global_store_dwordx4 v[4:5], v[0:3], off offset:256
	s_cbranch_vccz .LBB0_369
	v_mov_b32_e32 v20, v177
	v_mov_b32_e32 v28, v177
	v_mov_b32_e32 v12, v177
	v_mov_b32_e32 v24, v177
	v_mov_b32_e32 v4, v177
	v_mov_b32_e32 v16, v177
	v_mov_b32_e32 v0, v177
	v_mov_b32_e32 v8, v177
	v_mov_b32_e32 v80, v177
	v_mov_b32_e32 v92, v177
	v_mov_b32_e32 v64, v177
	v_mov_b32_e32 v84, v177
	v_mov_b32_e32 v52, v177
	v_mov_b32_e32 v76, v177
	v_mov_b32_e32 v40, v177
	v_mov_b32_e32 v60, v177
	v_mov_b32_e32 v68, v177
	v_mov_b32_e32 v88, v177
	v_mov_b32_e32 v48, v177
	v_mov_b32_e32 v72, v177
	v_mov_b32_e32 v36, v177
	v_mov_b32_e32 v56, v177
	v_mov_b32_e32 v32, v177
	v_mov_b32_e32 v44, v177
	v_mov_b32_e32 v120, v177
	v_mov_b32_e32 v124, v177
	v_mov_b32_e32 v112, v177
	v_mov_b32_e32 v116, v177
	v_mov_b32_e32 v104, v177
	v_mov_b32_e32 v108, v177
	v_mov_b32_e32 v96, v177
	v_mov_b32_e32 v100, v177
	s_nop 0
	v_mov_b32_e32 v21, v20
	v_mov_b32_e32 v22, v20
	v_mov_b32_e32 v23, v20
	v_mov_b32_e32 v29, v28
	v_mov_b32_e32 v30, v28
	v_mov_b32_e32 v31, v28
	v_mov_b32_e32 v13, v12
	v_mov_b32_e32 v14, v12
	v_mov_b32_e32 v15, v12
	v_mov_b32_e32 v25, v24
	v_mov_b32_e32 v26, v24
	v_mov_b32_e32 v27, v24
	v_mov_b32_e32 v5, v4
	v_mov_b32_e32 v6, v4
	v_mov_b32_e32 v7, v4
	v_mov_b32_e32 v17, v16
	v_mov_b32_e32 v18, v16
	v_mov_b32_e32 v19, v16
	s_nop 0
	v_mov_b32_e32 v1, v0
	v_mov_b32_e32 v2, v0
	v_mov_b32_e32 v3, v0
	v_mov_b32_e32 v9, v8
	v_mov_b32_e32 v10, v8
	v_mov_b32_e32 v11, v8
	v_mov_b32_e32 v81, v80
	v_mov_b32_e32 v82, v80
	v_mov_b32_e32 v83, v80
	v_mov_b32_e32 v93, v92
	v_mov_b32_e32 v94, v92
	v_mov_b32_e32 v95, v92
	v_mov_b32_e32 v65, v64
	v_mov_b32_e32 v66, v64
	v_mov_b32_e32 v67, v64
	v_mov_b32_e32 v85, v84
	v_mov_b32_e32 v86, v84
	v_mov_b32_e32 v87, v84
	s_nop 0
	v_mov_b32_e32 v53, v52
	v_mov_b32_e32 v54, v52
	v_mov_b32_e32 v55, v52
	v_mov_b32_e32 v77, v76
	v_mov_b32_e32 v78, v76
	v_mov_b32_e32 v79, v76
	v_mov_b32_e32 v41, v40
	v_mov_b32_e32 v42, v40
	v_mov_b32_e32 v43, v40
	v_mov_b32_e32 v61, v60
	v_mov_b32_e32 v62, v60
	v_mov_b32_e32 v63, v60
	v_mov_b32_e32 v69, v68
	v_mov_b32_e32 v70, v68
	v_mov_b32_e32 v71, v68
	v_mov_b32_e32 v89, v88
	v_mov_b32_e32 v90, v88
	v_mov_b32_e32 v91, v88
	s_nop 0
	v_mov_b32_e32 v49, v48
	v_mov_b32_e32 v50, v48
	v_mov_b32_e32 v51, v48
	v_mov_b32_e32 v73, v72
	v_mov_b32_e32 v74, v72
	v_mov_b32_e32 v75, v72
	v_mov_b32_e32 v37, v36
	v_mov_b32_e32 v38, v36
	v_mov_b32_e32 v39, v36
	v_mov_b32_e32 v57, v56
	v_mov_b32_e32 v58, v56
	v_mov_b32_e32 v59, v56
	v_mov_b32_e32 v33, v32
	v_mov_b32_e32 v34, v32
	v_mov_b32_e32 v35, v32
	v_mov_b32_e32 v45, v44
	v_mov_b32_e32 v46, v44
	v_mov_b32_e32 v47, v44
	s_nop 0
	v_mov_b32_e32 v121, v120
	v_mov_b32_e32 v122, v120
	v_mov_b32_e32 v123, v120
	v_mov_b32_e32 v125, v124
	v_mov_b32_e32 v126, v124
	v_mov_b32_e32 v127, v124
	v_mov_b32_e32 v113, v112
	v_mov_b32_e32 v114, v112
	v_mov_b32_e32 v115, v112
	v_mov_b32_e32 v117, v116
	v_mov_b32_e32 v118, v116
	v_mov_b32_e32 v119, v116
	v_mov_b32_e32 v105, v104
	v_mov_b32_e32 v106, v104
	v_mov_b32_e32 v107, v104
	v_mov_b32_e32 v109, v108
	v_mov_b32_e32 v110, v108
	v_mov_b32_e32 v111, v108
	s_mov_b64 s[2:3], 0
	v_mov_b32_e32 v97, v96
	v_mov_b32_e32 v98, v96
	v_mov_b32_e32 v99, v96
	v_mov_b32_e32 v101, v100
	v_mov_b32_e32 v102, v100
	v_mov_b32_e32 v103, v100
	s_branch .LBB0_369

; #define G_STAGE(bufoff, gbase) do { _Pragma("unroll") for (int _i = 0; _i < 2; ++_i) \
;     __builtin_amdgcn_global_load_lds((const unsigned*)((const char*)(gbase) + voff[_i]), (GLAS unsigned*)(lds + (bufoff) + ldsw + _i * 8192), 16, 0, 0); } while (0)
; #define G_LDA(dst, b, h) do { _Pragma("unroll") for (int m = 0; m < 4; ++m) _Pragma("unroll") for (int k = 0; k < 2; ++k) \
;     dst[m][k] = *(const GLAS bf16x8*)(lds + G_SA(b, h) + aoff + m * 2048 + k * 1024); } while (0)
; #define G_LDB(dst, b, h) do { _Pragma("unroll") for (int n = 0; n < 2; ++n) _Pragma("unroll") for (int k = 0; k < 2; ++k) \
;     dst[n][k] = *(const GLAS bf16x8*)(lds + G_SB(b, h) + boff + n * 2048 + k * 1024); } while (0)
; #define G_MMA(ai, bj, At_, Bt_) do { __builtin_amdgcn_s_setprio(1); \
;     _Pragma("unroll") for (int m = 0; m < 4; ++m) _Pragma("unroll") for (int n = 0; n < 2; ++n) _Pragma("unroll") for (int k = 0; k < 2; ++k) \
;       acc[ai][bj][m][n] = __builtin_amdgcn_mfma_f32_16x16x32_bf16(Bt_[n][k], At_[m][k], acc[ai][bj][m][n], 0, 0, 0); \
;     __builtin_amdgcn_s_setprio(0); } while (0)
; #define G_WAIT_L(n) asm volatile("s_waitcnt lgkmcnt(" #n ")" ::: "memory")
; #define G_BAR __builtin_amdgcn_s_barrier()
; #define G_SCHED __builtin_amdgcn_sched_barrier(0)
; __device__ __forceinline__ void gemm_phase(const Params& p, int l, const bf16_t* __restrict__ A, const bf16_t* __restrict__ Bt, int M, int N, int K,
;                            int epi, bf16_t* __restrict__ outp, char* smem, int wvi) {
;     ...
;       for (int t = 0; t < nt; t += 2) {
;         const bool lastt = (t == nt - 2);
;         const char* a1 = cA + (size_t)(t + 1) * kstep;
;         const char* a2 = lastt ? nA : cA + (size_t)(t + 2) * kstep; const char* b2 = lastt ? nB : cB + (size_t)(t + 2) * kstep;
;         const char* a3 = a2 + kstep; const char* b3 = b2 + kstep;
;         G_LDB(B0, 0, 0); G_SCHED; G_LDA(At, 0, 0); G_STAGE(G_SA(1, 1), a1 + hstep);
;         G_WAIT_L(8); G_BAR; G_WAIT_L(0); G_MMA(0, 0, At, B0); G_BAR; G_SCHED;
;         G_LDB(B1, 0, 1); G_STAGE(G_SB(0, 0), b2);
;         G_BAR; G_WAIT_L(0); G_MMA(0, 1, At, B1); G_BAR;
;         G_LDA(At, 0, 1); G_STAGE(G_SA(0, 0), a2);
;         G_BAR; G_WAIT_L(0); G_MMA(1, 0, At, B0); G_BAR; G_SCHED;
.LBB0_568:
	s_add_u32 s2, s6, 0x100
	s_addc_u32 s3, s7, 0
	s_add_i32 s21, 0, 0x10000
	v_add_u32_e32 v140, s21, v159
	ds_read_b128 v[128:131], v140
	ds_read_b128 v[132:135], v140 offset:1024
	ds_read_b128 v[136:139], v140 offset:2048
	ds_read_b128 v[140:143], v140 offset:3072
	s_cmp_eq_u32 s20, 12
	s_cselect_b32 s29, s13, s3
	s_cselect_b32 s28, s12, s2
	s_cselect_b32 s5, s9, s17
	s_cselect_b32 s4, s1, s11
	v_lshl_add_u64 v[156:157], s[6:7], 0, v[152:153]
	s_add_i32 m0, s30, 0xc000
	ds_read_b128 v[162:165], v160
	ds_read_b128 v[166:169], v160 offset:1024
	ds_read_b128 v[170:173], v160 offset:2048
	ds_read_b128 v[182:185], v160 offset:3072
	ds_read_b128 v[186:189], v160 offset:4096
	ds_read_b128 v[214:217], v160 offset:5120
	ds_read_b128 v[218:221], v160 offset:6144
	ds_read_b128 v[222:225], v160 offset:7168
	global_load_lds_dwordx4 v[156:157], off
	v_lshl_add_u64 v[156:157], s[6:7], 0, v[154:155]
	s_add_i32 m0, s30, 0xe000
	s_nop 0
	global_load_lds_dwordx4 v[156:157], off
	s_waitcnt lgkmcnt(8)
	s_barrier
	s_waitcnt lgkmcnt(0)
	s_waitcnt lgkmcnt(0)
	v_mfma_f32_16x16x32_bf16 v[20:23], v[128:131], v[162:165], v[20:23]
	v_mfma_f32_16x16x32_bf16 v[28:31], v[136:139], v[162:165], v[28:31]
	v_mfma_f32_16x16x32_bf16 v[12:15], v[128:131], v[170:173], v[12:15]
	v_mfma_f32_16x16x32_bf16 v[24:27], v[136:139], v[170:173], v[24:27]
	v_mfma_f32_16x16x32_bf16 v[4:7], v[128:131], v[186:189], v[4:7]
	v_mfma_f32_16x16x32_bf16 v[16:19], v[136:139], v[186:189], v[16:19]
	v_mfma_f32_16x16x32_bf16 v[0:3], v[128:131], v[218:221], v[0:3]
	v_mfma_f32_16x16x32_bf16 v[8:11], v[136:139], v[218:221], v[8:11]
	v_mfma_f32_16x16x32_bf16 v[20:23], v[132:135], v[166:169], v[20:23]
	v_mfma_f32_16x16x32_bf16 v[28:31], v[140:143], v[166:169], v[28:31]
	v_mfma_f32_16x16x32_bf16 v[12:15], v[132:135], v[182:185], v[12:15]
	v_mfma_f32_16x16x32_bf16 v[24:27], v[140:143], v[182:185], v[24:27]
	v_mfma_f32_16x16x32_bf16 v[4:7], v[132:135], v[214:217], v[4:7]
	v_mfma_f32_16x16x32_bf16 v[16:19], v[140:143], v[214:217], v[16:19]
	v_mfma_f32_16x16x32_bf16 v[0:3], v[132:135], v[222:225], v[0:3]
	v_mfma_f32_16x16x32_bf16 v[8:11], v[140:143], v[222:225], v[8:11]
	s_barrier
	s_add_i32 s22, 0, 0x14000
	v_add_u32_e32 v156, s22, v159
	s_add_i32 s6, s21, s58
	ds_read_b128 v[226:229], v156
	ds_read_b128 v[230:233], v156 offset:1024
	ds_read_b128 v[234:237], v156 offset:2048
	ds_read_b128 v[238:241], v156 offset:3072
	v_lshl_add_u64 v[156:157], s[4:5], 0, v[146:147]
	s_mov_b32 m0, s6
	v_lshl_add_u64 v[174:175], s[4:5], 0, v[144:145]
	global_load_lds_dwordx4 v[156:157], off
	s_add_i32 m0, s6, 0x2000
	s_nop 0
	global_load_lds_dwordx4 v[174:175], off
	s_barrier
	s_waitcnt lgkmcnt(0)
	s_waitcnt lgkmcnt(0)
	v_mfma_f32_16x16x32_bf16 v[84:87], v[226:229], v[162:165], v[84:87]
	v_mfma_f32_16x16x32_bf16 v[100:103], v[234:237], v[162:165], v[100:103]
	v_mfma_f32_16x16x32_bf16 v[76:79], v[226:229], v[170:173], v[76:79]
	v_mfma_f32_16x16x32_bf16 v[92:95], v[234:237], v[170:173], v[92:95]
	v_mfma_f32_16x16x32_bf16 v[64:67], v[226:229], v[186:189], v[64:67]
	v_mfma_f32_16x16x32_bf16 v[80:83], v[234:237], v[186:189], v[80:83]
	v_mfma_f32_16x16x32_bf16 v[52:55], v[226:229], v[218:221], v[52:55]
	v_mfma_f32_16x16x32_bf16 v[68:71], v[234:237], v[218:221], v[68:71]
	v_mfma_f32_16x16x32_bf16 v[84:87], v[230:233], v[166:169], v[84:87]
	v_mfma_f32_16x16x32_bf16 v[100:103], v[238:241], v[166:169], v[100:103]
	v_mfma_f32_16x16x32_bf16 v[76:79], v[230:233], v[182:185], v[76:79]
	v_mfma_f32_16x16x32_bf16 v[92:95], v[238:241], v[182:185], v[92:95]
	v_mfma_f32_16x16x32_bf16 v[64:67], v[230:233], v[214:217], v[64:67]
	v_mfma_f32_16x16x32_bf16 v[80:83], v[238:241], v[214:217], v[80:83]
	v_mfma_f32_16x16x32_bf16 v[52:55], v[230:233], v[222:225], v[52:55]
	v_mfma_f32_16x16x32_bf16 v[68:71], v[238:241], v[222:225], v[68:71]
	s_mov_b32 m0, s30
	v_lshl_add_u64 v[190:191], s[28:29], 0, v[146:147]
	s_barrier
	ds_read_b128 v[162:165], v160 offset:16384
	ds_read_b128 v[166:169], v160 offset:17408
	ds_read_b128 v[170:173], v160 offset:18432
	ds_read_b128 v[182:185], v160 offset:19456
	ds_read_b128 v[186:189], v160 offset:20480
	ds_read_b128 v[214:217], v160 offset:21504
	ds_read_b128 v[218:221], v160 offset:22528
	ds_read_b128 v[222:225], v160 offset:23552
	global_load_lds_dwordx4 v[190:191], off
	v_lshl_add_u64 v[242:243], s[28:29], 0, v[144:145]
	s_mov_b32 m0, s31
	s_nop 0
	global_load_lds_dwordx4 v[242:243], off
	s_waitcnt vmcnt(10)
	s_barrier
	s_waitcnt lgkmcnt(0)
	s_waitcnt lgkmcnt(0)
	v_mfma_f32_16x16x32_bf16 v[56:59], v[128:131], v[162:165], v[56:59]
	v_mfma_f32_16x16x32_bf16 v[72:75], v[136:139], v[162:165], v[72:75]
	v_mfma_f32_16x16x32_bf16 v[44:47], v[128:131], v[170:173], v[44:47]
	v_mfma_f32_16x16x32_bf16 v[60:63], v[136:139], v[170:173], v[60:63]
	v_mfma_f32_16x16x32_bf16 v[36:39], v[128:131], v[186:189], v[36:39]
	v_mfma_f32_16x16x32_bf16 v[48:51], v[136:139], v[186:189], v[48:51]
	v_mfma_f32_16x16x32_bf16 v[32:35], v[128:131], v[218:221], v[32:35]
	v_mfma_f32_16x16x32_bf16 v[40:43], v[136:139], v[218:221], v[40:43]
	v_mfma_f32_16x16x32_bf16 v[56:59], v[132:135], v[166:169], v[56:59]
	v_mfma_f32_16x16x32_bf16 v[72:75], v[140:143], v[166:169], v[72:75]
	v_mfma_f32_16x16x32_bf16 v[44:47], v[132:135], v[182:185], v[44:47]
	v_mfma_f32_16x16x32_bf16 v[60:63], v[140:143], v[182:185], v[60:63]
	v_mfma_f32_16x16x32_bf16 v[36:39], v[132:135], v[214:217], v[36:39]
	v_mfma_f32_16x16x32_bf16 v[48:51], v[140:143], v[214:217], v[48:51]
	v_mfma_f32_16x16x32_bf16 v[32:35], v[132:135], v[222:225], v[32:35]
	v_mfma_f32_16x16x32_bf16 v[40:43], v[140:143], v[222:225], v[40:43]
	s_barrier
; #define G_STAGE(bufoff, gbase) do { _Pragma("unroll") for (int _i = 0; _i < 2; ++_i) \
;     __builtin_amdgcn_global_load_lds((const unsigned*)((const char*)(gbase) + voff[_i]), (GLAS unsigned*)(lds + (bufoff) + ldsw + _i * 8192), 16, 0, 0); } while (0)
; #define G_LDA(dst, b, h) do { _Pragma("unroll") for (int m = 0; m < 4; ++m) _Pragma("unroll") for (int k = 0; k < 2; ++k) \
;     dst[m][k] = *(const GLAS bf16x8*)(lds + G_SA(b, h) + aoff + m * 2048 + k * 1024); } while (0)
; #define G_LDB(dst, b, h) do { _Pragma("unroll") for (int n = 0; n < 2; ++n) _Pragma("unroll") for (int k = 0; k < 2; ++k) \
;     dst[n][k] = *(const GLAS bf16x8*)(lds + G_SB(b, h) + boff + n * 2048 + k * 1024); } while (0)
; #define G_MMA(ai, bj, At_, Bt_) do { __builtin_amdgcn_s_setprio(1); \
;     _Pragma("unroll") for (int m = 0; m < 4; ++m) _Pragma("unroll") for (int n = 0; n < 2; ++n) _Pragma("unroll") for (int k = 0; k < 2; ++k) \
;       acc[ai][bj][m][n] = __builtin_amdgcn_mfma_f32_16x16x32_bf16(Bt_[n][k], At_[m][k], acc[ai][bj][m][n], 0, 0, 0); \
;     __builtin_amdgcn_s_setprio(0); } while (0)
; #define G_WAIT_V(n) asm volatile("s_waitcnt vmcnt(" #n ")" ::: "memory")
; #define G_WAIT_L(n) asm volatile("s_waitcnt lgkmcnt(" #n ")" ::: "memory")
; #define G_BAR __builtin_amdgcn_s_barrier()
; #define G_SCHED __builtin_amdgcn_sched_barrier(0)
; __device__ __forceinline__ void gemm_phase(const Params& p, int l, const bf16_t* __restrict__ A, const bf16_t* __restrict__ Bt, int M, int N, int K,
;                            int epi, bf16_t* __restrict__ outp, char* smem, int wvi) {
;     ...
;         G_STAGE(G_SB(0, 1), b2 + hstep);
;         G_WAIT_V(6); G_BAR; G_MMA(1, 1, At, B1); G_BAR;
;         G_LDB(B0, 1, 0); G_SCHED; G_LDA(At, 1, 0); G_STAGE(G_SA(0, 1), a2 + hstep);
;         G_WAIT_L(8); G_BAR; G_WAIT_L(0); G_MMA(0, 0, At, B0); G_BAR; G_SCHED;
;         G_LDB(B1, 1, 1); G_STAGE(G_SB(1, 0), b3);
;         G_BAR; G_WAIT_L(0); G_MMA(0, 1, At, B1); G_BAR;
;         G_LDA(At, 1, 1); G_STAGE(G_SA(1, 0), a3);
;         G_BAR; G_WAIT_L(0); G_MMA(1, 0, At, B0); G_BAR; G_SCHED;
	s_add_u32 s6, s4, 0x40000
	s_addc_u32 s7, s5, 0
	s_add_i32 s21, s22, s58
	v_lshl_add_u64 v[128:129], s[6:7], 0, v[146:147]
	s_mov_b32 m0, s21
	s_nop 0
	global_load_lds_dwordx4 v[128:129], off
	v_lshl_add_u64 v[128:129], s[6:7], 0, v[144:145]
	s_add_i32 m0, s21, 0x2000
	s_nop 0
	global_load_lds_dwordx4 v[128:129], off
	v_add_u32_e32 v140, 0x18000, v159
	ds_read_b128 v[128:131], v140
	ds_read_b128 v[132:135], v140 offset:1024
	ds_read_b128 v[136:139], v140 offset:2048
	ds_read_b128 v[140:143], v140 offset:3072
	s_waitcnt vmcnt(6)
	s_barrier
	v_mfma_f32_16x16x32_bf16 v[120:123], v[226:229], v[162:165], v[120:123]
	v_mfma_f32_16x16x32_bf16 v[124:127], v[234:237], v[162:165], v[124:127]
	v_mfma_f32_16x16x32_bf16 v[112:115], v[226:229], v[170:173], v[112:115]
	v_mfma_f32_16x16x32_bf16 v[116:119], v[234:237], v[170:173], v[116:119]
	v_mfma_f32_16x16x32_bf16 v[104:107], v[226:229], v[186:189], v[104:107]
	v_mfma_f32_16x16x32_bf16 v[108:111], v[234:237], v[186:189], v[108:111]
	v_mfma_f32_16x16x32_bf16 v[88:91], v[226:229], v[218:221], v[88:91]
	v_mfma_f32_16x16x32_bf16 v[96:99], v[234:237], v[218:221], v[96:99]
	v_mfma_f32_16x16x32_bf16 v[120:123], v[230:233], v[166:169], v[120:123]
	v_mfma_f32_16x16x32_bf16 v[124:127], v[238:241], v[166:169], v[124:127]
	v_mfma_f32_16x16x32_bf16 v[112:115], v[230:233], v[182:185], v[112:115]
	v_mfma_f32_16x16x32_bf16 v[116:119], v[238:241], v[182:185], v[116:119]
	v_mfma_f32_16x16x32_bf16 v[104:107], v[230:233], v[214:217], v[104:107]
	v_mfma_f32_16x16x32_bf16 v[108:111], v[238:241], v[214:217], v[108:111]
	v_mfma_f32_16x16x32_bf16 v[88:91], v[230:233], v[222:225], v[88:91]
	v_mfma_f32_16x16x32_bf16 v[96:99], v[238:241], v[222:225], v[96:99]
	s_add_i32 s21, 0, 0x18000
	s_barrier
	s_add_u32 s6, s28, 0x40000
	s_addc_u32 s7, s29, 0
	s_mov_b32 m0, s88
	v_lshl_add_u64 v[226:227], s[6:7], 0, v[146:147]
	ds_read_b128 v[162:165], v160 offset:32768
	ds_read_b128 v[166:169], v160 offset:33792
	ds_read_b128 v[170:173], v160 offset:34816
	ds_read_b128 v[182:185], v160 offset:35840
	ds_read_b128 v[186:189], v160 offset:36864
	ds_read_b128 v[214:217], v160 offset:37888
	ds_read_b128 v[218:221], v160 offset:38912
	ds_read_b128 v[222:225], v160 offset:39936
	global_load_lds_dwordx4 v[226:227], off
	v_lshl_add_u64 v[226:227], s[6:7], 0, v[144:145]
	s_mov_b32 m0, s89
	s_nop 0
	global_load_lds_dwordx4 v[226:227], off
	s_waitcnt lgkmcnt(8)
	s_barrier
	s_waitcnt lgkmcnt(0)
	s_waitcnt lgkmcnt(0)
	v_mfma_f32_16x16x32_bf16 v[20:23], v[128:131], v[162:165], v[20:23]
	v_mfma_f32_16x16x32_bf16 v[28:31], v[136:139], v[162:165], v[28:31]
	v_mfma_f32_16x16x32_bf16 v[12:15], v[128:131], v[170:173], v[12:15]
	v_mfma_f32_16x16x32_bf16 v[24:27], v[136:139], v[170:173], v[24:27]
	v_mfma_f32_16x16x32_bf16 v[4:7], v[128:131], v[186:189], v[4:7]
	v_mfma_f32_16x16x32_bf16 v[16:19], v[136:139], v[186:189], v[16:19]
	v_mfma_f32_16x16x32_bf16 v[0:3], v[128:131], v[218:221], v[0:3]
	v_mfma_f32_16x16x32_bf16 v[8:11], v[136:139], v[218:221], v[8:11]
	v_mfma_f32_16x16x32_bf16 v[20:23], v[132:135], v[166:169], v[20:23]
	v_mfma_f32_16x16x32_bf16 v[28:31], v[140:143], v[166:169], v[28:31]
	v_mfma_f32_16x16x32_bf16 v[12:15], v[132:135], v[182:185], v[12:15]
	v_mfma_f32_16x16x32_bf16 v[24:27], v[140:143], v[182:185], v[24:27]
	v_mfma_f32_16x16x32_bf16 v[4:7], v[132:135], v[214:217], v[4:7]
	v_mfma_f32_16x16x32_bf16 v[16:19], v[140:143], v[214:217], v[16:19]
	v_mfma_f32_16x16x32_bf16 v[0:3], v[132:135], v[222:225], v[0:3]
	v_mfma_f32_16x16x32_bf16 v[8:11], v[140:143], v[222:225], v[8:11]
	s_barrier
	s_add_i32 s6, 0, 0x1c000
	s_add_i32 s7, s21, s58
	v_add_u32_e32 v161, s6, v159
	v_lshl_add_u64 v[156:157], v[156:157], 0, s[64:65]
	s_mov_b32 m0, s7
	ds_read_b128 v[226:229], v161
	ds_read_b128 v[230:233], v161 offset:1024
	ds_read_b128 v[234:237], v161 offset:2048
	ds_read_b128 v[238:241], v161 offset:3072
	global_load_lds_dwordx4 v[156:157], off
	v_lshl_add_u64 v[156:157], v[174:175], 0, s[64:65]
	s_add_i32 m0, s7, 0x2000
	s_nop 0
	global_load_lds_dwordx4 v[156:157], off
	s_barrier
	s_waitcnt lgkmcnt(0)
	s_waitcnt lgkmcnt(0)
	v_mfma_f32_16x16x32_bf16 v[84:87], v[226:229], v[162:165], v[84:87]
	v_mfma_f32_16x16x32_bf16 v[100:103], v[234:237], v[162:165], v[100:103]
	v_mfma_f32_16x16x32_bf16 v[76:79], v[226:229], v[170:173], v[76:79]
	v_mfma_f32_16x16x32_bf16 v[92:95], v[234:237], v[170:173], v[92:95]
	v_mfma_f32_16x16x32_bf16 v[64:67], v[226:229], v[186:189], v[64:67]
	v_mfma_f32_16x16x32_bf16 v[80:83], v[234:237], v[186:189], v[80:83]
	v_mfma_f32_16x16x32_bf16 v[52:55], v[226:229], v[218:221], v[52:55]
	v_mfma_f32_16x16x32_bf16 v[68:71], v[234:237], v[218:221], v[68:71]
	v_mfma_f32_16x16x32_bf16 v[84:87], v[230:233], v[166:169], v[84:87]
	v_mfma_f32_16x16x32_bf16 v[100:103], v[238:241], v[166:169], v[100:103]
	v_mfma_f32_16x16x32_bf16 v[76:79], v[230:233], v[182:185], v[76:79]
	v_mfma_f32_16x16x32_bf16 v[92:95], v[238:241], v[182:185], v[92:95]
	v_mfma_f32_16x16x32_bf16 v[64:67], v[230:233], v[214:217], v[64:67]
	v_mfma_f32_16x16x32_bf16 v[80:83], v[238:241], v[214:217], v[80:83]
	v_mfma_f32_16x16x32_bf16 v[52:55], v[230:233], v[222:225], v[52:55]
	v_mfma_f32_16x16x32_bf16 v[68:71], v[238:241], v[222:225], v[68:71]
	s_mov_b32 m0, s92
	v_lshl_add_u64 v[156:157], v[190:191], 0, s[64:65]
	s_barrier
; #define G_STAGE(bufoff, gbase) do { _Pragma("unroll") for (int _i = 0; _i < 2; ++_i) \
;     __builtin_amdgcn_global_load_lds((const unsigned*)((const char*)(gbase) + voff[_i]), (GLAS unsigned*)(lds + (bufoff) + ldsw + _i * 8192), 16, 0, 0); } while (0)
; #define G_LDA(dst, b, h) do { _Pragma("unroll") for (int m = 0; m < 4; ++m) _Pragma("unroll") for (int k = 0; k < 2; ++k) \
;     dst[m][k] = *(const GLAS bf16x8*)(lds + G_SA(b, h) + aoff + m * 2048 + k * 1024); } while (0)
; #define G_MMA(ai, bj, At_, Bt_) do { __builtin_amdgcn_s_setprio(1); \
;     _Pragma("unroll") for (int m = 0; m < 4; ++m) _Pragma("unroll") for (int n = 0; n < 2; ++n) _Pragma("unroll") for (int k = 0; k < 2; ++k) \
;       acc[ai][bj][m][n] = __builtin_amdgcn_mfma_f32_16x16x32_bf16(Bt_[n][k], At_[m][k], acc[ai][bj][m][n], 0, 0, 0); \
;     __builtin_amdgcn_s_setprio(0); } while (0)
; #define G_WAIT_V(n) asm volatile("s_waitcnt vmcnt(" #n ")" ::: "memory")
; #define G_WAIT_L(n) asm volatile("s_waitcnt lgkmcnt(" #n ")" ::: "memory")
; #define G_BAR __builtin_amdgcn_s_barrier()
; #define G_SCHED __builtin_amdgcn_sched_barrier(0)
; __device__ __forceinline__ void gemm_phase(const Params& p, int l, const bf16_t* __restrict__ A, const bf16_t* __restrict__ Bt, int M, int N, int K,
;                            int epi, bf16_t* __restrict__ outp, char* smem, int wvi) {
;     ...
;         G_BAR; G_WAIT_L(0); G_MMA(0, 1, At, B1); G_BAR;
;         G_LDA(At, 1, 1); G_STAGE(G_SA(1, 0), a3);
;         G_BAR; G_WAIT_L(0); G_MMA(1, 0, At, B0); G_BAR; G_SCHED;
;         G_STAGE(G_SB(1, 1), b3 + hstep);
;         G_WAIT_V(6); G_BAR; G_MMA(1, 1, At, B1); G_BAR;
;       }
;     ...
;       } else if (wc == 0 && fq < 2) {
;         const float* db = p.dt_bias + l * 16 + fq * 8;
;         float dbv[8];
; #pragma unroll
;         for (int i = 0; i < 8; ++i) dbv[i] = db[i];
; #pragma unroll
;         for (int ai = 0; ai < 2; ++ai)
; #pragma unroll
;           for (int m = 0; m < 4; ++m) {
;             const f32x4 v0 = acc[ai][0][m][0], v1 = acc[ai][0][m][1];
;             float4 o0, o1;
;             o0.x = softplus_f(v0[0] + dbv[0]); o0.y = softplus_f(v0[1] + dbv[1]); o0.z = softplus_f(v0[2] + dbv[2]); o0.w = softplus_f(v0[3] + dbv[3]);
;             o1.x = softplus_f(v1[0] + dbv[4]); o1.y = softplus_f(v1[1] + dbv[5]); o1.z = softplus_f(v1[2] + dbv[6]); o1.w = softplus_f(v1[3] + dbv[7]);
	ds_read_b128 v[162:165], v160 offset:49152
	ds_read_b128 v[166:169], v160 offset:50176
	ds_read_b128 v[170:173], v160 offset:51200
	ds_read_b128 v[182:185], v160 offset:52224
	ds_read_b128 v[186:189], v160 offset:53248
	ds_read_b128 v[214:217], v160 offset:54272
	ds_read_b128 v[218:221], v160 offset:55296
	ds_read_b128 v[222:225], v160 offset:56320
	global_load_lds_dwordx4 v[156:157], off
	v_lshl_add_u64 v[156:157], v[242:243], 0, s[64:65]
	s_mov_b32 m0, s93
	s_nop 0
	global_load_lds_dwordx4 v[156:157], off
	s_barrier
	s_waitcnt lgkmcnt(0)
	s_waitcnt lgkmcnt(0)
	v_mfma_f32_16x16x32_bf16 v[56:59], v[128:131], v[162:165], v[56:59]
	v_mfma_f32_16x16x32_bf16 v[72:75], v[136:139], v[162:165], v[72:75]
	v_mfma_f32_16x16x32_bf16 v[44:47], v[128:131], v[170:173], v[44:47]
	v_mfma_f32_16x16x32_bf16 v[60:63], v[136:139], v[170:173], v[60:63]
	v_mfma_f32_16x16x32_bf16 v[36:39], v[128:131], v[186:189], v[36:39]
	v_mfma_f32_16x16x32_bf16 v[48:51], v[136:139], v[186:189], v[48:51]
	v_mfma_f32_16x16x32_bf16 v[32:35], v[128:131], v[218:221], v[32:35]
	v_mfma_f32_16x16x32_bf16 v[40:43], v[136:139], v[218:221], v[40:43]
	v_mfma_f32_16x16x32_bf16 v[56:59], v[132:135], v[166:169], v[56:59]
	v_mfma_f32_16x16x32_bf16 v[72:75], v[140:143], v[166:169], v[72:75]
	v_mfma_f32_16x16x32_bf16 v[44:47], v[132:135], v[182:185], v[44:47]
	v_mfma_f32_16x16x32_bf16 v[60:63], v[140:143], v[182:185], v[60:63]
	v_mfma_f32_16x16x32_bf16 v[36:39], v[132:135], v[214:217], v[36:39]
	v_mfma_f32_16x16x32_bf16 v[48:51], v[140:143], v[214:217], v[48:51]
	v_mfma_f32_16x16x32_bf16 v[32:35], v[132:135], v[222:225], v[32:35]
	v_mfma_f32_16x16x32_bf16 v[40:43], v[140:143], v[222:225], v[40:43]
	s_barrier
	s_add_u32 s4, s4, 0x40080
	s_addc_u32 s5, s5, 0
	s_add_i32 s6, s6, s58
	v_lshl_add_u64 v[128:129], s[4:5], 0, v[146:147]
	s_mov_b32 m0, s6
	s_nop 0
	global_load_lds_dwordx4 v[128:129], off
	v_lshl_add_u64 v[128:129], s[4:5], 0, v[144:145]
	s_add_i32 m0, s6, 0x2000
	s_nop 0
	global_load_lds_dwordx4 v[128:129], off
	s_waitcnt vmcnt(6)
	s_barrier
	v_mfma_f32_16x16x32_bf16 v[120:123], v[226:229], v[162:165], v[120:123]
	v_mfma_f32_16x16x32_bf16 v[124:127], v[234:237], v[162:165], v[124:127]
	v_mfma_f32_16x16x32_bf16 v[112:115], v[226:229], v[170:173], v[112:115]
	v_mfma_f32_16x16x32_bf16 v[116:119], v[234:237], v[170:173], v[116:119]
	v_mfma_f32_16x16x32_bf16 v[104:107], v[226:229], v[186:189], v[104:107]
	v_mfma_f32_16x16x32_bf16 v[108:111], v[234:237], v[186:189], v[108:111]
	v_mfma_f32_16x16x32_bf16 v[88:91], v[226:229], v[218:221], v[88:91]
	v_mfma_f32_16x16x32_bf16 v[96:99], v[234:237], v[218:221], v[96:99]
	v_mfma_f32_16x16x32_bf16 v[120:123], v[230:233], v[166:169], v[120:123]
	v_mfma_f32_16x16x32_bf16 v[124:127], v[238:241], v[166:169], v[124:127]
	v_mfma_f32_16x16x32_bf16 v[112:115], v[230:233], v[182:185], v[112:115]
	v_mfma_f32_16x16x32_bf16 v[116:119], v[238:241], v[182:185], v[116:119]
	v_mfma_f32_16x16x32_bf16 v[104:107], v[230:233], v[214:217], v[104:107]
	v_mfma_f32_16x16x32_bf16 v[108:111], v[238:241], v[214:217], v[108:111]
	v_mfma_f32_16x16x32_bf16 v[88:91], v[230:233], v[222:225], v[88:91]
	v_mfma_f32_16x16x32_bf16 v[96:99], v[238:241], v[222:225], v[96:99]
	s_add_i32 s20, s20, 2
	s_add_u32 s11, s11, 0x100
	s_addc_u32 s17, s17, 0
	s_cmp_gt_u32 s20, 13
	s_mov_b64 s[6:7], s[2:3]
	s_barrier
	s_cbranch_scc0 .LBB0_568
	v_lshl_add_u32 v156, s0, 8, v158
	s_cmp_gt_i32 s16, 11
	s_mov_b64 s[2:3], -1
	s_mov_b32 s9, 0x41a00000
	s_cbranch_scc0 .LBB0_957
	s_and_saveexec_b64 s[6:7], s[24:25]
	s_cbranch_execz .LBB0_956
	global_load_dwordx4 v[132:135], v[148:149], off
	global_load_dwordx4 v[128:131], v[148:149], off offset:16
	s_waitcnt vmcnt(0)
	v_add_f32_e32 v136, v20, v132
	v_cmp_nlt_f32_e32 vcc, s9, v136
	s_and_saveexec_b64 s[2:3], vcc
	s_cbranch_execz .LBB0_577
	v_mul_f32_e32 v136, 0x3fb8aa3b, v136
	v_exp_f32_e32 v137, v136
	s_nop 0
	v_cmp_ngt_f32_e32 vcc, s18, v137
	s_and_saveexec_b64 s[0:1], vcc
	s_xor_b64 s[28:29], exec, s[0:1]
	s_cbranch_execz .LBB0_574
	v_add_f32_e32 v136, 1.0, v137
	s_mov_b32 s0, 0x800000
	v_cmp_gt_f32_e32 vcc, s0, v136
	s_mov_b32 s0, 0x3f317217
	s_nop 0
	v_cndmask_b32_e64 v137, 0, 32, vcc
	v_ldexp_f32 v136, v136, v137
	v_log_f32_e32 v136, v136
	s_nop 0
	v_mul_f32_e32 v137, 0x3f317217, v136
	v_fma_f32 v137, v136, s0, -v137
	v_fmac_f32_e32 v137, 0x3377d1cf, v136
	s_mov_b32 s0, 0x7f800000
	v_fmac_f32_e32 v137, 0x3f317217, v136
	v_cmp_lt_f32_e64 s[4:5], |v136|, s0
	s_nop 1
	v_cndmask_b32_e64 v136, v136, v137, s[4:5]
	v_cndmask_b32_e32 v137, 0, v212, vcc
	v_sub_f32_e32 v136, v136, v137

; #define G_STAGE(bufoff, gbase) do { _Pragma("unroll") for (int _i = 0; _i < 2; ++_i) \
;     __builtin_amdgcn_global_load_lds((const unsigned*)((const char*)(gbase) + voff[_i]), (GLAS unsigned*)(lds + (bufoff) + ldsw + _i * 8192), 16, 0, 0); } while (0)
; #define G_LDA(dst, b, h) do { _Pragma("unroll") for (int m = 0; m < 4; ++m) _Pragma("unroll") for (int k = 0; k < 2; ++k) \
;     dst[m][k] = *(const GLAS bf16x8*)(lds + G_SA(b, h) + aoff + m * 2048 + k * 1024); } while (0)
; #define G_LDB(dst, b, h) do { _Pragma("unroll") for (int n = 0; n < 2; ++n) _Pragma("unroll") for (int k = 0; k < 2; ++k) \
;     dst[n][k] = *(const GLAS bf16x8*)(lds + G_SB(b, h) + boff + n * 2048 + k * 1024); } while (0)
; #define G_MMA(ai, bj, At_, Bt_) do { __builtin_amdgcn_s_setprio(1); \
;     _Pragma("unroll") for (int m = 0; m < 4; ++m) _Pragma("unroll") for (int n = 0; n < 2; ++n) _Pragma("unroll") for (int k = 0; k < 2; ++k) \
;       acc[ai][bj][m][n] = __builtin_amdgcn_mfma_f32_16x16x32_bf16(Bt_[n][k], At_[m][k], acc[ai][bj][m][n], 0, 0, 0); \
;     __builtin_amdgcn_s_setprio(0); } while (0)
; #define G_WAIT_L(n) asm volatile("s_waitcnt lgkmcnt(" #n ")" ::: "memory")
; #define G_BAR __builtin_amdgcn_s_barrier()
; #define G_SCHED __builtin_amdgcn_sched_barrier(0)
; __device__ __forceinline__ void gemm_phase(const Params& p, int l, const bf16_t* __restrict__ A, const bf16_t* __restrict__ Bt, int M, int N, int K,
;                            int epi, bf16_t* __restrict__ outp, char* smem, int wvi) {
;     ...
;       for (int t = 0; t < nt; t += 2) {
;         const bool lastt = (t == nt - 2);
;         const char* a1 = cA + (size_t)(t + 1) * kstep;
;         const char* a2 = lastt ? nA : cA + (size_t)(t + 2) * kstep; const char* b2 = lastt ? nB : cB + (size_t)(t + 2) * kstep;
;         const char* a3 = a2 + kstep; const char* b3 = b2 + kstep;
;         G_LDB(B0, 0, 0); G_SCHED; G_LDA(At, 0, 0); G_STAGE(G_SA(1, 1), a1 + hstep);
;         G_WAIT_L(8); G_BAR; G_WAIT_L(0); G_MMA(0, 0, At, B0); G_BAR; G_SCHED;
;         G_LDB(B1, 0, 1); G_STAGE(G_SB(0, 0), b2);
;         G_BAR; G_WAIT_L(0); G_MMA(0, 1, At, B1); G_BAR;
;         G_LDA(At, 0, 1); G_STAGE(G_SA(0, 0), a2);
;         G_BAR; G_WAIT_L(0); G_MMA(1, 0, At, B0); G_BAR; G_SCHED;
.LBB0_1039:
	s_add_u32 s2, s12, 0x100
	s_addc_u32 s3, s13, 0
	s_add_i32 s53, 0, 0x10000
	s_cmp_eq_u32 s31, 40
	s_cselect_b32 s15, s5, s3
	s_cselect_b32 s14, s4, s2
	s_cselect_b32 s11, s28, s30
	s_cselect_b32 s10, s27, s29
	v_lshl_add_u64 v[190:191], s[12:13], 0, v[132:133]
	s_add_i32 m0, s1, 0xc000
	ds_read_b128 v[156:159], v138
	ds_read_b128 v[160:163], v138 offset:1024
	ds_read_b128 v[164:167], v138 offset:2048
	ds_read_b128 v[168:171], v138 offset:3072
	ds_read_b128 v[172:175], v138 offset:4096
	ds_read_b128 v[182:185], v138 offset:5120
	ds_read_b128 v[186:189], v138 offset:6144
	ds_read_b128 v[214:217], v138 offset:7168
	global_load_lds_dwordx4 v[190:191], off
	v_lshl_add_u64 v[190:191], s[12:13], 0, v[134:135]
	s_add_i32 m0, s1, 0xe000
	s_nop 0
	global_load_lds_dwordx4 v[190:191], off
	s_waitcnt lgkmcnt(8)
	s_barrier
	s_waitcnt lgkmcnt(0)
	s_waitcnt lgkmcnt(0)
	v_mfma_f32_16x16x32_bf16 v[20:23], v[140:143], v[156:159], v[20:23]
	v_mfma_f32_16x16x32_bf16 v[28:31], v[148:151], v[156:159], v[28:31]
	v_mfma_f32_16x16x32_bf16 v[12:15], v[140:143], v[164:167], v[12:15]
	v_mfma_f32_16x16x32_bf16 v[24:27], v[148:151], v[164:167], v[24:27]
	v_mfma_f32_16x16x32_bf16 v[4:7], v[140:143], v[172:175], v[4:7]
	v_mfma_f32_16x16x32_bf16 v[16:19], v[148:151], v[172:175], v[16:19]
	v_mfma_f32_16x16x32_bf16 v[0:3], v[140:143], v[186:189], v[0:3]
	v_mfma_f32_16x16x32_bf16 v[8:11], v[148:151], v[186:189], v[8:11]
	v_mfma_f32_16x16x32_bf16 v[20:23], v[144:147], v[160:163], v[20:23]
	v_mfma_f32_16x16x32_bf16 v[28:31], v[152:155], v[160:163], v[28:31]
	v_mfma_f32_16x16x32_bf16 v[12:15], v[144:147], v[168:171], v[12:15]
	v_mfma_f32_16x16x32_bf16 v[24:27], v[152:155], v[168:171], v[24:27]
	v_mfma_f32_16x16x32_bf16 v[4:7], v[144:147], v[182:185], v[4:7]
	v_mfma_f32_16x16x32_bf16 v[16:19], v[152:155], v[182:185], v[16:19]
	v_mfma_f32_16x16x32_bf16 v[0:3], v[144:147], v[214:217], v[0:3]
	v_mfma_f32_16x16x32_bf16 v[8:11], v[152:155], v[214:217], v[8:11]
	s_barrier
	s_add_i32 s55, 0, 0x14000
	s_add_i32 s12, s53, s58
	v_add_u32_e32 v139, s55, v137
	v_lshl_add_u64 v[190:191], s[10:11], 0, v[176:177]
	s_mov_b32 m0, s12
	ds_read_b128 v[218:221], v139
	ds_read_b128 v[222:225], v139 offset:1024
	ds_read_b128 v[226:229], v139 offset:2048
	ds_read_b128 v[230:233], v139 offset:3072
	global_load_lds_dwordx4 v[190:191], off
	v_lshl_add_u64 v[234:235], s[10:11], 0, v[128:129]
	s_add_i32 m0, s12, 0x2000
	s_nop 0
	global_load_lds_dwordx4 v[234:235], off
	s_barrier
	s_waitcnt lgkmcnt(0)
	s_waitcnt lgkmcnt(0)
	v_mfma_f32_16x16x32_bf16 v[80:83], v[218:221], v[156:159], v[80:83]
	v_mfma_f32_16x16x32_bf16 v[92:95], v[226:229], v[156:159], v[92:95]
	v_mfma_f32_16x16x32_bf16 v[64:67], v[218:221], v[164:167], v[64:67]
	v_mfma_f32_16x16x32_bf16 v[84:87], v[226:229], v[164:167], v[84:87]
	v_mfma_f32_16x16x32_bf16 v[52:55], v[218:221], v[172:175], v[52:55]
	v_mfma_f32_16x16x32_bf16 v[76:79], v[226:229], v[172:175], v[76:79]
	v_mfma_f32_16x16x32_bf16 v[40:43], v[218:221], v[186:189], v[40:43]
	v_mfma_f32_16x16x32_bf16 v[60:63], v[226:229], v[186:189], v[60:63]
	v_mfma_f32_16x16x32_bf16 v[80:83], v[222:225], v[160:163], v[80:83]
	v_mfma_f32_16x16x32_bf16 v[92:95], v[230:233], v[160:163], v[92:95]
	v_mfma_f32_16x16x32_bf16 v[64:67], v[222:225], v[168:171], v[64:67]
	v_mfma_f32_16x16x32_bf16 v[84:87], v[230:233], v[168:171], v[84:87]
	v_mfma_f32_16x16x32_bf16 v[52:55], v[222:225], v[182:185], v[52:55]
	v_mfma_f32_16x16x32_bf16 v[76:79], v[230:233], v[182:185], v[76:79]
	v_mfma_f32_16x16x32_bf16 v[40:43], v[222:225], v[214:217], v[40:43]
	v_mfma_f32_16x16x32_bf16 v[60:63], v[230:233], v[214:217], v[60:63]
	s_mov_b32 m0, s1
	v_lshl_add_u64 v[236:237], s[14:15], 0, v[176:177]
	s_barrier
	ds_read_b128 v[156:159], v138 offset:16384
	ds_read_b128 v[160:163], v138 offset:17408
	ds_read_b128 v[164:167], v138 offset:18432
	ds_read_b128 v[168:171], v138 offset:19456
	ds_read_b128 v[172:175], v138 offset:20480
	ds_read_b128 v[182:185], v138 offset:21504
	ds_read_b128 v[186:189], v138 offset:22528
	ds_read_b128 v[214:217], v138 offset:23552
	global_load_lds_dwordx4 v[236:237], off
	v_lshl_add_u64 v[238:239], s[14:15], 0, v[128:129]
	s_mov_b32 m0, s16
	s_nop 0
	global_load_lds_dwordx4 v[238:239], off
	s_waitcnt vmcnt(10)
	s_barrier
	s_waitcnt lgkmcnt(0)
	s_waitcnt lgkmcnt(0)
	v_mfma_f32_16x16x32_bf16 v[68:71], v[140:143], v[156:159], v[68:71]
	v_mfma_f32_16x16x32_bf16 v[88:91], v[148:151], v[156:159], v[88:91]
	v_mfma_f32_16x16x32_bf16 v[48:51], v[140:143], v[164:167], v[48:51]
	v_mfma_f32_16x16x32_bf16 v[72:75], v[148:151], v[164:167], v[72:75]
	v_mfma_f32_16x16x32_bf16 v[36:39], v[140:143], v[172:175], v[36:39]
	v_mfma_f32_16x16x32_bf16 v[56:59], v[148:151], v[172:175], v[56:59]
	v_mfma_f32_16x16x32_bf16 v[32:35], v[140:143], v[186:189], v[32:35]
	v_mfma_f32_16x16x32_bf16 v[44:47], v[148:151], v[186:189], v[44:47]
	v_mfma_f32_16x16x32_bf16 v[68:71], v[144:147], v[160:163], v[68:71]
	v_mfma_f32_16x16x32_bf16 v[88:91], v[152:155], v[160:163], v[88:91]
	v_mfma_f32_16x16x32_bf16 v[48:51], v[144:147], v[168:171], v[48:51]
	v_mfma_f32_16x16x32_bf16 v[72:75], v[152:155], v[168:171], v[72:75]
	v_mfma_f32_16x16x32_bf16 v[36:39], v[144:147], v[182:185], v[36:39]
	v_mfma_f32_16x16x32_bf16 v[56:59], v[152:155], v[182:185], v[56:59]
	v_mfma_f32_16x16x32_bf16 v[32:35], v[144:147], v[214:217], v[32:35]
	v_mfma_f32_16x16x32_bf16 v[44:47], v[152:155], v[214:217], v[44:47]
	s_barrier
; #define G_STAGE(bufoff, gbase) do { _Pragma("unroll") for (int _i = 0; _i < 2; ++_i) \
;     __builtin_amdgcn_global_load_lds((const unsigned*)((const char*)(gbase) + voff[_i]), (GLAS unsigned*)(lds + (bufoff) + ldsw + _i * 8192), 16, 0, 0); } while (0)
; #define G_LDA(dst, b, h) do { _Pragma("unroll") for (int m = 0; m < 4; ++m) _Pragma("unroll") for (int k = 0; k < 2; ++k) \
;     dst[m][k] = *(const GLAS bf16x8*)(lds + G_SA(b, h) + aoff + m * 2048 + k * 1024); } while (0)
; #define G_LDB(dst, b, h) do { _Pragma("unroll") for (int n = 0; n < 2; ++n) _Pragma("unroll") for (int k = 0; k < 2; ++k) \
;     dst[n][k] = *(const GLAS bf16x8*)(lds + G_SB(b, h) + boff + n * 2048 + k * 1024); } while (0)
; #define G_MMA(ai, bj, At_, Bt_) do { __builtin_amdgcn_s_setprio(1); \
;     _Pragma("unroll") for (int m = 0; m < 4; ++m) _Pragma("unroll") for (int n = 0; n < 2; ++n) _Pragma("unroll") for (int k = 0; k < 2; ++k) \
;       acc[ai][bj][m][n] = __builtin_amdgcn_mfma_f32_16x16x32_bf16(Bt_[n][k], At_[m][k], acc[ai][bj][m][n], 0, 0, 0); \
;     __builtin_amdgcn_s_setprio(0); } while (0)
; #define G_WAIT_V(n) asm volatile("s_waitcnt vmcnt(" #n ")" ::: "memory")
; #define G_WAIT_L(n) asm volatile("s_waitcnt lgkmcnt(" #n ")" ::: "memory")
; #define G_BAR __builtin_amdgcn_s_barrier()
; #define G_SCHED __builtin_amdgcn_sched_barrier(0)
; __device__ __forceinline__ void gemm_phase(const Params& p, int l, const bf16_t* __restrict__ A, const bf16_t* __restrict__ Bt, int M, int N, int K,
;                            int epi, bf16_t* __restrict__ outp, char* smem, int wvi) {
;     ...
;         G_STAGE(G_SB(0, 1), b2 + hstep);
;         G_WAIT_V(6); G_BAR; G_MMA(1, 1, At, B1); G_BAR;
;         G_LDB(B0, 1, 0); G_SCHED; G_LDA(At, 1, 0); G_STAGE(G_SA(0, 1), a2 + hstep);
;         G_WAIT_L(8); G_BAR; G_WAIT_L(0); G_MMA(0, 0, At, B0); G_BAR; G_SCHED;
;         G_LDB(B1, 1, 1); G_STAGE(G_SB(1, 0), b3);
;         G_BAR; G_WAIT_L(0); G_MMA(0, 1, At, B1); G_BAR;
;         G_LDA(At, 1, 1); G_STAGE(G_SA(1, 0), a3);
;         G_BAR; G_WAIT_L(0); G_MMA(1, 0, At, B0); G_BAR; G_SCHED;
	s_add_u32 s12, s10, 0xb0000
	s_addc_u32 s13, s11, 0
	s_add_i32 s53, s55, s58
	v_lshl_add_u64 v[140:141], s[12:13], 0, v[176:177]
	s_mov_b32 m0, s53
	s_nop 0
	global_load_lds_dwordx4 v[140:141], off
	v_lshl_add_u64 v[140:141], s[12:13], 0, v[128:129]
	s_add_i32 m0, s53, 0x2000
	s_nop 0
	global_load_lds_dwordx4 v[140:141], off
	v_add_u32_e32 v139, 0x18000, v137
	ds_read_b128 v[140:143], v139
	ds_read_b128 v[144:147], v139 offset:1024
	ds_read_b128 v[148:151], v139 offset:2048
	ds_read_b128 v[152:155], v139 offset:3072
	s_waitcnt vmcnt(6)
	s_barrier
	v_mfma_f32_16x16x32_bf16 v[120:123], v[218:221], v[156:159], v[120:123]
	v_mfma_f32_16x16x32_bf16 v[124:127], v[226:229], v[156:159], v[124:127]
	v_mfma_f32_16x16x32_bf16 v[112:115], v[218:221], v[164:167], v[112:115]
	v_mfma_f32_16x16x32_bf16 v[116:119], v[226:229], v[164:167], v[116:119]
	v_mfma_f32_16x16x32_bf16 v[104:107], v[218:221], v[172:175], v[104:107]
	v_mfma_f32_16x16x32_bf16 v[108:111], v[226:229], v[172:175], v[108:111]
	v_mfma_f32_16x16x32_bf16 v[96:99], v[218:221], v[186:189], v[96:99]
	v_mfma_f32_16x16x32_bf16 v[100:103], v[226:229], v[186:189], v[100:103]
	v_mfma_f32_16x16x32_bf16 v[120:123], v[222:225], v[160:163], v[120:123]
	v_mfma_f32_16x16x32_bf16 v[124:127], v[230:233], v[160:163], v[124:127]
	v_mfma_f32_16x16x32_bf16 v[112:115], v[222:225], v[168:171], v[112:115]
	v_mfma_f32_16x16x32_bf16 v[116:119], v[230:233], v[168:171], v[116:119]
	v_mfma_f32_16x16x32_bf16 v[104:107], v[222:225], v[182:185], v[104:107]
	v_mfma_f32_16x16x32_bf16 v[108:111], v[230:233], v[182:185], v[108:111]
	v_mfma_f32_16x16x32_bf16 v[96:99], v[222:225], v[214:217], v[96:99]
	v_mfma_f32_16x16x32_bf16 v[100:103], v[230:233], v[214:217], v[100:103]
	s_add_i32 s53, 0, 0x18000
	s_barrier
	s_add_u32 s12, s14, 0xb0000
	s_addc_u32 s13, s15, 0
	s_mov_b32 m0, s17
	v_lshl_add_u64 v[218:219], s[12:13], 0, v[176:177]
	ds_read_b128 v[156:159], v138 offset:32768
	ds_read_b128 v[160:163], v138 offset:33792
	ds_read_b128 v[164:167], v138 offset:34816
	ds_read_b128 v[168:171], v138 offset:35840
	ds_read_b128 v[172:175], v138 offset:36864
	ds_read_b128 v[182:185], v138 offset:37888
	ds_read_b128 v[186:189], v138 offset:38912
	ds_read_b128 v[214:217], v138 offset:39936
	global_load_lds_dwordx4 v[218:219], off
	v_lshl_add_u64 v[218:219], s[12:13], 0, v[128:129]
	s_mov_b32 m0, s20
	s_nop 0
	global_load_lds_dwordx4 v[218:219], off
	s_waitcnt lgkmcnt(8)
	s_barrier
	s_waitcnt lgkmcnt(0)
	s_waitcnt lgkmcnt(0)
	v_mfma_f32_16x16x32_bf16 v[20:23], v[140:143], v[156:159], v[20:23]
	v_mfma_f32_16x16x32_bf16 v[28:31], v[148:151], v[156:159], v[28:31]
	v_mfma_f32_16x16x32_bf16 v[12:15], v[140:143], v[164:167], v[12:15]
	v_mfma_f32_16x16x32_bf16 v[24:27], v[148:151], v[164:167], v[24:27]
	v_mfma_f32_16x16x32_bf16 v[4:7], v[140:143], v[172:175], v[4:7]
	v_mfma_f32_16x16x32_bf16 v[16:19], v[148:151], v[172:175], v[16:19]
	v_mfma_f32_16x16x32_bf16 v[0:3], v[140:143], v[186:189], v[0:3]
	v_mfma_f32_16x16x32_bf16 v[8:11], v[148:151], v[186:189], v[8:11]
	v_mfma_f32_16x16x32_bf16 v[20:23], v[144:147], v[160:163], v[20:23]
	v_mfma_f32_16x16x32_bf16 v[28:31], v[152:155], v[160:163], v[28:31]
	v_mfma_f32_16x16x32_bf16 v[12:15], v[144:147], v[168:171], v[12:15]
	v_mfma_f32_16x16x32_bf16 v[24:27], v[152:155], v[168:171], v[24:27]
	v_mfma_f32_16x16x32_bf16 v[4:7], v[144:147], v[182:185], v[4:7]
	v_mfma_f32_16x16x32_bf16 v[16:19], v[152:155], v[182:185], v[16:19]
	v_mfma_f32_16x16x32_bf16 v[0:3], v[144:147], v[214:217], v[0:3]
	v_mfma_f32_16x16x32_bf16 v[8:11], v[152:155], v[214:217], v[8:11]
	s_barrier
	s_add_i32 s12, 0, 0x1c000
	s_add_i32 s13, s53, s58
	v_add_u32_e32 v139, s12, v137
	v_lshl_add_u64 v[190:191], v[190:191], 0, s[64:65]
	s_mov_b32 m0, s13
	ds_read_b128 v[218:221], v139
	ds_read_b128 v[222:225], v139 offset:1024
	ds_read_b128 v[226:229], v139 offset:2048
	ds_read_b128 v[230:233], v139 offset:3072
	global_load_lds_dwordx4 v[190:191], off
	v_lshl_add_u64 v[190:191], v[234:235], 0, s[64:65]
	s_add_i32 m0, s13, 0x2000
	s_nop 0
	global_load_lds_dwordx4 v[190:191], off
	s_barrier
	s_waitcnt lgkmcnt(0)
	s_waitcnt lgkmcnt(0)
	v_mfma_f32_16x16x32_bf16 v[80:83], v[218:221], v[156:159], v[80:83]
	v_mfma_f32_16x16x32_bf16 v[92:95], v[226:229], v[156:159], v[92:95]
	v_mfma_f32_16x16x32_bf16 v[64:67], v[218:221], v[164:167], v[64:67]
	v_mfma_f32_16x16x32_bf16 v[84:87], v[226:229], v[164:167], v[84:87]
	v_mfma_f32_16x16x32_bf16 v[52:55], v[218:221], v[172:175], v[52:55]
	v_mfma_f32_16x16x32_bf16 v[76:79], v[226:229], v[172:175], v[76:79]
	v_mfma_f32_16x16x32_bf16 v[40:43], v[218:221], v[186:189], v[40:43]
	v_mfma_f32_16x16x32_bf16 v[60:63], v[226:229], v[186:189], v[60:63]
	v_mfma_f32_16x16x32_bf16 v[80:83], v[222:225], v[160:163], v[80:83]
	v_mfma_f32_16x16x32_bf16 v[92:95], v[230:233], v[160:163], v[92:95]
	v_mfma_f32_16x16x32_bf16 v[64:67], v[222:225], v[168:171], v[64:67]
	v_mfma_f32_16x16x32_bf16 v[84:87], v[230:233], v[168:171], v[84:87]
	v_mfma_f32_16x16x32_bf16 v[52:55], v[222:225], v[182:185], v[52:55]
	v_mfma_f32_16x16x32_bf16 v[76:79], v[230:233], v[182:185], v[76:79]
	v_mfma_f32_16x16x32_bf16 v[40:43], v[222:225], v[214:217], v[40:43]
	v_mfma_f32_16x16x32_bf16 v[60:63], v[230:233], v[214:217], v[60:63]
	s_mov_b32 m0, s0
	v_lshl_add_u64 v[190:191], v[236:237], 0, s[64:65]
	s_barrier
	ds_read_b128 v[156:159], v138 offset:49152
	ds_read_b128 v[160:163], v138 offset:50176
	ds_read_b128 v[164:167], v138 offset:51200
	ds_read_b128 v[168:171], v138 offset:52224
	ds_read_b128 v[172:175], v138 offset:53248
	ds_read_b128 v[182:185], v138 offset:54272
	ds_read_b128 v[186:189], v138 offset:55296
	ds_read_b128 v[214:217], v138 offset:56320
	global_load_lds_dwordx4 v[190:191], off
	v_lshl_add_u64 v[190:191], v[238:239], 0, s[64:65]
	s_mov_b32 m0, s21
	s_nop 0
	global_load_lds_dwordx4 v[190:191], off
	s_waitcnt vmcnt(10)
	s_barrier
; __device__ __forceinline__ u32x4 mk4(unsigned a, unsigned b, unsigned c, unsigned d) { return (u32x4){a, b, c, d}; }
; #define G_STAGE(bufoff, gbase) do { _Pragma("unroll") for (int _i = 0; _i < 2; ++_i) \
;     __builtin_amdgcn_global_load_lds((const unsigned*)((const char*)(gbase) + voff[_i]), (GLAS unsigned*)(lds + (bufoff) + ldsw + _i * 8192), 16, 0, 0); } while (0)
; #define G_MMA(ai, bj, At_, Bt_) do { __builtin_amdgcn_s_setprio(1); \
;     _Pragma("unroll") for (int m = 0; m < 4; ++m) _Pragma("unroll") for (int n = 0; n < 2; ++n) _Pragma("unroll") for (int k = 0; k < 2; ++k) \
;       acc[ai][bj][m][n] = __builtin_amdgcn_mfma_f32_16x16x32_bf16(Bt_[n][k], At_[m][k], acc[ai][bj][m][n], 0, 0, 0); \
;     __builtin_amdgcn_s_setprio(0); } while (0)
; #define G_WAIT_V(n) asm volatile("s_waitcnt vmcnt(" #n ")" ::: "memory")
; #define G_BAR __builtin_amdgcn_s_barrier()
; __device__ __forceinline__ void gemm_phase(const Params& p, int l, const bf16_t* __restrict__ A, const bf16_t* __restrict__ Bt, int M, int N, int K,
;                            int epi, bf16_t* __restrict__ outp, char* smem, int wvi) {
;     ...
;         G_STAGE(G_SB(1, 1), b3 + hstep);
;         G_WAIT_V(6); G_BAR; G_MMA(1, 1, At, B1); G_BAR;
;       }
;       const int brow = pm * GBM, bcol = pn * GBM;
;     const int r0 = brow + wr * 64 + fr;
;     if (epi == EPI_PLAIN) {
; #pragma unroll
;       for (int ai = 0; ai < 2; ++ai)
; #pragma unroll
;         for (int m = 0; m < 4; ++m) {
;           bf16_t* rp = outp + (size_t)(r0 + ai * GHALF + m * 16) * N + bcol + wc * 32 + fq * 8;
; #pragma unroll
;           for (int bj = 0; bj < 2; ++bj) {
;             const f32x4 v0 = acc[ai][bj][m][0], v1 = acc[ai][bj][m][1];
;             *reinterpret_cast<u32x4*>(rp + bj * GHALF) = mk4(pk2(v0[0], v0[1]), pk2(v0[2], v0[3]), pk2(v1[0], v1[1]), pk2(v1[2], v1[3]));
;           }
;         }
	s_waitcnt lgkmcnt(0)
	s_waitcnt lgkmcnt(0)
	v_mfma_f32_16x16x32_bf16 v[68:71], v[140:143], v[156:159], v[68:71]
	v_mfma_f32_16x16x32_bf16 v[88:91], v[148:151], v[156:159], v[88:91]
	v_mfma_f32_16x16x32_bf16 v[48:51], v[140:143], v[164:167], v[48:51]
	v_mfma_f32_16x16x32_bf16 v[72:75], v[148:151], v[164:167], v[72:75]
	v_mfma_f32_16x16x32_bf16 v[36:39], v[140:143], v[172:175], v[36:39]
	v_mfma_f32_16x16x32_bf16 v[56:59], v[148:151], v[172:175], v[56:59]
	v_mfma_f32_16x16x32_bf16 v[32:35], v[140:143], v[186:189], v[32:35]
	v_mfma_f32_16x16x32_bf16 v[44:47], v[148:151], v[186:189], v[44:47]
	v_mfma_f32_16x16x32_bf16 v[68:71], v[144:147], v[160:163], v[68:71]
	v_mfma_f32_16x16x32_bf16 v[88:91], v[152:155], v[160:163], v[88:91]
	v_mfma_f32_16x16x32_bf16 v[48:51], v[144:147], v[168:171], v[48:51]
	v_mfma_f32_16x16x32_bf16 v[72:75], v[152:155], v[168:171], v[72:75]
	v_mfma_f32_16x16x32_bf16 v[36:39], v[144:147], v[182:185], v[36:39]
	v_mfma_f32_16x16x32_bf16 v[56:59], v[152:155], v[182:185], v[56:59]
	v_mfma_f32_16x16x32_bf16 v[32:35], v[144:147], v[214:217], v[32:35]
	v_mfma_f32_16x16x32_bf16 v[44:47], v[152:155], v[214:217], v[44:47]
	s_barrier
	s_add_u32 s10, s10, 0xb0080
	s_addc_u32 s11, s11, 0
	s_add_i32 s12, s12, s58
	v_lshl_add_u64 v[140:141], s[10:11], 0, v[176:177]
	s_mov_b32 m0, s12
	s_nop 0
	global_load_lds_dwordx4 v[140:141], off
	v_lshl_add_u64 v[140:141], s[10:11], 0, v[128:129]
	s_add_i32 m0, s12, 0x2000
	s_nop 0
	global_load_lds_dwordx4 v[140:141], off
	v_add_u32_e32 v139, 0x10000, v137
	ds_read_b128 v[140:143], v139
	ds_read_b128 v[144:147], v139 offset:1024
	ds_read_b128 v[148:151], v139 offset:2048
	ds_read_b128 v[152:155], v139 offset:3072
	s_waitcnt vmcnt(6)
	s_barrier
	v_mfma_f32_16x16x32_bf16 v[120:123], v[218:221], v[156:159], v[120:123]
	v_mfma_f32_16x16x32_bf16 v[124:127], v[226:229], v[156:159], v[124:127]
	v_mfma_f32_16x16x32_bf16 v[112:115], v[218:221], v[164:167], v[112:115]
	v_mfma_f32_16x16x32_bf16 v[116:119], v[226:229], v[164:167], v[116:119]
	v_mfma_f32_16x16x32_bf16 v[104:107], v[218:221], v[172:175], v[104:107]
	v_mfma_f32_16x16x32_bf16 v[108:111], v[226:229], v[172:175], v[108:111]
	v_mfma_f32_16x16x32_bf16 v[96:99], v[218:221], v[186:189], v[96:99]
	v_mfma_f32_16x16x32_bf16 v[100:103], v[226:229], v[186:189], v[100:103]
	v_mfma_f32_16x16x32_bf16 v[120:123], v[222:225], v[160:163], v[120:123]
	v_mfma_f32_16x16x32_bf16 v[124:127], v[230:233], v[160:163], v[124:127]
	v_mfma_f32_16x16x32_bf16 v[112:115], v[222:225], v[168:171], v[112:115]
	v_mfma_f32_16x16x32_bf16 v[116:119], v[230:233], v[168:171], v[116:119]
	v_mfma_f32_16x16x32_bf16 v[104:107], v[222:225], v[182:185], v[104:107]
	v_mfma_f32_16x16x32_bf16 v[108:111], v[230:233], v[182:185], v[108:111]
	v_mfma_f32_16x16x32_bf16 v[96:99], v[222:225], v[214:217], v[96:99]
	v_mfma_f32_16x16x32_bf16 v[100:103], v[230:233], v[214:217], v[100:103]
	s_add_i32 s31, s31, 2
	s_add_u32 s29, s29, 0x100
	s_addc_u32 s30, s30, 0
	s_cmp_gt_u32 s31, 41
	s_mov_b64 s[12:13], s[2:3]
	s_barrier
	s_cbranch_scc0 .LBB0_1039
	s_lshl_b32 s2, s26, 8
	v_lshl_add_u32 v250, s25, 8, v136
	s_ashr_i32 s3, s2, 31
	v_ashrrev_i32_e32 v251, 31, v250
	v_lshl_add_u64 v[252:253], s[2:3], 1, v[130:131]
	v_lshlrev_b64 v[254:255], 11, v[250:251]
	v_lshl_add_u64 v[254:255], v[252:253], 0, v[254:255]
	v_cvt_pk_bf16_f32 v20, v20, v21
	v_cvt_pk_bf16_f32 v21, v22, v23
	v_cvt_pk_bf16_f32 v22, v28, v29
	v_cvt_pk_bf16_f32 v23, v30, v31
	global_store_dwordx4 v[254:255], v[20:23], off
	v_cvt_pk_bf16_f32 v12, v12, v13
	v_cvt_pk_bf16_f32 v13, v14, v15
	v_cvt_pk_bf16_f32 v20, v80, v81
	v_cvt_pk_bf16_f32 v21, v82, v83
	v_cvt_pk_bf16_f32 v22, v92, v93
	v_cvt_pk_bf16_f32 v23, v94, v95
	global_store_dwordx4 v[254:255], v[20:23], off offset:256
	v_cvt_pk_bf16_f32 v14, v24, v25
	v_cvt_pk_bf16_f32 v15, v26, v27
	v_or_b32_e32 v20, 16, v250
	v_ashrrev_i32_e32 v21, 31, v20
	v_lshlrev_b64 v[20:21], 11, v[20:21]
	v_lshl_add_u64 v[20:21], v[252:253], 0, v[20:21]
	global_store_dwordx4 v[20:21], v[12:15], off
	v_cvt_pk_bf16_f32 v4, v4, v5
	v_cvt_pk_bf16_f32 v5, v6, v7
	v_cvt_pk_bf16_f32 v12, v64, v65
	v_cvt_pk_bf16_f32 v13, v66, v67
	v_cvt_pk_bf16_f32 v14, v84, v85
	v_cvt_pk_bf16_f32 v15, v86, v87
	global_store_dwordx4 v[20:21], v[12:15], off offset:256
	v_cvt_pk_bf16_f32 v6, v16, v17
	v_cvt_pk_bf16_f32 v7, v18, v19
	v_or_b32_e32 v12, 32, v250
	v_ashrrev_i32_e32 v13, 31, v12
	v_lshlrev_b64 v[12:13], 11, v[12:13]
	v_lshl_add_u64 v[12:13], v[252:253], 0, v[12:13]
	global_store_dwordx4 v[12:13], v[4:7], off
	v_cvt_pk_bf16_f32 v0, v0, v1
	v_cvt_pk_bf16_f32 v1, v2, v3
	v_cvt_pk_bf16_f32 v4, v52, v53
	v_cvt_pk_bf16_f32 v5, v54, v55
	v_cvt_pk_bf16_f32 v6, v76, v77
	v_cvt_pk_bf16_f32 v7, v78, v79
	global_store_dwordx4 v[12:13], v[4:7], off offset:256
	v_cvt_pk_bf16_f32 v2, v8, v9
	v_cvt_pk_bf16_f32 v3, v10, v11
	v_or_b32_e32 v4, 48, v250
	v_ashrrev_i32_e32 v5, 31, v4
	v_lshlrev_b64 v[4:5], 11, v[4:5]
	v_lshl_add_u64 v[4:5], v[252:253], 0, v[4:5]
	global_store_dwordx4 v[4:5], v[0:3], off
	s_mov_b64 s[2:3], 0x40000
	s_nop 0
	v_cvt_pk_bf16_f32 v0, v40, v41
	v_cvt_pk_bf16_f32 v1, v42, v43
	v_cvt_pk_bf16_f32 v2, v60, v61
	v_cvt_pk_bf16_f32 v3, v62, v63
	global_store_dwordx4 v[4:5], v[0:3], off offset:256
	v_lshl_add_u64 v[4:5], v[254:255], 0, s[2:3]
	s_mov_b32 s2, 0x40000
	v_add_co_u32_e32 v6, vcc, s2, v254
; __device__ __forceinline__ u32x4 mk4(unsigned a, unsigned b, unsigned c, unsigned d) { return (u32x4){a, b, c, d}; }
; __device__ __forceinline__ f32x4 zero4() { float z = 0.f; asm volatile("" : "+v"(z)); return (f32x4){z, z, z, z}; }
; __device__ __forceinline__ void gemm_phase(const Params& p, int l, const bf16_t* __restrict__ A, const bf16_t* __restrict__ Bt, int M, int N, int K,
;                            int epi, bf16_t* __restrict__ outp, char* smem, int wvi) {
;     ...
;           bf16_t* rp = outp + (size_t)(r0 + ai * GHALF + m * 16) * N + bcol + wc * 32 + fq * 8;
; #pragma unroll
;           for (int bj = 0; bj < 2; ++bj) {
;             const f32x4 v0 = acc[ai][bj][m][0], v1 = acc[ai][bj][m][1];
;             *reinterpret_cast<u32x4*>(rp + bj * GHALF) = mk4(pk2(v0[0], v0[1]), pk2(v0[2], v0[3]), pk2(v1[0], v1[1]), pk2(v1[2], v1[3]));
;           }
;         }
;     ...
;       if (!has_next) break;
; #pragma unroll
;       for (int a = 0; a < 2; ++a)
; #pragma unroll
;         for (int b = 0; b < 2; ++b)
; #pragma unroll
;           for (int m = 0; m < 4; ++m)
; #pragma unroll
;             for (int n = 0; n < 2; ++n) acc[a][b][m][n] = zero4();
;       Lw = Ln; pm = npm; pn = npn; cA = nA; cB = nB;
	v_cvt_pk_bf16_f32 v0, v68, v69
	v_cvt_pk_bf16_f32 v1, v70, v71
	v_cvt_pk_bf16_f32 v2, v88, v89
	v_cvt_pk_bf16_f32 v3, v90, v91
	v_addc_co_u32_e32 v7, vcc, 0, v255, vcc
	global_store_dwordx4 v[6:7], v[0:3], off
	s_mov_b64 s[2:3], 0x48000
	s_nop 0
	v_cvt_pk_bf16_f32 v0, v120, v121
	v_cvt_pk_bf16_f32 v1, v122, v123
	v_cvt_pk_bf16_f32 v2, v124, v125
	v_cvt_pk_bf16_f32 v3, v126, v127
	global_store_dwordx4 v[4:5], v[0:3], off offset:256
	v_lshl_add_u64 v[4:5], v[254:255], 0, s[2:3]
	s_mov_b32 s2, 0x48000
	v_add_co_u32_e32 v6, vcc, s2, v254
	v_cvt_pk_bf16_f32 v0, v48, v49
	v_cvt_pk_bf16_f32 v1, v50, v51
	v_cvt_pk_bf16_f32 v2, v72, v73
	v_cvt_pk_bf16_f32 v3, v74, v75
	v_addc_co_u32_e32 v7, vcc, 0, v255, vcc
	global_store_dwordx4 v[6:7], v[0:3], off
	s_mov_b64 s[2:3], 0x50000
	s_nop 0
	v_cvt_pk_bf16_f32 v0, v112, v113
	v_cvt_pk_bf16_f32 v1, v114, v115
	v_cvt_pk_bf16_f32 v2, v116, v117
	v_cvt_pk_bf16_f32 v3, v118, v119
	global_store_dwordx4 v[4:5], v[0:3], off offset:256
	v_lshl_add_u64 v[4:5], v[254:255], 0, s[2:3]
	s_mov_b32 s2, 0x50000
	v_add_co_u32_e32 v6, vcc, s2, v254
	v_cvt_pk_bf16_f32 v0, v36, v37
	v_cvt_pk_bf16_f32 v1, v38, v39
	v_cvt_pk_bf16_f32 v2, v56, v57
	v_cvt_pk_bf16_f32 v3, v58, v59
	v_addc_co_u32_e32 v7, vcc, 0, v255, vcc
	global_store_dwordx4 v[6:7], v[0:3], off
	s_mov_b64 s[2:3], 0x58000
	s_nop 0
	v_cvt_pk_bf16_f32 v0, v104, v105
	v_cvt_pk_bf16_f32 v1, v106, v107
	v_cvt_pk_bf16_f32 v2, v108, v109
	v_cvt_pk_bf16_f32 v3, v110, v111
	global_store_dwordx4 v[4:5], v[0:3], off offset:256
	v_lshl_add_u64 v[4:5], v[254:255], 0, s[2:3]
	s_mov_b32 s2, 0x58000
	v_add_co_u32_e32 v6, vcc, s2, v254
	v_cvt_pk_bf16_f32 v0, v32, v33
	v_cvt_pk_bf16_f32 v1, v34, v35
	v_cvt_pk_bf16_f32 v2, v44, v45
	v_cvt_pk_bf16_f32 v3, v46, v47
	v_addc_co_u32_e32 v7, vcc, 0, v255, vcc
	global_store_dwordx4 v[6:7], v[0:3], off
	s_mov_b64 s[2:3], -1
	s_and_b64 vcc, exec, s[8:9]
	v_cvt_pk_bf16_f32 v0, v96, v97
	v_cvt_pk_bf16_f32 v1, v98, v99
	v_cvt_pk_bf16_f32 v2, v100, v101
	v_cvt_pk_bf16_f32 v3, v102, v103
	global_store_dwordx4 v[4:5], v[0:3], off offset:256
	s_cbranch_vccz .LBB0_1035
	v_mov_b32_e32 v20, v177
	v_mov_b32_e32 v28, v177
	v_mov_b32_e32 v12, v177
	v_mov_b32_e32 v24, v177
	v_mov_b32_e32 v4, v177
	v_mov_b32_e32 v16, v177
	v_mov_b32_e32 v0, v177
	v_mov_b32_e32 v8, v177
	v_mov_b32_e32 v80, v177
	v_mov_b32_e32 v92, v177
	v_mov_b32_e32 v64, v177
	v_mov_b32_e32 v84, v177
	v_mov_b32_e32 v52, v177
	v_mov_b32_e32 v76, v177
	v_mov_b32_e32 v40, v177
	v_mov_b32_e32 v60, v177
	v_mov_b32_e32 v68, v177
	v_mov_b32_e32 v88, v177
	v_mov_b32_e32 v48, v177
	v_mov_b32_e32 v72, v177
	v_mov_b32_e32 v36, v177
	v_mov_b32_e32 v56, v177
	v_mov_b32_e32 v32, v177
	v_mov_b32_e32 v44, v177
	v_mov_b32_e32 v120, v177
	v_mov_b32_e32 v124, v177
	v_mov_b32_e32 v112, v177
	v_mov_b32_e32 v116, v177
	v_mov_b32_e32 v104, v177
	v_mov_b32_e32 v108, v177
	v_mov_b32_e32 v96, v177
	v_mov_b32_e32 v100, v177
	s_nop 0
	v_mov_b32_e32 v21, v20
	v_mov_b32_e32 v22, v20
	v_mov_b32_e32 v23, v20
	v_mov_b32_e32 v29, v28
	v_mov_b32_e32 v30, v28
	v_mov_b32_e32 v31, v28
	v_mov_b32_e32 v13, v12
	v_mov_b32_e32 v14, v12
	v_mov_b32_e32 v15, v12
	v_mov_b32_e32 v25, v24
	v_mov_b32_e32 v26, v24
	v_mov_b32_e32 v27, v24
	v_mov_b32_e32 v5, v4
	v_mov_b32_e32 v6, v4
	v_mov_b32_e32 v7, v4
	v_mov_b32_e32 v17, v16
	v_mov_b32_e32 v18, v16
	v_mov_b32_e32 v19, v16
	s_nop 0
	v_mov_b32_e32 v1, v0
	v_mov_b32_e32 v2, v0
	v_mov_b32_e32 v3, v0
	v_mov_b32_e32 v9, v8
	v_mov_b32_e32 v10, v8
	v_mov_b32_e32 v11, v8
	v_mov_b32_e32 v81, v80
	v_mov_b32_e32 v82, v80
	v_mov_b32_e32 v83, v80
	v_mov_b32_e32 v93, v92
	v_mov_b32_e32 v94, v92
	v_mov_b32_e32 v95, v92
	v_mov_b32_e32 v65, v64
	v_mov_b32_e32 v66, v64
	v_mov_b32_e32 v67, v64
	v_mov_b32_e32 v85, v84
	v_mov_b32_e32 v86, v84
	v_mov_b32_e32 v87, v84
	s_nop 0
	v_mov_b32_e32 v53, v52
	v_mov_b32_e32 v54, v52
	v_mov_b32_e32 v55, v52
	v_mov_b32_e32 v77, v76
	v_mov_b32_e32 v78, v76
	v_mov_b32_e32 v79, v76
	v_mov_b32_e32 v41, v40
	v_mov_b32_e32 v42, v40
	v_mov_b32_e32 v43, v40
	v_mov_b32_e32 v61, v60
	v_mov_b32_e32 v62, v60
	v_mov_b32_e32 v63, v60
	v_mov_b32_e32 v69, v68
	v_mov_b32_e32 v70, v68
	v_mov_b32_e32 v71, v68
	v_mov_b32_e32 v89, v88
	v_mov_b32_e32 v90, v88
	v_mov_b32_e32 v91, v88
	s_nop 0
	v_mov_b32_e32 v49, v48
	v_mov_b32_e32 v50, v48
	v_mov_b32_e32 v51, v48
	v_mov_b32_e32 v73, v72
	v_mov_b32_e32 v74, v72
	v_mov_b32_e32 v75, v72
	v_mov_b32_e32 v37, v36
	v_mov_b32_e32 v38, v36
	v_mov_b32_e32 v39, v36
	v_mov_b32_e32 v57, v56
	v_mov_b32_e32 v58, v56
	v_mov_b32_e32 v59, v56
	v_mov_b32_e32 v33, v32
	v_mov_b32_e32 v34, v32
	v_mov_b32_e32 v35, v32
	v_mov_b32_e32 v45, v44
	v_mov_b32_e32 v46, v44
	v_mov_b32_e32 v47, v44
	s_nop 0
	v_mov_b32_e32 v121, v120
	v_mov_b32_e32 v122, v120
	v_mov_b32_e32 v123, v120
	v_mov_b32_e32 v125, v124
	v_mov_b32_e32 v126, v124
	v_mov_b32_e32 v127, v124
	v_mov_b32_e32 v113, v112
	v_mov_b32_e32 v114, v112
	v_mov_b32_e32 v115, v112
	v_mov_b32_e32 v117, v116
	v_mov_b32_e32 v118, v116
	v_mov_b32_e32 v119, v116
	v_mov_b32_e32 v105, v104
	v_mov_b32_e32 v106, v104
	v_mov_b32_e32 v107, v104
	v_mov_b32_e32 v109, v108
	v_mov_b32_e32 v110, v108
	v_mov_b32_e32 v111, v108
	s_mov_b64 s[2:3], 0
	v_mov_b32_e32 v97, v96
	v_mov_b32_e32 v98, v96
	v_mov_b32_e32 v99, v96
	v_mov_b32_e32 v101, v100
	v_mov_b32_e32 v102, v100
	v_mov_b32_e32 v103, v100
	s_branch .LBB0_1035

; #define G_STAGE(bufoff, gbase) do { _Pragma("unroll") for (int _i = 0; _i < 2; ++_i) \
;     __builtin_amdgcn_global_load_lds((const unsigned*)((const char*)(gbase) + voff[_i]), (GLAS unsigned*)(lds + (bufoff) + ldsw + _i * 8192), 16, 0, 0); } while (0)
; #define G_LDA(dst, b, h) do { _Pragma("unroll") for (int m = 0; m < 4; ++m) _Pragma("unroll") for (int k = 0; k < 2; ++k) \
;     dst[m][k] = *(const GLAS bf16x8*)(lds + G_SA(b, h) + aoff + m * 2048 + k * 1024); } while (0)
; #define G_LDB(dst, b, h) do { _Pragma("unroll") for (int n = 0; n < 2; ++n) _Pragma("unroll") for (int k = 0; k < 2; ++k) \
;     dst[n][k] = *(const GLAS bf16x8*)(lds + G_SB(b, h) + boff + n * 2048 + k * 1024); } while (0)
; #define G_MMA(ai, bj, At_, Bt_) do { __builtin_amdgcn_s_setprio(1); \
;     _Pragma("unroll") for (int m = 0; m < 4; ++m) _Pragma("unroll") for (int n = 0; n < 2; ++n) _Pragma("unroll") for (int k = 0; k < 2; ++k) \
;       acc[ai][bj][m][n] = __builtin_amdgcn_mfma_f32_16x16x32_bf16(Bt_[n][k], At_[m][k], acc[ai][bj][m][n], 0, 0, 0); \
;     __builtin_amdgcn_s_setprio(0); } while (0)
; #define G_WAIT_L(n) asm volatile("s_waitcnt lgkmcnt(" #n ")" ::: "memory")
; #define G_BAR __builtin_amdgcn_s_barrier()
; #define G_SCHED __builtin_amdgcn_sched_barrier(0)
; __device__ __forceinline__ void gemm_phase(const Params& p, int l, const bf16_t* __restrict__ A, const bf16_t* __restrict__ Bt, int M, int N, int K,
;                            int epi, bf16_t* __restrict__ outp, char* smem, int wvi) {
;     ...
;       for (int t = 0; t < nt; t += 2) {
;         const bool lastt = (t == nt - 2);
;         const char* a1 = cA + (size_t)(t + 1) * kstep;
;         const char* a2 = lastt ? nA : cA + (size_t)(t + 2) * kstep; const char* b2 = lastt ? nB : cB + (size_t)(t + 2) * kstep;
;         const char* a3 = a2 + kstep; const char* b3 = b2 + kstep;
;         G_LDB(B0, 0, 0); G_SCHED; G_LDA(At, 0, 0); G_STAGE(G_SA(1, 1), a1 + hstep);
;         G_WAIT_L(8); G_BAR; G_WAIT_L(0); G_MMA(0, 0, At, B0); G_BAR; G_SCHED;
;         G_LDB(B1, 0, 1); G_STAGE(G_SB(0, 0), b2);
;         G_BAR; G_WAIT_L(0); G_MMA(0, 1, At, B1); G_BAR;
;         G_LDA(At, 0, 1); G_STAGE(G_SA(0, 0), a2);
;         G_BAR; G_WAIT_L(0); G_MMA(1, 0, At, B0); G_BAR; G_SCHED;
.LBB0_1199:
	s_add_u32 s2, s16, 0x100
	s_addc_u32 s3, s17, 0
	s_add_i32 s24, 0, 0x10000
	s_cmp_eq_u32 s23, 12
	s_cselect_b32 s29, s9, s3
	s_cselect_b32 s28, s8, s2
	s_cselect_b32 s15, s7, s22
	s_cselect_b32 s14, s5, s21
	v_lshl_add_u64 v[136:137], s[16:17], 0, v[132:133]
	s_add_i32 m0, s30, 0xc000
	ds_read_b128 v[158:161], v140
	ds_read_b128 v[162:165], v140 offset:1024
	ds_read_b128 v[166:169], v140 offset:2048
	ds_read_b128 v[170:173], v140 offset:3072
	ds_read_b128 v[182:185], v140 offset:4096
	ds_read_b128 v[186:189], v140 offset:5120
	ds_read_b128 v[214:217], v140 offset:6144
	ds_read_b128 v[218:221], v140 offset:7168
	global_load_lds_dwordx4 v[136:137], off
	v_lshl_add_u64 v[136:137], s[16:17], 0, v[134:135]
	s_add_i32 m0, s30, 0xe000
	s_nop 0
	global_load_lds_dwordx4 v[136:137], off
	s_waitcnt lgkmcnt(8)
	s_barrier
	s_waitcnt lgkmcnt(0)
	s_waitcnt lgkmcnt(0)
	v_mfma_f32_16x16x32_bf16 v[120:123], v[142:145], v[158:161], v[120:123]
	v_mfma_f32_16x16x32_bf16 v[124:127], v[150:153], v[158:161], v[124:127]
	v_mfma_f32_16x16x32_bf16 v[104:107], v[142:145], v[166:169], v[104:107]
	v_mfma_f32_16x16x32_bf16 v[108:111], v[150:153], v[166:169], v[108:111]
	v_mfma_f32_16x16x32_bf16 v[88:91], v[142:145], v[182:185], v[88:91]
	v_mfma_f32_16x16x32_bf16 v[92:95], v[150:153], v[182:185], v[92:95]
	v_mfma_f32_16x16x32_bf16 v[72:75], v[142:145], v[214:217], v[72:75]
	v_mfma_f32_16x16x32_bf16 v[76:79], v[150:153], v[214:217], v[76:79]
	v_mfma_f32_16x16x32_bf16 v[120:123], v[146:149], v[162:165], v[120:123]
	v_mfma_f32_16x16x32_bf16 v[124:127], v[154:157], v[162:165], v[124:127]
	v_mfma_f32_16x16x32_bf16 v[104:107], v[146:149], v[170:173], v[104:107]
	v_mfma_f32_16x16x32_bf16 v[108:111], v[154:157], v[170:173], v[108:111]
	v_mfma_f32_16x16x32_bf16 v[88:91], v[146:149], v[186:189], v[88:91]
	v_mfma_f32_16x16x32_bf16 v[92:95], v[154:157], v[186:189], v[92:95]
	v_mfma_f32_16x16x32_bf16 v[72:75], v[146:149], v[218:221], v[72:75]
	v_mfma_f32_16x16x32_bf16 v[76:79], v[154:157], v[218:221], v[76:79]
	s_barrier
	s_add_i32 s25, 0, 0x14000
	v_add_u32_e32 v136, s25, v139
	s_add_i32 s16, s24, s58
	ds_read_b128 v[222:225], v136
	ds_read_b128 v[226:229], v136 offset:1024
	ds_read_b128 v[230:233], v136 offset:2048
	ds_read_b128 v[234:237], v136 offset:3072
	v_lshl_add_u64 v[136:137], s[14:15], 0, v[176:177]
	s_mov_b32 m0, s16
	v_lshl_add_u64 v[174:175], s[14:15], 0, v[128:129]
	global_load_lds_dwordx4 v[136:137], off
	s_add_i32 m0, s16, 0x2000
	s_nop 0
	global_load_lds_dwordx4 v[174:175], off
	s_barrier
	s_waitcnt lgkmcnt(0)
	s_waitcnt lgkmcnt(0)
	v_mfma_f32_16x16x32_bf16 v[112:115], v[222:225], v[158:161], v[112:115]
	v_mfma_f32_16x16x32_bf16 v[116:119], v[230:233], v[158:161], v[116:119]
	v_mfma_f32_16x16x32_bf16 v[96:99], v[222:225], v[166:169], v[96:99]
	v_mfma_f32_16x16x32_bf16 v[100:103], v[230:233], v[166:169], v[100:103]
	v_mfma_f32_16x16x32_bf16 v[80:83], v[222:225], v[182:185], v[80:83]
	v_mfma_f32_16x16x32_bf16 v[84:87], v[230:233], v[182:185], v[84:87]
	v_mfma_f32_16x16x32_bf16 v[64:67], v[222:225], v[214:217], v[64:67]
	v_mfma_f32_16x16x32_bf16 v[68:71], v[230:233], v[214:217], v[68:71]
	v_mfma_f32_16x16x32_bf16 v[112:115], v[226:229], v[162:165], v[112:115]
	v_mfma_f32_16x16x32_bf16 v[116:119], v[234:237], v[162:165], v[116:119]
	v_mfma_f32_16x16x32_bf16 v[96:99], v[226:229], v[170:173], v[96:99]
	v_mfma_f32_16x16x32_bf16 v[100:103], v[234:237], v[170:173], v[100:103]
	v_mfma_f32_16x16x32_bf16 v[80:83], v[226:229], v[186:189], v[80:83]
	v_mfma_f32_16x16x32_bf16 v[84:87], v[234:237], v[186:189], v[84:87]
	v_mfma_f32_16x16x32_bf16 v[64:67], v[226:229], v[218:221], v[64:67]
	v_mfma_f32_16x16x32_bf16 v[68:71], v[234:237], v[218:221], v[68:71]
	s_mov_b32 m0, s30
	v_lshl_add_u64 v[190:191], s[28:29], 0, v[176:177]
	s_barrier
	ds_read_b128 v[158:161], v140 offset:16384
	ds_read_b128 v[162:165], v140 offset:17408
	ds_read_b128 v[166:169], v140 offset:18432
	ds_read_b128 v[170:173], v140 offset:19456
	ds_read_b128 v[182:185], v140 offset:20480
	ds_read_b128 v[186:189], v140 offset:21504
	ds_read_b128 v[214:217], v140 offset:22528
	ds_read_b128 v[218:221], v140 offset:23552
	global_load_lds_dwordx4 v[190:191], off
	v_lshl_add_u64 v[238:239], s[28:29], 0, v[128:129]
	s_mov_b32 m0, s31
	s_nop 0
	global_load_lds_dwordx4 v[238:239], off
	s_waitcnt vmcnt(10)
	s_barrier
	s_waitcnt lgkmcnt(0)
	s_waitcnt lgkmcnt(0)
	v_mfma_f32_16x16x32_bf16 v[56:59], v[142:145], v[158:161], v[56:59]
	v_mfma_f32_16x16x32_bf16 v[60:63], v[150:153], v[158:161], v[60:63]
	v_mfma_f32_16x16x32_bf16 v[40:43], v[142:145], v[166:169], v[40:43]
	v_mfma_f32_16x16x32_bf16 v[44:47], v[150:153], v[166:169], v[44:47]
	v_mfma_f32_16x16x32_bf16 v[24:27], v[142:145], v[182:185], v[24:27]
	v_mfma_f32_16x16x32_bf16 v[28:31], v[150:153], v[182:185], v[28:31]
	v_mfma_f32_16x16x32_bf16 v[8:11], v[142:145], v[214:217], v[8:11]
	v_mfma_f32_16x16x32_bf16 v[12:15], v[150:153], v[214:217], v[12:15]
	v_mfma_f32_16x16x32_bf16 v[56:59], v[146:149], v[162:165], v[56:59]
	v_mfma_f32_16x16x32_bf16 v[60:63], v[154:157], v[162:165], v[60:63]
	v_mfma_f32_16x16x32_bf16 v[40:43], v[146:149], v[170:173], v[40:43]
	v_mfma_f32_16x16x32_bf16 v[44:47], v[154:157], v[170:173], v[44:47]
	v_mfma_f32_16x16x32_bf16 v[24:27], v[146:149], v[186:189], v[24:27]
	v_mfma_f32_16x16x32_bf16 v[28:31], v[154:157], v[186:189], v[28:31]
	v_mfma_f32_16x16x32_bf16 v[8:11], v[146:149], v[218:221], v[8:11]
	v_mfma_f32_16x16x32_bf16 v[12:15], v[154:157], v[218:221], v[12:15]
	s_barrier
; #define G_STAGE(bufoff, gbase) do { _Pragma("unroll") for (int _i = 0; _i < 2; ++_i) \
;     __builtin_amdgcn_global_load_lds((const unsigned*)((const char*)(gbase) + voff[_i]), (GLAS unsigned*)(lds + (bufoff) + ldsw + _i * 8192), 16, 0, 0); } while (0)
; #define G_LDA(dst, b, h) do { _Pragma("unroll") for (int m = 0; m < 4; ++m) _Pragma("unroll") for (int k = 0; k < 2; ++k) \
;     dst[m][k] = *(const GLAS bf16x8*)(lds + G_SA(b, h) + aoff + m * 2048 + k * 1024); } while (0)
; #define G_LDB(dst, b, h) do { _Pragma("unroll") for (int n = 0; n < 2; ++n) _Pragma("unroll") for (int k = 0; k < 2; ++k) \
;     dst[n][k] = *(const GLAS bf16x8*)(lds + G_SB(b, h) + boff + n * 2048 + k * 1024); } while (0)
; #define G_MMA(ai, bj, At_, Bt_) do { __builtin_amdgcn_s_setprio(1); \
;     _Pragma("unroll") for (int m = 0; m < 4; ++m) _Pragma("unroll") for (int n = 0; n < 2; ++n) _Pragma("unroll") for (int k = 0; k < 2; ++k) \
;       acc[ai][bj][m][n] = __builtin_amdgcn_mfma_f32_16x16x32_bf16(Bt_[n][k], At_[m][k], acc[ai][bj][m][n], 0, 0, 0); \
;     __builtin_amdgcn_s_setprio(0); } while (0)
; #define G_WAIT_V(n) asm volatile("s_waitcnt vmcnt(" #n ")" ::: "memory")
; #define G_WAIT_L(n) asm volatile("s_waitcnt lgkmcnt(" #n ")" ::: "memory")
; #define G_BAR __builtin_amdgcn_s_barrier()
; #define G_SCHED __builtin_amdgcn_sched_barrier(0)
; __device__ __forceinline__ void gemm_phase(const Params& p, int l, const bf16_t* __restrict__ A, const bf16_t* __restrict__ Bt, int M, int N, int K,
;                            int epi, bf16_t* __restrict__ outp, char* smem, int wvi) {
;     ...
;         G_STAGE(G_SB(0, 1), b2 + hstep);
;         G_WAIT_V(6); G_BAR; G_MMA(1, 1, At, B1); G_BAR;
;         G_LDB(B0, 1, 0); G_SCHED; G_LDA(At, 1, 0); G_STAGE(G_SA(0, 1), a2 + hstep);
;         G_WAIT_L(8); G_BAR; G_WAIT_L(0); G_MMA(0, 0, At, B0); G_BAR; G_SCHED;
;         G_LDB(B1, 1, 1); G_STAGE(G_SB(1, 0), b3);
;         G_BAR; G_WAIT_L(0); G_MMA(0, 1, At, B1); G_BAR;
;         G_LDA(At, 1, 1); G_STAGE(G_SA(1, 0), a3);
;         G_BAR; G_WAIT_L(0); G_MMA(1, 0, At, B0); G_BAR; G_SCHED;
	s_add_u32 s16, s14, 0x40000
	s_addc_u32 s17, s15, 0
	s_add_i32 s24, s25, s58
	v_lshl_add_u64 v[142:143], s[16:17], 0, v[176:177]
	s_mov_b32 m0, s24
	s_nop 0
	global_load_lds_dwordx4 v[142:143], off
	v_lshl_add_u64 v[142:143], s[16:17], 0, v[128:129]
	s_add_i32 m0, s24, 0x2000
	s_nop 0
	global_load_lds_dwordx4 v[142:143], off
	v_add_u32_e32 v141, 0x18000, v139
	ds_read_b128 v[142:145], v141
	ds_read_b128 v[146:149], v141 offset:1024
	ds_read_b128 v[150:153], v141 offset:2048
	ds_read_b128 v[154:157], v141 offset:3072
	s_waitcnt vmcnt(6)
	s_barrier
	v_mfma_f32_16x16x32_bf16 v[48:51], v[222:225], v[158:161], v[48:51]
	v_mfma_f32_16x16x32_bf16 v[52:55], v[230:233], v[158:161], v[52:55]
	v_mfma_f32_16x16x32_bf16 v[32:35], v[222:225], v[166:169], v[32:35]
	v_mfma_f32_16x16x32_bf16 v[36:39], v[230:233], v[166:169], v[36:39]
	v_mfma_f32_16x16x32_bf16 v[16:19], v[222:225], v[182:185], v[16:19]
	v_mfma_f32_16x16x32_bf16 v[20:23], v[230:233], v[182:185], v[20:23]
	v_mfma_f32_16x16x32_bf16 v[0:3], v[222:225], v[214:217], v[0:3]
	v_mfma_f32_16x16x32_bf16 v[4:7], v[230:233], v[214:217], v[4:7]
	v_mfma_f32_16x16x32_bf16 v[48:51], v[226:229], v[162:165], v[48:51]
	v_mfma_f32_16x16x32_bf16 v[52:55], v[234:237], v[162:165], v[52:55]
	v_mfma_f32_16x16x32_bf16 v[32:35], v[226:229], v[170:173], v[32:35]
	v_mfma_f32_16x16x32_bf16 v[36:39], v[234:237], v[170:173], v[36:39]
	v_mfma_f32_16x16x32_bf16 v[16:19], v[226:229], v[186:189], v[16:19]
	v_mfma_f32_16x16x32_bf16 v[20:23], v[234:237], v[186:189], v[20:23]
	v_mfma_f32_16x16x32_bf16 v[0:3], v[226:229], v[218:221], v[0:3]
	v_mfma_f32_16x16x32_bf16 v[4:7], v[234:237], v[218:221], v[4:7]
	s_add_i32 s24, 0, 0x18000
	s_barrier
	s_add_u32 s16, s28, 0x40000
	s_addc_u32 s17, s29, 0
	s_mov_b32 m0, s55
	v_lshl_add_u64 v[222:223], s[16:17], 0, v[176:177]
	ds_read_b128 v[158:161], v140 offset:32768
	ds_read_b128 v[162:165], v140 offset:33792
	ds_read_b128 v[166:169], v140 offset:34816
	ds_read_b128 v[170:173], v140 offset:35840
	ds_read_b128 v[182:185], v140 offset:36864
	ds_read_b128 v[186:189], v140 offset:37888
	ds_read_b128 v[214:217], v140 offset:38912
	ds_read_b128 v[218:221], v140 offset:39936
	global_load_lds_dwordx4 v[222:223], off
	v_lshl_add_u64 v[222:223], s[16:17], 0, v[128:129]
	s_mov_b32 m0, s88
	s_nop 0
	global_load_lds_dwordx4 v[222:223], off
	s_waitcnt lgkmcnt(8)
	s_barrier
	s_waitcnt lgkmcnt(0)
	s_waitcnt lgkmcnt(0)
	v_mfma_f32_16x16x32_bf16 v[120:123], v[142:145], v[158:161], v[120:123]
	v_mfma_f32_16x16x32_bf16 v[124:127], v[150:153], v[158:161], v[124:127]
	v_mfma_f32_16x16x32_bf16 v[104:107], v[142:145], v[166:169], v[104:107]
	v_mfma_f32_16x16x32_bf16 v[108:111], v[150:153], v[166:169], v[108:111]
	v_mfma_f32_16x16x32_bf16 v[88:91], v[142:145], v[182:185], v[88:91]
	v_mfma_f32_16x16x32_bf16 v[92:95], v[150:153], v[182:185], v[92:95]
	v_mfma_f32_16x16x32_bf16 v[72:75], v[142:145], v[214:217], v[72:75]
	v_mfma_f32_16x16x32_bf16 v[76:79], v[150:153], v[214:217], v[76:79]
	v_mfma_f32_16x16x32_bf16 v[120:123], v[146:149], v[162:165], v[120:123]
	v_mfma_f32_16x16x32_bf16 v[124:127], v[154:157], v[162:165], v[124:127]
	v_mfma_f32_16x16x32_bf16 v[104:107], v[146:149], v[170:173], v[104:107]
	v_mfma_f32_16x16x32_bf16 v[108:111], v[154:157], v[170:173], v[108:111]
	v_mfma_f32_16x16x32_bf16 v[88:91], v[146:149], v[186:189], v[88:91]
	v_mfma_f32_16x16x32_bf16 v[92:95], v[154:157], v[186:189], v[92:95]
	v_mfma_f32_16x16x32_bf16 v[72:75], v[146:149], v[218:221], v[72:75]
	v_mfma_f32_16x16x32_bf16 v[76:79], v[154:157], v[218:221], v[76:79]
	s_barrier
	s_add_i32 s16, 0, 0x1c000
	s_add_i32 s17, s24, s58
	v_add_u32_e32 v141, s16, v139
	v_lshl_add_u64 v[136:137], v[136:137], 0, s[64:65]
	s_mov_b32 m0, s17
	ds_read_b128 v[222:225], v141
	ds_read_b128 v[226:229], v141 offset:1024
	ds_read_b128 v[230:233], v141 offset:2048
	ds_read_b128 v[234:237], v141 offset:3072
	global_load_lds_dwordx4 v[136:137], off
	v_lshl_add_u64 v[136:137], v[174:175], 0, s[64:65]
	s_add_i32 m0, s17, 0x2000
	s_nop 0
	global_load_lds_dwordx4 v[136:137], off
	s_barrier
	s_waitcnt lgkmcnt(0)
	s_waitcnt lgkmcnt(0)
	v_mfma_f32_16x16x32_bf16 v[112:115], v[222:225], v[158:161], v[112:115]
	v_mfma_f32_16x16x32_bf16 v[116:119], v[230:233], v[158:161], v[116:119]
	v_mfma_f32_16x16x32_bf16 v[96:99], v[222:225], v[166:169], v[96:99]
	v_mfma_f32_16x16x32_bf16 v[100:103], v[230:233], v[166:169], v[100:103]
	v_mfma_f32_16x16x32_bf16 v[80:83], v[222:225], v[182:185], v[80:83]
	v_mfma_f32_16x16x32_bf16 v[84:87], v[230:233], v[182:185], v[84:87]
	v_mfma_f32_16x16x32_bf16 v[64:67], v[222:225], v[214:217], v[64:67]
	v_mfma_f32_16x16x32_bf16 v[68:71], v[230:233], v[214:217], v[68:71]
	v_mfma_f32_16x16x32_bf16 v[112:115], v[226:229], v[162:165], v[112:115]
	v_mfma_f32_16x16x32_bf16 v[116:119], v[234:237], v[162:165], v[116:119]
	v_mfma_f32_16x16x32_bf16 v[96:99], v[226:229], v[170:173], v[96:99]
	v_mfma_f32_16x16x32_bf16 v[100:103], v[234:237], v[170:173], v[100:103]
	v_mfma_f32_16x16x32_bf16 v[80:83], v[226:229], v[186:189], v[80:83]
	v_mfma_f32_16x16x32_bf16 v[84:87], v[234:237], v[186:189], v[84:87]
	v_mfma_f32_16x16x32_bf16 v[64:67], v[226:229], v[218:221], v[64:67]
	v_mfma_f32_16x16x32_bf16 v[68:71], v[234:237], v[218:221], v[68:71]
	s_mov_b32 m0, s89
	v_lshl_add_u64 v[136:137], v[190:191], 0, s[64:65]
	s_barrier
	ds_read_b128 v[158:161], v140 offset:49152
	ds_read_b128 v[162:165], v140 offset:50176
	ds_read_b128 v[166:169], v140 offset:51200
	ds_read_b128 v[170:173], v140 offset:52224
	ds_read_b128 v[182:185], v140 offset:53248
	ds_read_b128 v[186:189], v140 offset:54272
	ds_read_b128 v[214:217], v140 offset:55296
	ds_read_b128 v[218:221], v140 offset:56320
	global_load_lds_dwordx4 v[136:137], off
	v_lshl_add_u64 v[136:137], v[238:239], 0, s[64:65]
	s_mov_b32 m0, s92
	s_nop 0
	global_load_lds_dwordx4 v[136:137], off
	s_waitcnt vmcnt(10)
	s_barrier
; __device__ __forceinline__ u32x4 mk4(unsigned a, unsigned b, unsigned c, unsigned d) { return (u32x4){a, b, c, d}; }
; __device__ __forceinline__ float silu_f(float x) { return x * __builtin_amdgcn_rcpf(1.f + __expf(-x)); }
; #define G_STAGE(bufoff, gbase) do { _Pragma("unroll") for (int _i = 0; _i < 2; ++_i) \
;     __builtin_amdgcn_global_load_lds((const unsigned*)((const char*)(gbase) + voff[_i]), (GLAS unsigned*)(lds + (bufoff) + ldsw + _i * 8192), 16, 0, 0); } while (0)
; #define G_MMA(ai, bj, At_, Bt_) do { __builtin_amdgcn_s_setprio(1); \
;     _Pragma("unroll") for (int m = 0; m < 4; ++m) _Pragma("unroll") for (int n = 0; n < 2; ++n) _Pragma("unroll") for (int k = 0; k < 2; ++k) \
;       acc[ai][bj][m][n] = __builtin_amdgcn_mfma_f32_16x16x32_bf16(Bt_[n][k], At_[m][k], acc[ai][bj][m][n], 0, 0, 0); \
;     __builtin_amdgcn_s_setprio(0); } while (0)
; #define G_WAIT_V(n) asm volatile("s_waitcnt vmcnt(" #n ")" ::: "memory")
; #define G_WAIT_L(n) asm volatile("s_waitcnt lgkmcnt(" #n ")" ::: "memory")
; #define G_BAR __builtin_amdgcn_s_barrier()
; #define G_SCHED __builtin_amdgcn_sched_barrier(0)
; __device__ __forceinline__ void gemm_phase(const Params& p, int l, const bf16_t* __restrict__ A, const bf16_t* __restrict__ Bt, int M, int N, int K,
;                            int epi, bf16_t* __restrict__ outp, char* smem, int wvi) {
;     ...
;         G_BAR; G_WAIT_L(0); G_MMA(1, 0, At, B0); G_BAR; G_SCHED;
;         G_STAGE(G_SB(1, 1), b3 + hstep);
;         G_WAIT_V(6); G_BAR; G_MMA(1, 1, At, B1); G_BAR;
;       }
;     ...
;     } else if (epi == EPI_SWIGLU) {
; #pragma unroll
;       for (int ai = 0; ai < 2; ++ai)
; #pragma unroll
;         for (int m = 0; m < 4; ++m) {
;           bf16_t* rp = outp + (size_t)(r0 + ai * GHALF + m * 16) * DFF + pn * 128 + wc * 32 + fq * 8;
;           unsigned pk[4];
; #pragma unroll
;           for (int bj = 0; bj < 2; ++bj) {
;             const f32x4 g = acc[ai][bj][m][0], u = acc[ai][bj][m][1];
;             const float o0 = silu_f(g[0]) * u[0], o1 = silu_f(g[1]) * u[1], o2 = silu_f(g[2]) * u[2], o3 = silu_f(g[3]) * u[3];
;             pk[2 * bj] = pk2(o0, o1); pk[2 * bj + 1] = pk2(o2, o3);
;           }
;           *reinterpret_cast<u32x4*>(rp) = mk4(pk[0], pk[1], pk[2], pk[3]);
;         }
	s_waitcnt lgkmcnt(0)
	s_waitcnt lgkmcnt(0)
	v_mfma_f32_16x16x32_bf16 v[56:59], v[142:145], v[158:161], v[56:59]
	v_mfma_f32_16x16x32_bf16 v[60:63], v[150:153], v[158:161], v[60:63]
	v_mfma_f32_16x16x32_bf16 v[40:43], v[142:145], v[166:169], v[40:43]
	v_mfma_f32_16x16x32_bf16 v[44:47], v[150:153], v[166:169], v[44:47]
	v_mfma_f32_16x16x32_bf16 v[24:27], v[142:145], v[182:185], v[24:27]
	v_mfma_f32_16x16x32_bf16 v[28:31], v[150:153], v[182:185], v[28:31]
	v_mfma_f32_16x16x32_bf16 v[8:11], v[142:145], v[214:217], v[8:11]
	v_mfma_f32_16x16x32_bf16 v[12:15], v[150:153], v[214:217], v[12:15]
	v_mfma_f32_16x16x32_bf16 v[56:59], v[146:149], v[162:165], v[56:59]
	v_mfma_f32_16x16x32_bf16 v[60:63], v[154:157], v[162:165], v[60:63]
	v_mfma_f32_16x16x32_bf16 v[40:43], v[146:149], v[170:173], v[40:43]
	v_mfma_f32_16x16x32_bf16 v[44:47], v[154:157], v[170:173], v[44:47]
	v_mfma_f32_16x16x32_bf16 v[24:27], v[146:149], v[186:189], v[24:27]
	v_mfma_f32_16x16x32_bf16 v[28:31], v[154:157], v[186:189], v[28:31]
	v_mfma_f32_16x16x32_bf16 v[8:11], v[146:149], v[218:221], v[8:11]
	v_mfma_f32_16x16x32_bf16 v[12:15], v[154:157], v[218:221], v[12:15]
	s_barrier
	s_add_u32 s14, s14, 0x40080
	s_addc_u32 s15, s15, 0
	s_add_i32 s16, s16, s58
	v_lshl_add_u64 v[136:137], s[14:15], 0, v[176:177]
	s_mov_b32 m0, s16
	s_nop 0
	global_load_lds_dwordx4 v[136:137], off
	v_lshl_add_u64 v[136:137], s[14:15], 0, v[128:129]
	s_add_i32 m0, s16, 0x2000
	s_nop 0
	global_load_lds_dwordx4 v[136:137], off
	v_add_u32_e32 v136, 0x10000, v139
	ds_read_b128 v[142:145], v136
	ds_read_b128 v[146:149], v136 offset:1024
	ds_read_b128 v[150:153], v136 offset:2048
	ds_read_b128 v[154:157], v136 offset:3072
	s_waitcnt vmcnt(6)
	s_barrier
	v_mfma_f32_16x16x32_bf16 v[48:51], v[222:225], v[158:161], v[48:51]
	v_mfma_f32_16x16x32_bf16 v[52:55], v[230:233], v[158:161], v[52:55]
	v_mfma_f32_16x16x32_bf16 v[32:35], v[222:225], v[166:169], v[32:35]
	v_mfma_f32_16x16x32_bf16 v[36:39], v[230:233], v[166:169], v[36:39]
	v_mfma_f32_16x16x32_bf16 v[16:19], v[222:225], v[182:185], v[16:19]
	v_mfma_f32_16x16x32_bf16 v[20:23], v[230:233], v[182:185], v[20:23]
	v_mfma_f32_16x16x32_bf16 v[0:3], v[222:225], v[214:217], v[0:3]
	v_mfma_f32_16x16x32_bf16 v[4:7], v[230:233], v[214:217], v[4:7]
	v_mfma_f32_16x16x32_bf16 v[48:51], v[226:229], v[162:165], v[48:51]
	v_mfma_f32_16x16x32_bf16 v[52:55], v[234:237], v[162:165], v[52:55]
	v_mfma_f32_16x16x32_bf16 v[32:35], v[226:229], v[170:173], v[32:35]
	v_mfma_f32_16x16x32_bf16 v[36:39], v[234:237], v[170:173], v[36:39]
	v_mfma_f32_16x16x32_bf16 v[16:19], v[226:229], v[186:189], v[16:19]
	v_mfma_f32_16x16x32_bf16 v[20:23], v[234:237], v[186:189], v[20:23]
	v_mfma_f32_16x16x32_bf16 v[0:3], v[226:229], v[218:221], v[0:3]
	v_mfma_f32_16x16x32_bf16 v[4:7], v[234:237], v[218:221], v[4:7]
	s_add_i32 s23, s23, 2
	s_add_u32 s21, s21, 0x100
	s_addc_u32 s22, s22, 0
	s_cmp_gt_u32 s23, 13
	s_mov_b64 s[16:17], s[2:3]
	s_barrier
	s_cbranch_scc0 .LBB0_1199
	v_mul_f32_e32 v252, 0xbfb8aa3b, v120
	v_mul_f32_e32 v253, 0xbfb8aa3b, v121
	v_exp_f32_e32 v252, v252
	v_exp_f32_e32 v253, v253
	v_lshl_add_u32 v141, s0, 8, v138
	s_lshl_b32 s0, s1, 7
	v_add_f32_e32 v252, 1.0, v252
	v_add_f32_e32 v253, 1.0, v253
	v_rcp_f32_e32 v252, v252
	v_rcp_f32_e32 v253, v253
	s_ashr_i32 s1, s0, 31
	v_lshl_add_u64 v[136:137], s[0:1], 1, v[130:131]
	s_movk_i32 s2, 0x1600
	v_pk_mul_f32 v[120:121], v[120:121], v[252:253]
	s_and_b64 vcc, exec, s[12:13]
	v_pk_mul_f32 v[120:121], v[124:125], v[120:121]
	v_mul_f32_e32 v124, 0xbfb8aa3b, v122
	v_mul_f32_e32 v125, 0xbfb8aa3b, v123
	v_exp_f32_e32 v124, v124
	v_exp_f32_e32 v125, v125
	v_cvt_pk_bf16_f32 v120, v120, v121
	v_add_f32_e32 v124, 1.0, v124
	v_add_f32_e32 v125, 1.0, v125
	v_rcp_f32_e32 v124, v124
	v_rcp_f32_e32 v125, v125
	s_nop 0
	v_pk_mul_f32 v[122:123], v[122:123], v[124:125]
	s_nop 0
	v_pk_mul_f32 v[122:123], v[126:127], v[122:123]
	s_nop 0
	v_cvt_pk_bf16_f32 v121, v122, v123
	v_mul_f32_e32 v122, 0xbfb8aa3b, v112
	v_mul_f32_e32 v123, 0xbfb8aa3b, v113
	v_exp_f32_e32 v122, v122
	v_exp_f32_e32 v123, v123
	v_add_f32_e32 v122, 1.0, v122
	v_add_f32_e32 v123, 1.0, v123
	v_rcp_f32_e32 v122, v122
	v_rcp_f32_e32 v123, v123
	s_nop 0
	v_pk_mul_f32 v[112:113], v[112:113], v[122:123]
	s_nop 0
	v_pk_mul_f32 v[112:113], v[116:117], v[112:113]
	v_mul_f32_e32 v116, 0xbfb8aa3b, v114
	v_mul_f32_e32 v117, 0xbfb8aa3b, v115
	v_exp_f32_e32 v116, v116
	v_exp_f32_e32 v117, v117
	v_cvt_pk_bf16_f32 v122, v112, v113
	v_mad_i64_i32 v[112:113], s[0:1], v141, s2, v[136:137]
	v_add_f32_e32 v116, 1.0, v116
	v_add_f32_e32 v117, 1.0, v117
	v_rcp_f32_e32 v116, v116
	v_rcp_f32_e32 v117, v117
	s_nop 0
	v_pk_mul_f32 v[114:115], v[114:115], v[116:117]
	s_nop 0
	v_pk_mul_f32 v[114:115], v[118:119], v[114:115]
	s_nop 0
	v_cvt_pk_bf16_f32 v123, v114, v115
	global_store_dwordx4 v[112:113], v[120:123], off
	v_mul_f32_e32 v112, 0xbfb8aa3b, v104
	v_mul_f32_e32 v113, 0xbfb8aa3b, v105
	v_exp_f32_e32 v112, v112
	v_exp_f32_e32 v113, v113
	v_or_b32_e32 v114, 16, v141
	v_add_f32_e32 v112, 1.0, v112
	v_add_f32_e32 v113, 1.0, v113
	v_rcp_f32_e32 v112, v112
	v_rcp_f32_e32 v113, v113
	s_nop 0
	v_pk_mul_f32 v[104:105], v[104:105], v[112:113]
	s_nop 0
	v_pk_mul_f32 v[104:105], v[108:109], v[104:105]
	v_mul_f32_e32 v108, 0xbfb8aa3b, v106
	v_mul_f32_e32 v109, 0xbfb8aa3b, v107
	v_exp_f32_e32 v108, v108
	v_exp_f32_e32 v109, v109
	v_cvt_pk_bf16_f32 v104, v104, v105
	v_add_f32_e32 v108, 1.0, v108
	v_add_f32_e32 v109, 1.0, v109
	v_rcp_f32_e32 v108, v108
	v_rcp_f32_e32 v109, v109
	s_nop 0
	v_pk_mul_f32 v[106:107], v[106:107], v[108:109]
	s_nop 0
	v_pk_mul_f32 v[106:107], v[110:111], v[106:107]
	s_nop 0
	v_cvt_pk_bf16_f32 v105, v106, v107
; __device__ __forceinline__ u32x4 mk4(unsigned a, unsigned b, unsigned c, unsigned d) { return (u32x4){a, b, c, d}; }
; __device__ __forceinline__ float silu_f(float x) { return x * __builtin_amdgcn_rcpf(1.f + __expf(-x)); }
; __device__ __forceinline__ void gemm_phase(const Params& p, int l, const bf16_t* __restrict__ A, const bf16_t* __restrict__ Bt, int M, int N, int K,
;                            int epi, bf16_t* __restrict__ outp, char* smem, int wvi) {
;     ...
;     } else if (epi == EPI_SWIGLU) {
; #pragma unroll
;       for (int ai = 0; ai < 2; ++ai)
; #pragma unroll
;         for (int m = 0; m < 4; ++m) {
;           bf16_t* rp = outp + (size_t)(r0 + ai * GHALF + m * 16) * DFF + pn * 128 + wc * 32 + fq * 8;
;           unsigned pk[4];
; #pragma unroll
;           for (int bj = 0; bj < 2; ++bj) {
;             const f32x4 g = acc[ai][bj][m][0], u = acc[ai][bj][m][1];
;             const float o0 = silu_f(g[0]) * u[0], o1 = silu_f(g[1]) * u[1], o2 = silu_f(g[2]) * u[2], o3 = silu_f(g[3]) * u[3];
;             pk[2 * bj] = pk2(o0, o1); pk[2 * bj + 1] = pk2(o2, o3);
;           }
;           *reinterpret_cast<u32x4*>(rp) = mk4(pk[0], pk[1], pk[2], pk[3]);
;         }
	v_mul_f32_e32 v106, 0xbfb8aa3b, v96
	v_mul_f32_e32 v107, 0xbfb8aa3b, v97
	v_exp_f32_e32 v106, v106
	v_exp_f32_e32 v107, v107
	v_add_f32_e32 v106, 1.0, v106
	v_add_f32_e32 v107, 1.0, v107
	v_rcp_f32_e32 v106, v106
	v_rcp_f32_e32 v107, v107
	s_nop 0
	v_pk_mul_f32 v[96:97], v[96:97], v[106:107]
	s_nop 0
	v_pk_mul_f32 v[96:97], v[100:101], v[96:97]
	v_mul_f32_e32 v100, 0xbfb8aa3b, v98
	v_mul_f32_e32 v101, 0xbfb8aa3b, v99
	v_exp_f32_e32 v100, v100
	v_exp_f32_e32 v101, v101
	v_cvt_pk_bf16_f32 v106, v96, v97
	v_mad_i64_i32 v[96:97], s[0:1], v114, s2, v[136:137]
	v_add_f32_e32 v100, 1.0, v100
	v_add_f32_e32 v101, 1.0, v101
	v_rcp_f32_e32 v100, v100
	v_rcp_f32_e32 v101, v101
	s_nop 0
	v_pk_mul_f32 v[98:99], v[98:99], v[100:101]
	s_nop 0
	v_pk_mul_f32 v[98:99], v[102:103], v[98:99]
	s_nop 0
	v_cvt_pk_bf16_f32 v107, v98, v99
	global_store_dwordx4 v[96:97], v[104:107], off
	v_mul_f32_e32 v96, 0xbfb8aa3b, v88
	v_mul_f32_e32 v97, 0xbfb8aa3b, v89
	v_exp_f32_e32 v96, v96
	v_exp_f32_e32 v97, v97
	v_or_b32_e32 v98, 32, v141
	v_add_f32_e32 v96, 1.0, v96
	v_add_f32_e32 v97, 1.0, v97
	v_rcp_f32_e32 v96, v96
	v_rcp_f32_e32 v97, v97
	s_nop 0
	v_pk_mul_f32 v[88:89], v[88:89], v[96:97]
	s_nop 0
	v_pk_mul_f32 v[88:89], v[92:93], v[88:89]
	v_mul_f32_e32 v92, 0xbfb8aa3b, v90
	v_mul_f32_e32 v93, 0xbfb8aa3b, v91
	v_exp_f32_e32 v92, v92
	v_exp_f32_e32 v93, v93
	v_cvt_pk_bf16_f32 v88, v88, v89
	v_add_f32_e32 v92, 1.0, v92
	v_add_f32_e32 v93, 1.0, v93
	v_rcp_f32_e32 v92, v92
	v_rcp_f32_e32 v93, v93
	s_nop 0
	v_pk_mul_f32 v[90:91], v[90:91], v[92:93]
	s_nop 0
	v_pk_mul_f32 v[90:91], v[94:95], v[90:91]
	s_nop 0
	v_cvt_pk_bf16_f32 v89, v90, v91
	v_mul_f32_e32 v90, 0xbfb8aa3b, v80
	v_mul_f32_e32 v91, 0xbfb8aa3b, v81
	v_exp_f32_e32 v90, v90
	v_exp_f32_e32 v91, v91
	v_add_f32_e32 v90, 1.0, v90
	v_add_f32_e32 v91, 1.0, v91
	v_rcp_f32_e32 v90, v90
	v_rcp_f32_e32 v91, v91
	s_nop 0
	v_pk_mul_f32 v[80:81], v[80:81], v[90:91]
	s_nop 0
	v_pk_mul_f32 v[80:81], v[84:85], v[80:81]
	v_mul_f32_e32 v84, 0xbfb8aa3b, v82
	v_mul_f32_e32 v85, 0xbfb8aa3b, v83
	v_exp_f32_e32 v84, v84
	v_exp_f32_e32 v85, v85
	v_cvt_pk_bf16_f32 v90, v80, v81
	v_mad_i64_i32 v[80:81], s[0:1], v98, s2, v[136:137]
	v_add_f32_e32 v84, 1.0, v84
	v_add_f32_e32 v85, 1.0, v85
	v_rcp_f32_e32 v84, v84
	v_rcp_f32_e32 v85, v85
	s_nop 0
	v_pk_mul_f32 v[82:83], v[82:83], v[84:85]
	s_nop 0
	v_pk_mul_f32 v[82:83], v[86:87], v[82:83]
	s_nop 0
	v_cvt_pk_bf16_f32 v91, v82, v83
	global_store_dwordx4 v[80:81], v[88:91], off
	v_mul_f32_e32 v80, 0xbfb8aa3b, v72
	v_mul_f32_e32 v81, 0xbfb8aa3b, v73
	v_exp_f32_e32 v80, v80
	v_exp_f32_e32 v81, v81
	v_or_b32_e32 v82, 48, v141
	v_add_f32_e32 v80, 1.0, v80
	v_add_f32_e32 v81, 1.0, v81
	v_rcp_f32_e32 v80, v80
	v_rcp_f32_e32 v81, v81
	s_nop 0
	v_pk_mul_f32 v[72:73], v[72:73], v[80:81]
	s_nop 0
	v_pk_mul_f32 v[72:73], v[76:77], v[72:73]
	v_mul_f32_e32 v76, 0xbfb8aa3b, v74
	v_mul_f32_e32 v77, 0xbfb8aa3b, v75
	v_exp_f32_e32 v76, v76
	v_exp_f32_e32 v77, v77
	v_cvt_pk_bf16_f32 v72, v72, v73
	v_add_f32_e32 v76, 1.0, v76
	v_add_f32_e32 v77, 1.0, v77
	v_rcp_f32_e32 v76, v76
	v_rcp_f32_e32 v77, v77
	s_nop 0
	v_pk_mul_f32 v[74:75], v[74:75], v[76:77]
	s_nop 0
	v_pk_mul_f32 v[74:75], v[78:79], v[74:75]
	s_nop 0
	v_cvt_pk_bf16_f32 v73, v74, v75
	v_mul_f32_e32 v74, 0xbfb8aa3b, v64
	v_mul_f32_e32 v75, 0xbfb8aa3b, v65
	v_exp_f32_e32 v74, v74
	v_exp_f32_e32 v75, v75
	v_add_f32_e32 v74, 1.0, v74
	v_add_f32_e32 v75, 1.0, v75
	v_rcp_f32_e32 v74, v74
	v_rcp_f32_e32 v75, v75
	s_nop 0
	v_pk_mul_f32 v[64:65], v[64:65], v[74:75]
	s_nop 0
	v_pk_mul_f32 v[64:65], v[68:69], v[64:65]
	v_mul_f32_e32 v68, 0xbfb8aa3b, v66
	v_mul_f32_e32 v69, 0xbfb8aa3b, v67
	v_exp_f32_e32 v68, v68
	v_exp_f32_e32 v69, v69
	v_cvt_pk_bf16_f32 v74, v64, v65
	v_mad_i64_i32 v[64:65], s[0:1], v82, s2, v[136:137]
	v_add_f32_e32 v68, 1.0, v68
	v_add_f32_e32 v69, 1.0, v69
	v_rcp_f32_e32 v68, v68
	v_rcp_f32_e32 v69, v69
	s_nop 0
	v_pk_mul_f32 v[66:67], v[66:67], v[68:69]
	s_nop 0
	v_pk_mul_f32 v[66:67], v[70:71], v[66:67]
	s_nop 0
	v_cvt_pk_bf16_f32 v75, v66, v67
	global_store_dwordx4 v[64:65], v[72:75], off
	v_mul_f32_e32 v64, 0xbfb8aa3b, v56
	v_mul_f32_e32 v65, 0xbfb8aa3b, v57
	v_exp_f32_e32 v64, v64
	v_exp_f32_e32 v65, v65
	v_add_u32_e32 v66, 0x80, v141
	v_add_f32_e32 v64, 1.0, v64
	v_add_f32_e32 v65, 1.0, v65
	v_rcp_f32_e32 v64, v64
	v_rcp_f32_e32 v65, v65
	s_nop 0
	v_pk_mul_f32 v[56:57], v[56:57], v[64:65]
	s_nop 0
	v_pk_mul_f32 v[56:57], v[60:61], v[56:57]
	v_mul_f32_e32 v60, 0xbfb8aa3b, v58
	v_mul_f32_e32 v61, 0xbfb8aa3b, v59
	v_exp_f32_e32 v60, v60
	v_exp_f32_e32 v61, v61
	v_cvt_pk_bf16_f32 v56, v56, v57
	v_add_f32_e32 v60, 1.0, v60
	v_add_f32_e32 v61, 1.0, v61
	v_rcp_f32_e32 v60, v60
	v_rcp_f32_e32 v61, v61
	s_nop 0
	v_pk_mul_f32 v[58:59], v[58:59], v[60:61]
	s_nop 0
	v_pk_mul_f32 v[58:59], v[62:63], v[58:59]
	s_nop 0
	v_cvt_pk_bf16_f32 v57, v58, v59
	v_mul_f32_e32 v58, 0xbfb8aa3b, v48
	v_mul_f32_e32 v59, 0xbfb8aa3b, v49
	v_exp_f32_e32 v58, v58
	v_exp_f32_e32 v59, v59
	v_add_f32_e32 v58, 1.0, v58
	v_add_f32_e32 v59, 1.0, v59
	v_rcp_f32_e32 v58, v58
	v_rcp_f32_e32 v59, v59
	s_nop 0
	v_pk_mul_f32 v[48:49], v[48:49], v[58:59]
	s_nop 0
	v_pk_mul_f32 v[48:49], v[52:53], v[48:49]
	v_mul_f32_e32 v52, 0xbfb8aa3b, v50
	v_mul_f32_e32 v53, 0xbfb8aa3b, v51
	v_exp_f32_e32 v52, v52
	v_exp_f32_e32 v53, v53
	v_cvt_pk_bf16_f32 v58, v48, v49
	v_mad_i64_i32 v[48:49], s[0:1], v66, s2, v[136:137]
	v_add_f32_e32 v52, 1.0, v52
	v_add_f32_e32 v53, 1.0, v53
	v_rcp_f32_e32 v52, v52
	v_rcp_f32_e32 v53, v53
	s_nop 0
	v_pk_mul_f32 v[50:51], v[50:51], v[52:53]
	s_nop 0
	v_pk_mul_f32 v[50:51], v[54:55], v[50:51]
	s_nop 0
	v_cvt_pk_bf16_f32 v59, v50, v51
; __device__ __forceinline__ u32x4 mk4(unsigned a, unsigned b, unsigned c, unsigned d) { return (u32x4){a, b, c, d}; }
; __device__ __forceinline__ float silu_f(float x) { return x * __builtin_amdgcn_rcpf(1.f + __expf(-x)); }
; __device__ __forceinline__ void gemm_phase(const Params& p, int l, const bf16_t* __restrict__ A, const bf16_t* __restrict__ Bt, int M, int N, int K,
;                            int epi, bf16_t* __restrict__ outp, char* smem, int wvi) {
;     ...
;     } else if (epi == EPI_SWIGLU) {
; #pragma unroll
;       for (int ai = 0; ai < 2; ++ai)
; #pragma unroll
;         for (int m = 0; m < 4; ++m) {
;           bf16_t* rp = outp + (size_t)(r0 + ai * GHALF + m * 16) * DFF + pn * 128 + wc * 32 + fq * 8;
;           unsigned pk[4];
; #pragma unroll
;           for (int bj = 0; bj < 2; ++bj) {
;             const f32x4 g = acc[ai][bj][m][0], u = acc[ai][bj][m][1];
;             const float o0 = silu_f(g[0]) * u[0], o1 = silu_f(g[1]) * u[1], o2 = silu_f(g[2]) * u[2], o3 = silu_f(g[3]) * u[3];
;             pk[2 * bj] = pk2(o0, o1); pk[2 * bj + 1] = pk2(o2, o3);
;           }
;           *reinterpret_cast<u32x4*>(rp) = mk4(pk[0], pk[1], pk[2], pk[3]);
;         }
	global_store_dwordx4 v[48:49], v[56:59], off
	v_mul_f32_e32 v48, 0xbfb8aa3b, v40
	v_mul_f32_e32 v49, 0xbfb8aa3b, v41
	v_exp_f32_e32 v48, v48
	v_exp_f32_e32 v49, v49
	v_add_u32_e32 v50, 0x90, v141
	v_add_f32_e32 v48, 1.0, v48
	v_add_f32_e32 v49, 1.0, v49
	v_rcp_f32_e32 v48, v48
	v_rcp_f32_e32 v49, v49
	s_nop 0
	v_pk_mul_f32 v[40:41], v[40:41], v[48:49]
	s_nop 0
	v_pk_mul_f32 v[40:41], v[44:45], v[40:41]
	v_mul_f32_e32 v44, 0xbfb8aa3b, v42
	v_mul_f32_e32 v45, 0xbfb8aa3b, v43
	v_exp_f32_e32 v44, v44
	v_exp_f32_e32 v45, v45
	v_cvt_pk_bf16_f32 v40, v40, v41
	v_add_f32_e32 v44, 1.0, v44
	v_add_f32_e32 v45, 1.0, v45
	v_rcp_f32_e32 v44, v44
	v_rcp_f32_e32 v45, v45
	s_nop 0
	v_pk_mul_f32 v[42:43], v[42:43], v[44:45]
	s_nop 0
	v_pk_mul_f32 v[42:43], v[46:47], v[42:43]
	s_nop 0
	v_cvt_pk_bf16_f32 v41, v42, v43
	v_mul_f32_e32 v42, 0xbfb8aa3b, v32
	v_mul_f32_e32 v43, 0xbfb8aa3b, v33
	v_exp_f32_e32 v42, v42
	v_exp_f32_e32 v43, v43
	v_add_f32_e32 v42, 1.0, v42
	v_add_f32_e32 v43, 1.0, v43
	v_rcp_f32_e32 v42, v42
	v_rcp_f32_e32 v43, v43
	s_nop 0
	v_pk_mul_f32 v[32:33], v[32:33], v[42:43]
	s_nop 0
	v_pk_mul_f32 v[32:33], v[36:37], v[32:33]
	v_mul_f32_e32 v36, 0xbfb8aa3b, v34
	v_mul_f32_e32 v37, 0xbfb8aa3b, v35
	v_exp_f32_e32 v36, v36
	v_exp_f32_e32 v37, v37
	v_cvt_pk_bf16_f32 v42, v32, v33
	v_mad_i64_i32 v[32:33], s[0:1], v50, s2, v[136:137]
	v_add_f32_e32 v36, 1.0, v36
	v_add_f32_e32 v37, 1.0, v37
	v_rcp_f32_e32 v36, v36
	v_rcp_f32_e32 v37, v37
	s_nop 0
	v_pk_mul_f32 v[34:35], v[34:35], v[36:37]
	s_nop 0
	v_pk_mul_f32 v[34:35], v[38:39], v[34:35]
	s_nop 0
	v_cvt_pk_bf16_f32 v43, v34, v35
	global_store_dwordx4 v[32:33], v[40:43], off
	v_mul_f32_e32 v32, 0xbfb8aa3b, v24
	v_mul_f32_e32 v33, 0xbfb8aa3b, v25
	v_exp_f32_e32 v32, v32
	v_exp_f32_e32 v33, v33
	v_add_u32_e32 v34, 0xa0, v141
	v_add_f32_e32 v32, 1.0, v32
	v_add_f32_e32 v33, 1.0, v33
	v_rcp_f32_e32 v32, v32
	v_rcp_f32_e32 v33, v33
	s_nop 0
	v_pk_mul_f32 v[24:25], v[24:25], v[32:33]
	s_nop 0
	v_pk_mul_f32 v[24:25], v[28:29], v[24:25]
	v_mul_f32_e32 v28, 0xbfb8aa3b, v26
	v_mul_f32_e32 v29, 0xbfb8aa3b, v27
	v_exp_f32_e32 v28, v28
	v_exp_f32_e32 v29, v29
	v_cvt_pk_bf16_f32 v24, v24, v25
	v_add_f32_e32 v28, 1.0, v28
	v_add_f32_e32 v29, 1.0, v29
	v_rcp_f32_e32 v28, v28
	v_rcp_f32_e32 v29, v29
	s_nop 0
	v_pk_mul_f32 v[26:27], v[26:27], v[28:29]
	s_nop 0
	v_pk_mul_f32 v[26:27], v[30:31], v[26:27]
	s_nop 0
	v_cvt_pk_bf16_f32 v25, v26, v27
	v_mul_f32_e32 v26, 0xbfb8aa3b, v16
	v_mul_f32_e32 v27, 0xbfb8aa3b, v17
	v_exp_f32_e32 v26, v26
	v_exp_f32_e32 v27, v27
	v_add_f32_e32 v26, 1.0, v26
	v_add_f32_e32 v27, 1.0, v27
	v_rcp_f32_e32 v26, v26
	v_rcp_f32_e32 v27, v27
	s_nop 0
	v_pk_mul_f32 v[16:17], v[16:17], v[26:27]
	s_nop 0
	v_pk_mul_f32 v[16:17], v[20:21], v[16:17]
	v_mul_f32_e32 v20, 0xbfb8aa3b, v18
	v_mul_f32_e32 v21, 0xbfb8aa3b, v19
	v_exp_f32_e32 v20, v20
	v_exp_f32_e32 v21, v21
	v_cvt_pk_bf16_f32 v26, v16, v17
	v_mad_i64_i32 v[16:17], s[0:1], v34, s2, v[136:137]
	v_add_f32_e32 v20, 1.0, v20
	v_add_f32_e32 v21, 1.0, v21
	v_rcp_f32_e32 v20, v20
	v_rcp_f32_e32 v21, v21
	s_nop 0
	v_pk_mul_f32 v[18:19], v[18:19], v[20:21]
	s_nop 0
	v_pk_mul_f32 v[18:19], v[22:23], v[18:19]
	s_nop 0
	v_cvt_pk_bf16_f32 v27, v18, v19
	global_store_dwordx4 v[16:17], v[24:27], off
	v_mul_f32_e32 v16, 0xbfb8aa3b, v8
	v_mul_f32_e32 v17, 0xbfb8aa3b, v9
	v_exp_f32_e32 v16, v16
	v_exp_f32_e32 v17, v17
	v_add_u32_e32 v18, 0xb0, v141
	v_add_f32_e32 v16, 1.0, v16
	v_add_f32_e32 v17, 1.0, v17
	v_rcp_f32_e32 v16, v16
	v_rcp_f32_e32 v17, v17
	s_nop 0
	v_pk_mul_f32 v[8:9], v[8:9], v[16:17]
	s_nop 0
	v_pk_mul_f32 v[8:9], v[12:13], v[8:9]
	v_mul_f32_e32 v12, 0xbfb8aa3b, v10
	v_mul_f32_e32 v13, 0xbfb8aa3b, v11
	v_exp_f32_e32 v12, v12
	v_exp_f32_e32 v13, v13
	v_cvt_pk_bf16_f32 v8, v8, v9
	v_add_f32_e32 v12, 1.0, v12
	v_add_f32_e32 v13, 1.0, v13
	v_rcp_f32_e32 v12, v12
	v_rcp_f32_e32 v13, v13
	s_nop 0
	v_pk_mul_f32 v[10:11], v[10:11], v[12:13]
	s_nop 0
	v_pk_mul_f32 v[10:11], v[14:15], v[10:11]
	s_nop 0
	v_cvt_pk_bf16_f32 v9, v10, v11
	v_mul_f32_e32 v10, 0xbfb8aa3b, v0
	v_mul_f32_e32 v11, 0xbfb8aa3b, v1
	v_exp_f32_e32 v10, v10
	v_exp_f32_e32 v11, v11
	v_add_f32_e32 v10, 1.0, v10
	v_add_f32_e32 v11, 1.0, v11
	v_rcp_f32_e32 v10, v10
	v_rcp_f32_e32 v11, v11
	s_nop 0
	v_pk_mul_f32 v[0:1], v[0:1], v[10:11]
	s_nop 0
	v_pk_mul_f32 v[0:1], v[4:5], v[0:1]
	v_mul_f32_e32 v4, 0xbfb8aa3b, v2
	v_mul_f32_e32 v5, 0xbfb8aa3b, v3
	v_exp_f32_e32 v4, v4
	v_exp_f32_e32 v5, v5
	v_cvt_pk_bf16_f32 v10, v0, v1
	v_mad_i64_i32 v[0:1], s[0:1], v18, s2, v[136:137]
	v_add_f32_e32 v4, 1.0, v4
	v_add_f32_e32 v5, 1.0, v5
	v_rcp_f32_e32 v4, v4
	v_rcp_f32_e32 v5, v5
	s_mov_b64 s[2:3], -1
	v_pk_mul_f32 v[2:3], v[2:3], v[4:5]
	s_nop 0
	v_pk_mul_f32 v[2:3], v[6:7], v[2:3]
	s_nop 0
	v_cvt_pk_bf16_f32 v11, v2, v3
	global_store_dwordx4 v[0:1], v[8:11], off
	s_cbranch_vccz .LBB0_1195
; __device__ __forceinline__ f32x4 zero4() { float z = 0.f; asm volatile("" : "+v"(z)); return (f32x4){z, z, z, z}; }
; __device__ __forceinline__ void gemm_phase(const Params& p, int l, const bf16_t* __restrict__ A, const bf16_t* __restrict__ Bt, int M, int N, int K,
;                            int epi, bf16_t* __restrict__ outp, char* smem, int wvi) {
;     ...
;       if (!has_next) break;
; #pragma unroll
;       for (int a = 0; a < 2; ++a)
; #pragma unroll
;         for (int b = 0; b < 2; ++b)
; #pragma unroll
;           for (int m = 0; m < 4; ++m)
; #pragma unroll
;             for (int n = 0; n < 2; ++n) acc[a][b][m][n] = zero4();
;       Lw = Ln; pm = npm; pn = npn; cA = nA; cB = nB;
	v_mov_b32_e32 v120, v177
	v_mov_b32_e32 v124, v177
	v_mov_b32_e32 v104, v177
	v_mov_b32_e32 v108, v177
	v_mov_b32_e32 v88, v177
	v_mov_b32_e32 v92, v177
	v_mov_b32_e32 v72, v177
	v_mov_b32_e32 v76, v177
	v_mov_b32_e32 v112, v177
	v_mov_b32_e32 v116, v177
	v_mov_b32_e32 v96, v177
	v_mov_b32_e32 v100, v177
	v_mov_b32_e32 v80, v177
	v_mov_b32_e32 v84, v177
	v_mov_b32_e32 v64, v177
	v_mov_b32_e32 v68, v177
	v_mov_b32_e32 v56, v177
	v_mov_b32_e32 v60, v177
	v_mov_b32_e32 v40, v177
	v_mov_b32_e32 v44, v177
	v_mov_b32_e32 v24, v177
	v_mov_b32_e32 v28, v177
	v_mov_b32_e32 v8, v177
	v_mov_b32_e32 v12, v177
	v_mov_b32_e32 v48, v177
	v_mov_b32_e32 v52, v177
	v_mov_b32_e32 v32, v177
	v_mov_b32_e32 v36, v177
	v_mov_b32_e32 v16, v177
	v_mov_b32_e32 v20, v177
	v_mov_b32_e32 v0, v177
	v_mov_b32_e32 v4, v177
	s_nop 0
	v_mov_b32_e32 v121, v120
	v_mov_b32_e32 v122, v120
	v_mov_b32_e32 v123, v120
	v_mov_b32_e32 v125, v124
	v_mov_b32_e32 v126, v124
	v_mov_b32_e32 v127, v124
	v_mov_b32_e32 v105, v104
	v_mov_b32_e32 v106, v104
	v_mov_b32_e32 v107, v104
	v_mov_b32_e32 v109, v108
	v_mov_b32_e32 v110, v108
	v_mov_b32_e32 v111, v108
	v_mov_b32_e32 v89, v88
	v_mov_b32_e32 v90, v88
	v_mov_b32_e32 v91, v88
	v_mov_b32_e32 v93, v92
	v_mov_b32_e32 v94, v92
	v_mov_b32_e32 v95, v92
	s_nop 0
	v_mov_b32_e32 v73, v72
	v_mov_b32_e32 v74, v72
	v_mov_b32_e32 v75, v72
	v_mov_b32_e32 v77, v76
	v_mov_b32_e32 v78, v76
	v_mov_b32_e32 v79, v76
	v_mov_b32_e32 v113, v112
	v_mov_b32_e32 v114, v112
	v_mov_b32_e32 v115, v112
	v_mov_b32_e32 v117, v116
	v_mov_b32_e32 v118, v116
	v_mov_b32_e32 v119, v116
	v_mov_b32_e32 v97, v96
	v_mov_b32_e32 v98, v96
	v_mov_b32_e32 v99, v96
	v_mov_b32_e32 v101, v100
	v_mov_b32_e32 v102, v100
	v_mov_b32_e32 v103, v100
	s_nop 0
	v_mov_b32_e32 v81, v80
	v_mov_b32_e32 v82, v80
	v_mov_b32_e32 v83, v80
	v_mov_b32_e32 v85, v84
	v_mov_b32_e32 v86, v84
	v_mov_b32_e32 v87, v84
	v_mov_b32_e32 v65, v64
	v_mov_b32_e32 v66, v64
	v_mov_b32_e32 v67, v64
	v_mov_b32_e32 v69, v68
	v_mov_b32_e32 v70, v68
	v_mov_b32_e32 v71, v68
	v_mov_b32_e32 v57, v56
	v_mov_b32_e32 v58, v56
	v_mov_b32_e32 v59, v56
	v_mov_b32_e32 v61, v60
	v_mov_b32_e32 v62, v60
	v_mov_b32_e32 v63, v60
	s_nop 0
	v_mov_b32_e32 v41, v40
	v_mov_b32_e32 v42, v40
	v_mov_b32_e32 v43, v40
	v_mov_b32_e32 v45, v44
	v_mov_b32_e32 v46, v44
	v_mov_b32_e32 v47, v44
	v_mov_b32_e32 v25, v24
	v_mov_b32_e32 v26, v24
	v_mov_b32_e32 v27, v24
	v_mov_b32_e32 v29, v28
	v_mov_b32_e32 v30, v28
	v_mov_b32_e32 v31, v28
	v_mov_b32_e32 v9, v8
	v_mov_b32_e32 v10, v8
	v_mov_b32_e32 v11, v8
	v_mov_b32_e32 v13, v12
	v_mov_b32_e32 v14, v12
	v_mov_b32_e32 v15, v12
	s_nop 0
	v_mov_b32_e32 v49, v48
	v_mov_b32_e32 v50, v48
	v_mov_b32_e32 v51, v48
	v_mov_b32_e32 v53, v52
	v_mov_b32_e32 v54, v52
	v_mov_b32_e32 v55, v52
	v_mov_b32_e32 v33, v32
	v_mov_b32_e32 v34, v32
	v_mov_b32_e32 v35, v32
	v_mov_b32_e32 v37, v36
	v_mov_b32_e32 v38, v36
	v_mov_b32_e32 v39, v36
	v_mov_b32_e32 v17, v16
	v_mov_b32_e32 v18, v16
	v_mov_b32_e32 v19, v16
	v_mov_b32_e32 v21, v20
	v_mov_b32_e32 v22, v20
	v_mov_b32_e32 v23, v20
	s_mov_b64 s[2:3], 0
	v_mov_b32_e32 v1, v0
	v_mov_b32_e32 v2, v0
	v_mov_b32_e32 v3, v0
	v_mov_b32_e32 v5, v4
	v_mov_b32_e32 v6, v4
	v_mov_b32_e32 v7, v4
	s_branch .LBB0_1195
